# K loop without s_setprio toggles, residual GEMM register epilogue (cvt_pk, permlane swap, prefetched residual)
# baseline (speedup 1.0000x reference)
; #define STAGE_B(P, br, kt) do { const char* _gb = (const char*)(Bt + ((long)(br) * K + (long)(kt) * BK)); \
;     __builtin_amdgcn_global_load_lds((const unsigned*)(_gb + bofl0), (unsigned*)((char*)(P) + gtid_ * 16), 16, 0, 0); \
;     __builtin_amdgcn_global_load_lds((const unsigned*)(_gb + (long)K * 128 + bofl0), (unsigned*)((char*)(P) + gtid_ * 16 + 8192), 16, 0, 0); } while (0)
; #define LDA(dst, b, h) for (int m = 0; m < 4; ++m) for (int k = 0; k < 2; ++k) \
;     dst[m][k] = *reinterpret_cast<const bf16x8*>((char*)SA(b, h) + lds_byte(wr * 64 + m * 16 + fr, k * 32 + fq * 8))
; #define LDB(dst, b, h) for (int n = 0; n < 2; ++n) for (int k = 0; k < 2; ++k) \
;     dst[n][k] = *reinterpret_cast<const bf16x8*>((char*)SB(b, h) + lds_byte(wc * 32 + n * 16 + fr, k * 32 + fq * 8))
; #define MMA(ai, bj, At_, Bt_) do { __builtin_amdgcn_s_setprio(1); \
;     for (int m = 0; m < 4; ++m) for (int n = 0; n < 2; ++n) for (int k = 0; k < 2; ++k) \
;       acc[ai][bj][m][n] = __builtin_amdgcn_mfma_f32_16x16x32_bf16(At_[m][k], Bt_[n][k], acc[ai][bj][m][n], 0, 0, 0); \
;     __builtin_amdgcn_s_setprio(0); } while (0)
; #define WAIT_V(n) asm volatile("s_waitcnt vmcnt(" #n ")" ::: "memory")
; #define WAIT_L(n) asm volatile("s_waitcnt lgkmcnt(" #n ")" ::: "memory")
; #define BAR __builtin_amdgcn_s_barrier()
; #define SCHED __builtin_amdgcn_sched_barrier(0)
; template <int EPI>
; __device__ __forceinline__ void gemm_tile(const GemmArgs& g, int brow, int bcol, int parity, bool first, bool nvalid, int nbrow, int nbcol) {
;     ...
;   for (int t = 0; t < nt - 2; t += 2) {
;     LDB(B0, 0, 0); SCHED; LDA(At, 0, 0); STAGE_A(SA(1, 1), brow + HALF, t + 1);
;     WAIT_L(8); BAR; WAIT_L(0); MMA(0, 0, At, B0); BAR; SCHED;
;     LDB(B1, 0, 1); STAGE_B(SB(0, 0), bcol, t + 2);
;     BAR; WAIT_L(0); MMA(0, 1, At, B1); BAR; SCHED;
;     LDA(At, 0, 1); STAGE_A(SA(0, 0), brow, t + 2);
;     BAR; WAIT_L(0); MMA(1, 0, At, B0); BAR; SCHED;
;     STAGE_B(SB(0, 1), bcol + HALF, t + 2);
;     WAIT_V(6); BAR; MMA(1, 1, At, B1); BAR; SCHED;
.LBB0_90:
	ds_read_b128 v[164:167], v157
	ds_read_b128 v[168:171], v157 offset:1024
	ds_read_b128 v[172:175], v157 offset:2048
	ds_read_b128 v[176:179], v157 offset:3072
	ds_read_b128 v[180:183], v147
	ds_read_b128 v[184:187], v147 offset:1024
	ds_read_b128 v[188:191], v146
	ds_read_b128 v[192:195], v146 offset:1024
	ds_read_b128 v[196:199], v145
	ds_read_b128 v[202:205], v145 offset:1024
	ds_read_b128 v[206:209], v144
	ds_read_b128 v[216:219], v144 offset:1024
	s_waitcnt lgkmcnt(6)
	ds_read_b128 v[228:231], v154
	ds_read_b128 v[232:235], v154 offset:1024
	ds_read_b128 v[236:239], v154 offset:2048
	ds_read_b128 v[240:243], v154 offset:3072
	v_add_u32_e32 v161, 0xc000, v137
	v_lshl_add_u64 v[210:211], s[0:1], 0, v[130:131]
	v_readfirstlane_b32 s2, v161
	v_add_u32_e32 v162, 0xe000, v137
	v_lshl_add_u64 v[158:159], v[210:211], 0, s[26:27]
	s_mov_b32 m0, s2
	v_readfirstlane_b32 s2, v162
	global_load_lds_dwordx4 v[158:159], off
	v_lshl_add_u64 v[158:159], v[210:211], 0, s[36:37]
	s_mov_b32 m0, s2
	s_nop 0
	global_load_lds_dwordx4 v[158:159], off
	s_waitcnt vmcnt(8)
	s_barrier
	s_waitcnt lgkmcnt(0)
	v_mfma_f32_16x16x32_bf16 v[126:129], v[164:167], v[180:183], v[126:129]
	v_mfma_f32_16x16x32_bf16 v[122:125], v[172:175], v[180:183], v[122:125]
	v_mfma_f32_16x16x32_bf16 v[118:121], v[164:167], v[188:191], v[118:121]
	v_mfma_f32_16x16x32_bf16 v[114:117], v[172:175], v[188:191], v[114:117]
	v_mfma_f32_16x16x32_bf16 v[110:113], v[164:167], v[196:199], v[110:113]
	v_mfma_f32_16x16x32_bf16 v[106:109], v[172:175], v[196:199], v[106:109]
	v_mfma_f32_16x16x32_bf16 v[102:105], v[164:167], v[206:209], v[102:105]
	v_mfma_f32_16x16x32_bf16 v[98:101], v[172:175], v[206:209], v[98:101]
	v_mfma_f32_16x16x32_bf16 v[126:129], v[168:171], v[184:187], v[126:129]
	v_mfma_f32_16x16x32_bf16 v[122:125], v[176:179], v[184:187], v[122:125]
	v_mfma_f32_16x16x32_bf16 v[118:121], v[168:171], v[192:195], v[118:121]
	v_mfma_f32_16x16x32_bf16 v[114:117], v[176:179], v[192:195], v[114:117]
	v_mfma_f32_16x16x32_bf16 v[110:113], v[168:171], v[202:205], v[110:113]
	v_mfma_f32_16x16x32_bf16 v[106:109], v[176:179], v[202:205], v[106:109]
	v_mfma_f32_16x16x32_bf16 v[102:105], v[168:171], v[216:219], v[102:105]
	v_mfma_f32_16x16x32_bf16 v[98:101], v[176:179], v[216:219], v[98:101]
	v_mfma_f32_16x16x32_bf16 v[94:97], v[228:231], v[180:183], v[94:97]
	v_mfma_f32_16x16x32_bf16 v[90:93], v[236:239], v[180:183], v[90:93]
	v_mfma_f32_16x16x32_bf16 v[86:89], v[228:231], v[188:191], v[86:89]
	v_mfma_f32_16x16x32_bf16 v[82:85], v[236:239], v[188:191], v[82:85]
	v_mfma_f32_16x16x32_bf16 v[78:81], v[228:231], v[196:199], v[78:81]
	v_mfma_f32_16x16x32_bf16 v[74:77], v[236:239], v[196:199], v[74:77]
	v_mfma_f32_16x16x32_bf16 v[70:73], v[228:231], v[206:209], v[70:73]
	v_mfma_f32_16x16x32_bf16 v[66:69], v[236:239], v[206:209], v[66:69]
	v_mfma_f32_16x16x32_bf16 v[94:97], v[232:235], v[184:187], v[94:97]
	v_mfma_f32_16x16x32_bf16 v[90:93], v[240:243], v[184:187], v[90:93]
	v_mfma_f32_16x16x32_bf16 v[86:89], v[232:235], v[192:195], v[86:89]
	v_mfma_f32_16x16x32_bf16 v[82:85], v[240:243], v[192:195], v[82:85]
	v_mfma_f32_16x16x32_bf16 v[78:81], v[232:235], v[202:205], v[78:81]
	v_mfma_f32_16x16x32_bf16 v[74:77], v[240:243], v[202:205], v[74:77]
	v_mfma_f32_16x16x32_bf16 v[70:73], v[232:235], v[216:219], v[70:73]
	v_mfma_f32_16x16x32_bf16 v[66:69], v[240:243], v[216:219], v[66:69]
	s_barrier
	ds_read_b128 v[180:183], v147 offset:16384
	ds_read_b128 v[184:187], v147 offset:17408
	ds_read_b128 v[188:191], v146 offset:16384
	ds_read_b128 v[192:195], v146 offset:17408
	ds_read_b128 v[196:199], v145 offset:16384
	ds_read_b128 v[202:205], v145 offset:17408
	ds_read_b128 v[206:209], v144 offset:16384
	ds_read_b128 v[216:219], v144 offset:17408
	v_lshl_add_u64 v[212:213], s[12:13], 0, v[130:131]
	s_mov_b64 s[2:3], 0x900100
	v_add_u32_e32 v158, s14, v142
	v_lshl_add_u64 v[222:223], v[212:213], 0, s[2:3]
	v_readfirstlane_b32 s2, v158
	s_mov_b32 m0, s2
	s_mov_b64 s[2:3], 0x920100
	v_add_u32_e32 v159, 0x2000, v158
	global_load_lds_dwordx4 v[222:223], off
	v_lshl_add_u64 v[222:223], v[212:213], 0, s[2:3]
	v_readfirstlane_b32 s2, v159
	s_mov_b32 m0, s2
	s_nop 0
	global_load_lds_dwordx4 v[222:223], off
	v_readfirstlane_b32 s2, v137
	v_lshl_add_u64 v[222:223], v[210:211], 0, s[40:41]
	s_mov_b32 m0, s2
	v_readfirstlane_b32 s2, v136
	global_load_lds_dwordx4 v[222:223], off
	v_lshl_add_u64 v[222:223], v[210:211], 0, s[44:45]
	s_mov_b32 m0, s2
	s_nop 0
	global_load_lds_dwordx4 v[222:223], off
	s_mov_b64 s[2:3], 0x940100
	v_lshl_add_u64 v[244:245], v[212:213], 0, s[2:3]
	v_readfirstlane_b32 s2, v135
	s_mov_b32 m0, s2
	s_mov_b64 s[2:3], 0x960100
	v_add_u32_e32 v160, 0x2000, v135
	global_load_lds_dwordx4 v[244:245], off
	v_lshl_add_u64 v[244:245], v[212:213], 0, s[2:3]
	v_readfirstlane_b32 s2, v160
	s_mov_b32 m0, s2
	s_nop 0
	global_load_lds_dwordx4 v[244:245], off
	s_waitcnt vmcnt(8)
	s_barrier
; #define STAGE_B(P, br, kt) do { const char* _gb = (const char*)(Bt + ((long)(br) * K + (long)(kt) * BK)); \
;     __builtin_amdgcn_global_load_lds((const unsigned*)(_gb + bofl0), (unsigned*)((char*)(P) + gtid_ * 16), 16, 0, 0); \
;     __builtin_amdgcn_global_load_lds((const unsigned*)(_gb + (long)K * 128 + bofl0), (unsigned*)((char*)(P) + gtid_ * 16 + 8192), 16, 0, 0); } while (0)
; #define LDA(dst, b, h) for (int m = 0; m < 4; ++m) for (int k = 0; k < 2; ++k) \
;     dst[m][k] = *reinterpret_cast<const bf16x8*>((char*)SA(b, h) + lds_byte(wr * 64 + m * 16 + fr, k * 32 + fq * 8))
; #define LDB(dst, b, h) for (int n = 0; n < 2; ++n) for (int k = 0; k < 2; ++k) \
;     dst[n][k] = *reinterpret_cast<const bf16x8*>((char*)SB(b, h) + lds_byte(wc * 32 + n * 16 + fr, k * 32 + fq * 8))
; #define MMA(ai, bj, At_, Bt_) do { __builtin_amdgcn_s_setprio(1); \
;     for (int m = 0; m < 4; ++m) for (int n = 0; n < 2; ++n) for (int k = 0; k < 2; ++k) \
;       acc[ai][bj][m][n] = __builtin_amdgcn_mfma_f32_16x16x32_bf16(At_[m][k], Bt_[n][k], acc[ai][bj][m][n], 0, 0, 0); \
;     __builtin_amdgcn_s_setprio(0); } while (0)
; #define WAIT_V(n) asm volatile("s_waitcnt vmcnt(" #n ")" ::: "memory")
; #define WAIT_L(n) asm volatile("s_waitcnt lgkmcnt(" #n ")" ::: "memory")
; #define BAR __builtin_amdgcn_s_barrier()
; #define SCHED __builtin_amdgcn_sched_barrier(0)
; template <int EPI>
; __device__ __forceinline__ void gemm_tile(const GemmArgs& g, int brow, int bcol, int parity, bool first, bool nvalid, int nbrow, int nbcol) {
;     ...
;   for (int t = 0; t < nt - 2; t += 2) {
;     LDB(B0, 0, 0); SCHED; LDA(At, 0, 0); STAGE_A(SA(1, 1), brow + HALF, t + 1);
;     WAIT_L(8); BAR; WAIT_L(0); MMA(0, 0, At, B0); BAR; SCHED;
;     LDB(B1, 0, 1); STAGE_B(SB(0, 0), bcol, t + 2);
;     BAR; WAIT_L(0); MMA(0, 1, At, B1); BAR; SCHED;
;     LDA(At, 0, 1); STAGE_A(SA(0, 0), brow, t + 2);
;     BAR; WAIT_L(0); MMA(1, 0, At, B0); BAR; SCHED;
;     STAGE_B(SB(0, 1), bcol + HALF, t + 2);
;     WAIT_V(6); BAR; MMA(1, 1, At, B1); BAR; SCHED;
;     LDB(B0, 1, 0); SCHED; LDA(At, 1, 0); STAGE_A(SA(0, 1), brow + HALF, t + 2);
;     WAIT_L(8); BAR; WAIT_L(0); MMA(0, 0, At, B0); BAR; SCHED;
;     LDB(B1, 1, 1); STAGE_B(SB(1, 0), bcol, t + 3);
;     BAR; WAIT_L(0); MMA(0, 1, At, B1); BAR; SCHED;
;     LDA(At, 1, 1); STAGE_A(SA(1, 0), brow, t + 3);
;     BAR; WAIT_L(0); MMA(1, 0, At, B0); BAR; SCHED;
	s_waitcnt lgkmcnt(0)
	v_mfma_f32_16x16x32_bf16 v[62:65], v[164:167], v[180:183], v[62:65]
	v_mfma_f32_16x16x32_bf16 v[58:61], v[172:175], v[180:183], v[58:61]
	v_mfma_f32_16x16x32_bf16 v[54:57], v[164:167], v[188:191], v[54:57]
	v_mfma_f32_16x16x32_bf16 v[50:53], v[172:175], v[188:191], v[50:53]
	v_mfma_f32_16x16x32_bf16 v[46:49], v[164:167], v[196:199], v[46:49]
	v_mfma_f32_16x16x32_bf16 v[42:45], v[172:175], v[196:199], v[42:45]
	v_mfma_f32_16x16x32_bf16 v[38:41], v[164:167], v[206:209], v[38:41]
	v_mfma_f32_16x16x32_bf16 v[34:37], v[172:175], v[206:209], v[34:37]
	v_mfma_f32_16x16x32_bf16 v[62:65], v[168:171], v[184:187], v[62:65]
	v_mfma_f32_16x16x32_bf16 v[58:61], v[176:179], v[184:187], v[58:61]
	v_mfma_f32_16x16x32_bf16 v[54:57], v[168:171], v[192:195], v[54:57]
	v_mfma_f32_16x16x32_bf16 v[50:53], v[176:179], v[192:195], v[50:53]
	v_mfma_f32_16x16x32_bf16 v[46:49], v[168:171], v[202:205], v[46:49]
	v_mfma_f32_16x16x32_bf16 v[42:45], v[176:179], v[202:205], v[42:45]
	v_mfma_f32_16x16x32_bf16 v[38:41], v[168:171], v[216:219], v[38:41]
	v_mfma_f32_16x16x32_bf16 v[34:37], v[176:179], v[216:219], v[34:37]
	v_mfma_f32_16x16x32_bf16 v[30:33], v[228:231], v[180:183], v[30:33]
	v_mfma_f32_16x16x32_bf16 v[26:29], v[236:239], v[180:183], v[26:29]
	v_mfma_f32_16x16x32_bf16 v[22:25], v[228:231], v[188:191], v[22:25]
	v_mfma_f32_16x16x32_bf16 v[18:21], v[236:239], v[188:191], v[18:21]
	v_mfma_f32_16x16x32_bf16 v[14:17], v[228:231], v[196:199], v[14:17]
	v_mfma_f32_16x16x32_bf16 v[10:13], v[236:239], v[196:199], v[10:13]
	v_mfma_f32_16x16x32_bf16 v[6:9], v[228:231], v[206:209], v[6:9]
	v_mfma_f32_16x16x32_bf16 v[2:5], v[236:239], v[206:209], v[2:5]
	v_mfma_f32_16x16x32_bf16 v[30:33], v[232:235], v[184:187], v[30:33]
	v_mfma_f32_16x16x32_bf16 v[26:29], v[240:243], v[184:187], v[26:29]
	v_mfma_f32_16x16x32_bf16 v[22:25], v[232:235], v[192:195], v[22:25]
	v_mfma_f32_16x16x32_bf16 v[18:21], v[240:243], v[192:195], v[18:21]
	v_mfma_f32_16x16x32_bf16 v[14:17], v[232:235], v[202:205], v[14:17]
	v_mfma_f32_16x16x32_bf16 v[10:13], v[240:243], v[202:205], v[10:13]
	v_mfma_f32_16x16x32_bf16 v[6:9], v[232:235], v[216:219], v[6:9]
	v_mfma_f32_16x16x32_bf16 v[2:5], v[240:243], v[216:219], v[2:5]
	s_barrier
	ds_read_b128 v[164:167], v149
	ds_read_b128 v[168:171], v149 offset:1024
	ds_read_b128 v[172:175], v149 offset:2048
	ds_read_b128 v[176:179], v149 offset:3072
	ds_read_b128 v[180:183], v147 offset:32768
	ds_read_b128 v[184:187], v147 offset:33792
	ds_read_b128 v[188:191], v146 offset:32768
	ds_read_b128 v[192:195], v146 offset:33792
	ds_read_b128 v[196:199], v145 offset:32768
	ds_read_b128 v[202:205], v145 offset:33792
	ds_read_b128 v[206:209], v144 offset:32768
	ds_read_b128 v[216:219], v144 offset:33792
	s_waitcnt lgkmcnt(6)
	ds_read_b128 v[228:231], v148
	ds_read_b128 v[232:235], v148 offset:1024
	ds_read_b128 v[236:239], v148 offset:2048
	ds_read_b128 v[240:243], v148 offset:3072
	v_readfirstlane_b32 s2, v134
	v_lshl_add_u64 v[222:223], v[210:211], 0, s[46:47]
	s_mov_b32 m0, s2
	v_readfirstlane_b32 s2, v133
	global_load_lds_dwordx4 v[222:223], off
	v_lshl_add_u64 v[222:223], v[210:211], 0, s[48:49]
	s_mov_b32 m0, s2
	s_nop 0
	global_load_lds_dwordx4 v[222:223], off
	s_waitcnt vmcnt(8)
	s_barrier
	s_waitcnt lgkmcnt(0)
	v_mfma_f32_16x16x32_bf16 v[126:129], v[164:167], v[180:183], v[126:129]
	v_mfma_f32_16x16x32_bf16 v[122:125], v[172:175], v[180:183], v[122:125]
	v_mfma_f32_16x16x32_bf16 v[118:121], v[164:167], v[188:191], v[118:121]
	v_mfma_f32_16x16x32_bf16 v[114:117], v[172:175], v[188:191], v[114:117]
	v_mfma_f32_16x16x32_bf16 v[110:113], v[164:167], v[196:199], v[110:113]
	v_mfma_f32_16x16x32_bf16 v[106:109], v[172:175], v[196:199], v[106:109]
	v_mfma_f32_16x16x32_bf16 v[102:105], v[164:167], v[206:209], v[102:105]
	v_mfma_f32_16x16x32_bf16 v[98:101], v[172:175], v[206:209], v[98:101]
	v_mfma_f32_16x16x32_bf16 v[126:129], v[168:171], v[184:187], v[126:129]
	v_mfma_f32_16x16x32_bf16 v[122:125], v[176:179], v[184:187], v[122:125]
	v_mfma_f32_16x16x32_bf16 v[118:121], v[168:171], v[192:195], v[118:121]
	v_mfma_f32_16x16x32_bf16 v[114:117], v[176:179], v[192:195], v[114:117]
	v_mfma_f32_16x16x32_bf16 v[110:113], v[168:171], v[202:205], v[110:113]
	v_mfma_f32_16x16x32_bf16 v[106:109], v[176:179], v[202:205], v[106:109]
	v_mfma_f32_16x16x32_bf16 v[102:105], v[168:171], v[216:219], v[102:105]
	v_mfma_f32_16x16x32_bf16 v[98:101], v[176:179], v[216:219], v[98:101]
	v_mfma_f32_16x16x32_bf16 v[94:97], v[228:231], v[180:183], v[94:97]
	v_mfma_f32_16x16x32_bf16 v[90:93], v[236:239], v[180:183], v[90:93]
	v_mfma_f32_16x16x32_bf16 v[86:89], v[228:231], v[188:191], v[86:89]
	v_mfma_f32_16x16x32_bf16 v[82:85], v[236:239], v[188:191], v[82:85]
	v_mfma_f32_16x16x32_bf16 v[78:81], v[228:231], v[196:199], v[78:81]
	v_mfma_f32_16x16x32_bf16 v[74:77], v[236:239], v[196:199], v[74:77]
	v_mfma_f32_16x16x32_bf16 v[70:73], v[228:231], v[206:209], v[70:73]
	v_mfma_f32_16x16x32_bf16 v[66:69], v[236:239], v[206:209], v[66:69]
	v_mfma_f32_16x16x32_bf16 v[94:97], v[232:235], v[184:187], v[94:97]
	v_mfma_f32_16x16x32_bf16 v[90:93], v[240:243], v[184:187], v[90:93]
	v_mfma_f32_16x16x32_bf16 v[86:89], v[232:235], v[192:195], v[86:89]
	v_mfma_f32_16x16x32_bf16 v[82:85], v[240:243], v[192:195], v[82:85]
	v_mfma_f32_16x16x32_bf16 v[78:81], v[232:235], v[202:205], v[78:81]
	v_mfma_f32_16x16x32_bf16 v[74:77], v[240:243], v[202:205], v[74:77]
	v_mfma_f32_16x16x32_bf16 v[70:73], v[232:235], v[216:219], v[70:73]
	v_mfma_f32_16x16x32_bf16 v[66:69], v[240:243], v[216:219], v[66:69]
	s_barrier
; #define STAGE_B(P, br, kt) do { const char* _gb = (const char*)(Bt + ((long)(br) * K + (long)(kt) * BK)); \
;     __builtin_amdgcn_global_load_lds((const unsigned*)(_gb + bofl0), (unsigned*)((char*)(P) + gtid_ * 16), 16, 0, 0); \
;     __builtin_amdgcn_global_load_lds((const unsigned*)(_gb + (long)K * 128 + bofl0), (unsigned*)((char*)(P) + gtid_ * 16 + 8192), 16, 0, 0); } while (0)
; #define LDA(dst, b, h) for (int m = 0; m < 4; ++m) for (int k = 0; k < 2; ++k) \
;     dst[m][k] = *reinterpret_cast<const bf16x8*>((char*)SA(b, h) + lds_byte(wr * 64 + m * 16 + fr, k * 32 + fq * 8))
; #define LDB(dst, b, h) for (int n = 0; n < 2; ++n) for (int k = 0; k < 2; ++k) \
;     dst[n][k] = *reinterpret_cast<const bf16x8*>((char*)SB(b, h) + lds_byte(wc * 32 + n * 16 + fr, k * 32 + fq * 8))
; #define MMA(ai, bj, At_, Bt_) do { __builtin_amdgcn_s_setprio(1); \
;     for (int m = 0; m < 4; ++m) for (int n = 0; n < 2; ++n) for (int k = 0; k < 2; ++k) \
;       acc[ai][bj][m][n] = __builtin_amdgcn_mfma_f32_16x16x32_bf16(At_[m][k], Bt_[n][k], acc[ai][bj][m][n], 0, 0, 0); \
;     __builtin_amdgcn_s_setprio(0); } while (0)
; #define WAIT_V(n) asm volatile("s_waitcnt vmcnt(" #n ")" ::: "memory")
; #define WAIT_L(n) asm volatile("s_waitcnt lgkmcnt(" #n ")" ::: "memory")
; #define BAR __builtin_amdgcn_s_barrier()
; #define SCHED __builtin_amdgcn_sched_barrier(0)
; template <int EPI>
; __device__ __forceinline__ void gemm_tile(const GemmArgs& g, int brow, int bcol, int parity, bool first, bool nvalid, int nbrow, int nbcol) {
;     ...
;     WAIT_V(6); BAR; MMA(1, 1, At, B1); BAR; SCHED;
;     LDB(B0, 1, 0); SCHED; LDA(At, 1, 0); STAGE_A(SA(0, 1), brow + HALF, t + 2);
;     WAIT_L(8); BAR; WAIT_L(0); MMA(0, 0, At, B0); BAR; SCHED;
;     LDB(B1, 1, 1); STAGE_B(SB(1, 0), bcol, t + 3);
;     BAR; WAIT_L(0); MMA(0, 1, At, B1); BAR; SCHED;
;     LDA(At, 1, 1); STAGE_A(SA(1, 0), brow, t + 3);
;     BAR; WAIT_L(0); MMA(1, 0, At, B0); BAR; SCHED;
;     STAGE_B(SB(1, 1), bcol + HALF, t + 3);
;     WAIT_V(6); BAR; MMA(1, 1, At, B1); BAR; SCHED;
;   }
;   { LDB(B0, 0, 0); LDA(At, 0, 0); STAGE_A(SA(1, 1), brow + HALF, nt - 1);
;     BAR; WAIT_L(0); MMA(0, 0, At, B0); BAR;
	ds_read_b128 v[180:183], v147 offset:49152
	ds_read_b128 v[184:187], v147 offset:50176
	ds_read_b128 v[188:191], v146 offset:49152
	ds_read_b128 v[192:195], v146 offset:50176
	ds_read_b128 v[196:199], v145 offset:49152
	ds_read_b128 v[202:205], v145 offset:50176
	ds_read_b128 v[206:209], v144 offset:49152
	ds_read_b128 v[216:219], v144 offset:50176
	s_mov_b64 s[2:3], 0x900180
	v_lshl_add_u64 v[222:223], v[212:213], 0, s[2:3]
	v_readfirstlane_b32 s2, v150
	s_mov_b32 m0, s2
	s_mov_b64 s[2:3], 0x920180
	global_load_lds_dwordx4 v[222:223], off
	v_lshl_add_u64 v[222:223], v[212:213], 0, s[2:3]
	v_readfirstlane_b32 s2, v151
	s_mov_b32 m0, s2
	s_nop 0
	global_load_lds_dwordx4 v[222:223], off
	v_readfirstlane_b32 s2, v152
	v_lshl_add_u64 v[222:223], v[210:211], 0, s[50:51]
	s_mov_b32 m0, s2
	v_readfirstlane_b32 s2, v153
	global_load_lds_dwordx4 v[222:223], off
	v_lshl_add_u64 v[210:211], v[210:211], 0, s[52:53]
	s_mov_b32 m0, s2
	s_nop 0
	global_load_lds_dwordx4 v[210:211], off
	s_mov_b64 s[2:3], 0x940180
	v_lshl_add_u64 v[244:245], v[212:213], 0, s[2:3]
	v_readfirstlane_b32 s2, v155
	s_mov_b32 m0, s2
	s_mov_b64 s[2:3], 0x960180
	global_load_lds_dwordx4 v[244:245], off
	v_lshl_add_u64 v[244:245], v[212:213], 0, s[2:3]
	v_readfirstlane_b32 s2, v156
	s_mov_b32 m0, s2
	s_nop 0
	global_load_lds_dwordx4 v[244:245], off
	s_waitcnt vmcnt(8)
	s_barrier
	s_waitcnt lgkmcnt(0)
	v_mfma_f32_16x16x32_bf16 v[62:65], v[164:167], v[180:183], v[62:65]
	v_mfma_f32_16x16x32_bf16 v[58:61], v[172:175], v[180:183], v[58:61]
	v_mfma_f32_16x16x32_bf16 v[54:57], v[164:167], v[188:191], v[54:57]
	v_mfma_f32_16x16x32_bf16 v[50:53], v[172:175], v[188:191], v[50:53]
	v_mfma_f32_16x16x32_bf16 v[46:49], v[164:167], v[196:199], v[46:49]
	v_mfma_f32_16x16x32_bf16 v[42:45], v[172:175], v[196:199], v[42:45]
	v_mfma_f32_16x16x32_bf16 v[38:41], v[164:167], v[206:209], v[38:41]
	v_mfma_f32_16x16x32_bf16 v[34:37], v[172:175], v[206:209], v[34:37]
	v_mfma_f32_16x16x32_bf16 v[62:65], v[168:171], v[184:187], v[62:65]
	v_mfma_f32_16x16x32_bf16 v[58:61], v[176:179], v[184:187], v[58:61]
	v_mfma_f32_16x16x32_bf16 v[54:57], v[168:171], v[192:195], v[54:57]
	v_mfma_f32_16x16x32_bf16 v[50:53], v[176:179], v[192:195], v[50:53]
	v_mfma_f32_16x16x32_bf16 v[46:49], v[168:171], v[202:205], v[46:49]
	v_mfma_f32_16x16x32_bf16 v[42:45], v[176:179], v[202:205], v[42:45]
	v_mfma_f32_16x16x32_bf16 v[38:41], v[168:171], v[216:219], v[38:41]
	v_mfma_f32_16x16x32_bf16 v[34:37], v[176:179], v[216:219], v[34:37]
	v_mfma_f32_16x16x32_bf16 v[30:33], v[228:231], v[180:183], v[30:33]
	v_mfma_f32_16x16x32_bf16 v[26:29], v[236:239], v[180:183], v[26:29]
	v_mfma_f32_16x16x32_bf16 v[22:25], v[228:231], v[188:191], v[22:25]
	v_mfma_f32_16x16x32_bf16 v[18:21], v[236:239], v[188:191], v[18:21]
	v_mfma_f32_16x16x32_bf16 v[14:17], v[228:231], v[196:199], v[14:17]
	v_mfma_f32_16x16x32_bf16 v[10:13], v[236:239], v[196:199], v[10:13]
	v_mfma_f32_16x16x32_bf16 v[6:9], v[228:231], v[206:209], v[6:9]
	v_mfma_f32_16x16x32_bf16 v[2:5], v[236:239], v[206:209], v[2:5]
	v_mfma_f32_16x16x32_bf16 v[30:33], v[232:235], v[184:187], v[30:33]
	v_mfma_f32_16x16x32_bf16 v[26:29], v[240:243], v[184:187], v[26:29]
	v_mfma_f32_16x16x32_bf16 v[22:25], v[232:235], v[192:195], v[22:25]
	v_mfma_f32_16x16x32_bf16 v[18:21], v[240:243], v[192:195], v[18:21]
	v_mfma_f32_16x16x32_bf16 v[14:17], v[232:235], v[202:205], v[14:17]
	v_mfma_f32_16x16x32_bf16 v[10:13], v[240:243], v[202:205], v[10:13]
	v_mfma_f32_16x16x32_bf16 v[6:9], v[232:235], v[216:219], v[6:9]
	v_mfma_f32_16x16x32_bf16 v[2:5], v[240:243], v[216:219], v[2:5]
	s_barrier
	s_add_i32 s15, s15, 2
	s_add_u32 s0, s0, 0x100
	s_addc_u32 s1, s1, 0
	s_add_u32 s12, s12, 0x100
	s_addc_u32 s13, s13, 0
	s_cmp_lt_u32 s15, 12
	s_cbranch_scc1 .LBB0_90
	s_or_b32 s0, s38, 0x80
	s_ashr_i32 s1, s0, 31
	s_lshl_b64 s[0:1], s[0:1], 11
	s_add_u32 s0, s80, s0
	s_addc_u32 s1, s81, s1
	v_lshl_add_u64 v[130:131], s[0:1], 0, v[0:1]
	s_mov_b64 s[0:1], 0x780
	ds_read_b128 v[150:153], v157
	ds_read_b128 v[164:167], v157 offset:1024
	ds_read_b128 v[168:171], v157 offset:2048
	ds_read_b128 v[172:175], v157 offset:3072
	ds_read_b128 v[176:179], v147
	ds_read_b128 v[180:183], v147 offset:1024
	ds_read_b128 v[184:187], v146
	ds_read_b128 v[188:191], v146 offset:1024
	ds_read_b128 v[192:195], v145
	ds_read_b128 v[196:199], v145 offset:1024
	ds_read_b128 v[202:205], v144
	ds_read_b128 v[206:209], v144 offset:1024
	v_lshl_add_u64 v[156:157], v[130:131], 0, s[0:1]
	v_readfirstlane_b32 s0, v161
	s_mov_b32 m0, s0
	s_mov_b64 s[0:1], 0x20780
	v_lshl_add_u64 v[130:131], v[130:131], 0, s[0:1]
	v_readfirstlane_b32 s0, v162
	global_load_lds_dwordx4 v[156:157], off
	s_mov_b32 m0, s0
	s_nop 0
	global_load_lds_dwordx4 v[130:131], off
	s_waitcnt vmcnt(8)
	s_barrier
	s_waitcnt lgkmcnt(0)
	s_setprio 1
	s_waitcnt lgkmcnt(0)
	v_mfma_f32_16x16x32_bf16 v[126:129], v[150:153], v[176:179], v[126:129]
	v_mfma_f32_16x16x32_bf16 v[118:121], v[150:153], v[184:187], v[118:121]
	v_mfma_f32_16x16x32_bf16 v[110:113], v[150:153], v[192:195], v[110:113]
	v_mfma_f32_16x16x32_bf16 v[102:105], v[150:153], v[202:205], v[102:105]
	v_mfma_f32_16x16x32_bf16 v[126:129], v[164:167], v[180:183], v[126:129]
	v_mfma_f32_16x16x32_bf16 v[122:125], v[168:171], v[176:179], v[122:125]
	v_mfma_f32_16x16x32_bf16 v[118:121], v[164:167], v[188:191], v[118:121]
	v_mfma_f32_16x16x32_bf16 v[114:117], v[168:171], v[184:187], v[114:117]
	v_mfma_f32_16x16x32_bf16 v[110:113], v[164:167], v[196:199], v[110:113]
	v_mfma_f32_16x16x32_bf16 v[106:109], v[168:171], v[192:195], v[106:109]
	v_mfma_f32_16x16x32_bf16 v[102:105], v[164:167], v[206:209], v[102:105]
	v_mfma_f32_16x16x32_bf16 v[98:101], v[168:171], v[202:205], v[98:101]
	v_mfma_f32_16x16x32_bf16 v[216:219], v[172:175], v[180:183], v[122:125]
	v_mfma_f32_16x16x32_bf16 v[228:231], v[172:175], v[188:191], v[114:117]
	v_mfma_f32_16x16x32_bf16 v[232:235], v[172:175], v[196:199], v[106:109]
	v_mfma_f32_16x16x32_bf16 v[236:239], v[172:175], v[206:209], v[98:101]
	s_setprio 0
	s_barrier
; #define LDA(dst, b, h) for (int m = 0; m < 4; ++m) for (int k = 0; k < 2; ++k) \
;     dst[m][k] = *reinterpret_cast<const bf16x8*>((char*)SA(b, h) + lds_byte(wr * 64 + m * 16 + fr, k * 32 + fq * 8))
; #define LDB(dst, b, h) for (int n = 0; n < 2; ++n) for (int k = 0; k < 2; ++k) \
;     dst[n][k] = *reinterpret_cast<const bf16x8*>((char*)SB(b, h) + lds_byte(wc * 32 + n * 16 + fr, k * 32 + fq * 8))
; #define MMA(ai, bj, At_, Bt_) do { __builtin_amdgcn_s_setprio(1); \
;     for (int m = 0; m < 4; ++m) for (int n = 0; n < 2; ++n) for (int k = 0; k < 2; ++k) \
;       acc[ai][bj][m][n] = __builtin_amdgcn_mfma_f32_16x16x32_bf16(At_[m][k], Bt_[n][k], acc[ai][bj][m][n], 0, 0, 0); \
;     __builtin_amdgcn_s_setprio(0); } while (0)
; #define WAIT_V(n) asm volatile("s_waitcnt vmcnt(" #n ")" ::: "memory")
; #define WAIT_L(n) asm volatile("s_waitcnt lgkmcnt(" #n ")" ::: "memory")
; #define BAR __builtin_amdgcn_s_barrier()
; #define SCHED __builtin_amdgcn_sched_barrier(0)
; template <int EPI>
; __device__ __forceinline__ void gemm_tile(const GemmArgs& g, int brow, int bcol, int parity, bool first, bool nvalid, int nbrow, int nbcol) {
;     ...
;   { LDB(B0, 0, 0); LDA(At, 0, 0); STAGE_A(SA(1, 1), brow + HALF, nt - 1);
;     BAR; WAIT_L(0); MMA(0, 0, At, B0); BAR;
;     LDB(B1, 0, 1); BAR; WAIT_L(0); MMA(0, 1, At, B1); BAR; SCHED;
;     LDA(At, 0, 1); WAIT_V(4); BAR; WAIT_L(0); MMA(1, 0, At, B0); MMA(1, 1, At, B1); BAR; }
;   { LDB(B0, 1, 0); LDA(At, 1, 0); WAIT_V(2); BAR; WAIT_L(0); MMA(0, 0, At, B0); BAR;
	s_nop 1
	ds_read_b128 v[98:101], v154
	ds_read_b128 v[106:109], v154 offset:1024
	ds_read_b128 v[114:117], v154 offset:2048
	ds_read_b128 v[122:125], v154 offset:3072
	s_barrier
	s_waitcnt lgkmcnt(0)
	s_setprio 1
	s_waitcnt lgkmcnt(0)
	v_mfma_f32_16x16x32_bf16 v[94:97], v[98:101], v[176:179], v[94:97]
	v_mfma_f32_16x16x32_bf16 v[86:89], v[98:101], v[184:187], v[86:89]
	v_mfma_f32_16x16x32_bf16 v[78:81], v[98:101], v[192:195], v[78:81]
	v_mfma_f32_16x16x32_bf16 v[70:73], v[98:101], v[202:205], v[70:73]
	v_mfma_f32_16x16x32_bf16 v[94:97], v[106:109], v[180:183], v[94:97]
	v_mfma_f32_16x16x32_bf16 v[90:93], v[114:117], v[176:179], v[90:93]
	v_mfma_f32_16x16x32_bf16 v[86:89], v[106:109], v[188:191], v[86:89]
	v_mfma_f32_16x16x32_bf16 v[82:85], v[114:117], v[184:187], v[82:85]
	v_mfma_f32_16x16x32_bf16 v[78:81], v[106:109], v[196:199], v[78:81]
	v_mfma_f32_16x16x32_bf16 v[74:77], v[114:117], v[192:195], v[74:77]
	v_mfma_f32_16x16x32_bf16 v[70:73], v[106:109], v[206:209], v[70:73]
	v_mfma_f32_16x16x32_bf16 v[66:69], v[114:117], v[202:205], v[66:69]
	v_mfma_f32_16x16x32_bf16 v[154:157], v[122:125], v[180:183], v[90:93]
	v_mfma_f32_16x16x32_bf16 v[176:179], v[122:125], v[188:191], v[82:85]
	v_mfma_f32_16x16x32_bf16 v[180:183], v[122:125], v[196:199], v[74:77]
	v_mfma_f32_16x16x32_bf16 v[184:187], v[122:125], v[206:209], v[66:69]
	s_setprio 0
	s_barrier
	s_nop 1
	ds_read_b128 v[66:69], v147 offset:16384
	ds_read_b128 v[74:77], v147 offset:17408
	ds_read_b128 v[82:85], v146 offset:16384
	ds_read_b128 v[90:93], v146 offset:17408
	ds_read_b128 v[188:191], v145 offset:16384
	ds_read_b128 v[192:195], v145 offset:17408
	ds_read_b128 v[196:199], v144 offset:16384
	ds_read_b128 v[202:205], v144 offset:17408
	s_waitcnt vmcnt(4)
	s_barrier
	s_waitcnt lgkmcnt(0)
	s_setprio 1
	s_waitcnt lgkmcnt(0)
	v_mfma_f32_16x16x32_bf16 v[62:65], v[150:153], v[66:69], v[62:65]
	v_mfma_f32_16x16x32_bf16 v[54:57], v[150:153], v[82:85], v[54:57]
	v_mfma_f32_16x16x32_bf16 v[46:49], v[150:153], v[188:191], v[46:49]
	v_mfma_f32_16x16x32_bf16 v[38:41], v[150:153], v[196:199], v[38:41]
	v_mfma_f32_16x16x32_bf16 v[62:65], v[164:167], v[74:77], v[62:65]
	v_mfma_f32_16x16x32_bf16 v[58:61], v[168:171], v[66:69], v[58:61]
	v_mfma_f32_16x16x32_bf16 v[54:57], v[164:167], v[90:93], v[54:57]
	v_mfma_f32_16x16x32_bf16 v[50:53], v[168:171], v[82:85], v[50:53]
	v_mfma_f32_16x16x32_bf16 v[46:49], v[164:167], v[192:195], v[46:49]
	v_mfma_f32_16x16x32_bf16 v[42:45], v[168:171], v[188:191], v[42:45]
	v_mfma_f32_16x16x32_bf16 v[38:41], v[164:167], v[202:205], v[38:41]
	v_mfma_f32_16x16x32_bf16 v[34:37], v[168:171], v[196:199], v[34:37]
	v_mfma_f32_16x16x32_bf16 v[206:209], v[172:175], v[74:77], v[58:61]
	v_mfma_f32_16x16x32_bf16 v[240:243], v[172:175], v[90:93], v[50:53]
	v_mfma_f32_16x16x32_bf16 v[244:247], v[172:175], v[192:195], v[42:45]
	v_mfma_f32_16x16x32_bf16 v[150:153], v[172:175], v[202:205], v[34:37]
	s_setprio 0
	s_setprio 1
	v_mfma_f32_16x16x32_bf16 v[30:33], v[98:101], v[66:69], v[30:33]
	v_mfma_f32_16x16x32_bf16 v[22:25], v[98:101], v[82:85], v[22:25]
	v_mfma_f32_16x16x32_bf16 v[14:17], v[98:101], v[188:191], v[14:17]
	v_mfma_f32_16x16x32_bf16 v[6:9], v[98:101], v[196:199], v[6:9]
	v_mfma_f32_16x16x32_bf16 v[30:33], v[106:109], v[74:77], v[30:33]
	v_mfma_f32_16x16x32_bf16 v[26:29], v[114:117], v[66:69], v[26:29]
	v_mfma_f32_16x16x32_bf16 v[22:25], v[106:109], v[90:93], v[22:25]
	v_mfma_f32_16x16x32_bf16 v[18:21], v[114:117], v[82:85], v[18:21]
	v_mfma_f32_16x16x32_bf16 v[14:17], v[106:109], v[192:195], v[14:17]
	v_mfma_f32_16x16x32_bf16 v[10:13], v[114:117], v[188:191], v[10:13]
	v_mfma_f32_16x16x32_bf16 v[6:9], v[106:109], v[202:205], v[6:9]
	v_mfma_f32_16x16x32_bf16 v[2:5], v[114:117], v[196:199], v[2:5]
	v_mfma_f32_16x16x32_bf16 v[162:165], v[122:125], v[74:77], v[26:29]
	v_mfma_f32_16x16x32_bf16 v[166:169], v[122:125], v[90:93], v[18:21]
	v_mfma_f32_16x16x32_bf16 v[170:173], v[122:125], v[192:195], v[10:13]
	v_mfma_f32_16x16x32_bf16 v[188:191], v[122:125], v[202:205], v[2:5]
	s_setprio 0
	s_barrier
	s_nop 1
	ds_read_b128 v[2:5], v149
	ds_read_b128 v[10:13], v149 offset:1024
	ds_read_b128 v[18:21], v149 offset:2048
	ds_read_b128 v[26:29], v149 offset:3072
	ds_read_b128 v[34:37], v147 offset:32768
	ds_read_b128 v[42:45], v147 offset:33792
	ds_read_b128 v[50:53], v146 offset:32768
	ds_read_b128 v[58:61], v146 offset:33792
	ds_read_b128 v[66:69], v145 offset:32768
	ds_read_b128 v[192:195], v145 offset:33792
	ds_read_b128 v[196:199], v144 offset:32768
	ds_read_b128 v[202:205], v144 offset:33792
	s_waitcnt vmcnt(2)
	s_barrier
; #define LDA(dst, b, h) for (int m = 0; m < 4; ++m) for (int k = 0; k < 2; ++k) \
;     dst[m][k] = *reinterpret_cast<const bf16x8*>((char*)SA(b, h) + lds_byte(wr * 64 + m * 16 + fr, k * 32 + fq * 8))
; #define LDB(dst, b, h) for (int n = 0; n < 2; ++n) for (int k = 0; k < 2; ++k) \
;     dst[n][k] = *reinterpret_cast<const bf16x8*>((char*)SB(b, h) + lds_byte(wc * 32 + n * 16 + fr, k * 32 + fq * 8))
; #define MMA(ai, bj, At_, Bt_) do { __builtin_amdgcn_s_setprio(1); \
;     for (int m = 0; m < 4; ++m) for (int n = 0; n < 2; ++n) for (int k = 0; k < 2; ++k) \
;       acc[ai][bj][m][n] = __builtin_amdgcn_mfma_f32_16x16x32_bf16(At_[m][k], Bt_[n][k], acc[ai][bj][m][n], 0, 0, 0); \
;     __builtin_amdgcn_s_setprio(0); } while (0)
; #define WAIT_V(n) asm volatile("s_waitcnt vmcnt(" #n ")" ::: "memory")
; #define WAIT_L(n) asm volatile("s_waitcnt lgkmcnt(" #n ")" ::: "memory")
; #define BAR __builtin_amdgcn_s_barrier()
; #define SCHED __builtin_amdgcn_sched_barrier(0)
; template <int EPI>
; __device__ __forceinline__ void gemm_tile(const GemmArgs& g, int brow, int bcol, int parity, bool first, bool nvalid, int nbrow, int nbcol) {
;     ...
;     LDA(At, 0, 1); WAIT_V(4); BAR; WAIT_L(0); MMA(1, 0, At, B0); MMA(1, 1, At, B1); BAR; }
;   { LDB(B0, 1, 0); LDA(At, 1, 0); WAIT_V(2); BAR; WAIT_L(0); MMA(0, 0, At, B0); BAR;
;     LDB(B1, 1, 1); WAIT_V(0); BAR; WAIT_L(0); MMA(0, 1, At, B1); BAR; SCHED;
;     LDA(At, 1, 1); BAR; WAIT_L(0); MMA(1, 0, At, B0); MMA(1, 1, At, B1); BAR; }
;   if (wr == 0) BAR;
	s_waitcnt lgkmcnt(0)
	s_setprio 1
	s_waitcnt lgkmcnt(0)
	v_mfma_f32_16x16x32_bf16 v[74:77], v[2:5], v[34:37], v[126:129]
	v_mfma_f32_16x16x32_bf16 v[122:125], v[10:13], v[42:45], v[74:77]
	v_mfma_f32_16x16x32_bf16 v[74:77], v[18:21], v[34:37], v[216:219]
	v_mfma_f32_16x16x32_bf16 v[126:129], v[26:29], v[42:45], v[74:77]
	v_mfma_f32_16x16x32_bf16 v[74:77], v[2:5], v[50:53], v[118:121]
	v_mfma_f32_16x16x32_bf16 v[114:117], v[10:13], v[58:61], v[74:77]
	v_mfma_f32_16x16x32_bf16 v[74:77], v[18:21], v[50:53], v[228:231]
	v_mfma_f32_16x16x32_bf16 v[118:121], v[26:29], v[58:61], v[74:77]
	v_mfma_f32_16x16x32_bf16 v[74:77], v[2:5], v[66:69], v[110:113]
	v_mfma_f32_16x16x32_bf16 v[106:109], v[10:13], v[192:195], v[74:77]
	v_mfma_f32_16x16x32_bf16 v[74:77], v[18:21], v[66:69], v[232:235]
	v_mfma_f32_16x16x32_bf16 v[110:113], v[26:29], v[192:195], v[74:77]
	v_mfma_f32_16x16x32_bf16 v[74:77], v[2:5], v[196:199], v[102:105]
	v_mfma_f32_16x16x32_bf16 v[98:101], v[10:13], v[202:205], v[74:77]
	v_mfma_f32_16x16x32_bf16 v[74:77], v[18:21], v[196:199], v[236:239]
	v_mfma_f32_16x16x32_bf16 v[102:105], v[26:29], v[202:205], v[74:77]
	s_setprio 0
	s_barrier
	ds_read_b128 v[216:219], v148
	ds_read_b128 v[228:231], v148 offset:1024
	ds_read_b128 v[232:235], v148 offset:2048
	ds_read_b128 v[236:239], v148 offset:3072
	s_waitcnt vmcnt(0)
	s_barrier
	s_waitcnt lgkmcnt(0)
	s_setprio 1
	s_waitcnt lgkmcnt(0)
	v_mfma_f32_16x16x32_bf16 v[74:77], v[216:219], v[34:37], v[94:97]
	v_mfma_f32_16x16x32_bf16 v[34:37], v[232:235], v[34:37], v[154:157]
	v_mfma_f32_16x16x32_bf16 v[94:97], v[236:239], v[42:45], v[34:37]
	v_mfma_f32_16x16x32_bf16 v[34:37], v[216:219], v[50:53], v[86:89]
	v_mfma_f32_16x16x32_bf16 v[82:85], v[228:231], v[58:61], v[34:37]
	v_mfma_f32_16x16x32_bf16 v[34:37], v[232:235], v[50:53], v[176:179]
	v_mfma_f32_16x16x32_bf16 v[86:89], v[236:239], v[58:61], v[34:37]
	v_mfma_f32_16x16x32_bf16 v[34:37], v[216:219], v[66:69], v[78:81]
	v_mfma_f32_16x16x32_bf16 v[90:93], v[228:231], v[42:45], v[74:77]
	v_mfma_f32_16x16x32_bf16 v[74:77], v[228:231], v[192:195], v[34:37]
	v_mfma_f32_16x16x32_bf16 v[34:37], v[232:235], v[66:69], v[180:183]
	v_mfma_f32_16x16x32_bf16 v[78:81], v[236:239], v[192:195], v[34:37]
	v_mfma_f32_16x16x32_bf16 v[34:37], v[216:219], v[196:199], v[70:73]
	v_mfma_f32_16x16x32_bf16 v[66:69], v[228:231], v[202:205], v[34:37]
	v_mfma_f32_16x16x32_bf16 v[34:37], v[232:235], v[196:199], v[184:187]
	v_mfma_f32_16x16x32_bf16 v[70:73], v[236:239], v[202:205], v[34:37]
	s_setprio 0
	s_barrier
	ds_read_b128 v[154:157], v147 offset:49152
	ds_read_b128 v[174:177], v147 offset:50176
	ds_read_b128 v[178:181], v146 offset:49152
	ds_read_b128 v[146:149], v146 offset:50176
	ds_read_b128 v[182:185], v145 offset:49152
	ds_read_b128 v[192:195], v145 offset:50176
	ds_read_b128 v[196:199], v144 offset:49152
	ds_read_b128 v[202:205], v144 offset:50176
	s_barrier
	s_waitcnt lgkmcnt(0)
	s_setprio 1
	s_waitcnt lgkmcnt(0)
	v_mfma_f32_16x16x32_bf16 v[34:37], v[2:5], v[154:157], v[62:65]
	v_mfma_f32_16x16x32_bf16 v[58:61], v[10:13], v[174:177], v[34:37]
	v_mfma_f32_16x16x32_bf16 v[34:37], v[18:21], v[154:157], v[206:209]
	v_mfma_f32_16x16x32_bf16 v[62:65], v[26:29], v[174:177], v[34:37]
	v_mfma_f32_16x16x32_bf16 v[34:37], v[2:5], v[178:181], v[54:57]
	v_mfma_f32_16x16x32_bf16 v[50:53], v[10:13], v[146:149], v[34:37]
	v_mfma_f32_16x16x32_bf16 v[34:37], v[18:21], v[178:181], v[240:243]
	v_mfma_f32_16x16x32_bf16 v[54:57], v[26:29], v[146:149], v[34:37]
	v_mfma_f32_16x16x32_bf16 v[34:37], v[2:5], v[182:185], v[46:49]
	v_mfma_f32_16x16x32_bf16 v[42:45], v[10:13], v[192:195], v[34:37]
	v_mfma_f32_16x16x32_bf16 v[34:37], v[18:21], v[182:185], v[244:247]
	v_mfma_f32_16x16x32_bf16 v[2:5], v[2:5], v[196:199], v[38:41]
	v_mfma_f32_16x16x32_bf16 v[46:49], v[26:29], v[192:195], v[34:37]
	v_mfma_f32_16x16x32_bf16 v[34:37], v[10:13], v[202:205], v[2:5]
	v_mfma_f32_16x16x32_bf16 v[2:5], v[18:21], v[196:199], v[150:153]
	v_mfma_f32_16x16x32_bf16 v[38:41], v[26:29], v[202:205], v[2:5]
	s_setprio 0
	s_setprio 1
	v_mfma_f32_16x16x32_bf16 v[2:5], v[216:219], v[154:157], v[30:33]
	v_mfma_f32_16x16x32_bf16 v[26:29], v[228:231], v[174:177], v[2:5]
	v_mfma_f32_16x16x32_bf16 v[2:5], v[232:235], v[154:157], v[162:165]
	v_mfma_f32_16x16x32_bf16 v[30:33], v[236:239], v[174:177], v[2:5]
	v_mfma_f32_16x16x32_bf16 v[2:5], v[216:219], v[178:181], v[22:25]
	v_mfma_f32_16x16x32_bf16 v[18:21], v[228:231], v[146:149], v[2:5]
	v_mfma_f32_16x16x32_bf16 v[2:5], v[232:235], v[178:181], v[166:169]
	v_mfma_f32_16x16x32_bf16 v[22:25], v[236:239], v[146:149], v[2:5]
	v_mfma_f32_16x16x32_bf16 v[2:5], v[216:219], v[182:185], v[14:17]
	v_mfma_f32_16x16x32_bf16 v[10:13], v[228:231], v[192:195], v[2:5]
	v_mfma_f32_16x16x32_bf16 v[2:5], v[232:235], v[182:185], v[170:173]
	v_mfma_f32_16x16x32_bf16 v[14:17], v[236:239], v[192:195], v[2:5]
	v_mfma_f32_16x16x32_bf16 v[2:5], v[216:219], v[196:199], v[6:9]
	v_mfma_f32_16x16x32_bf16 v[6:9], v[232:235], v[196:199], v[188:191]
	v_mfma_f32_16x16x32_bf16 v[2:5], v[228:231], v[202:205], v[2:5]
	v_mfma_f32_16x16x32_bf16 v[6:9], v[236:239], v[202:205], v[6:9]
	s_setprio 0
	s_movk_i32 s0, 0x100
	v_cmp_gt_u32_e32 vcc, s0, v138
	s_barrier
	s_and_saveexec_b64 s[0:1], vcc
	s_cbranch_execz .LBB0_93
	s_barrier

; #define STAGE_B(P, br, kt) do { const char* _gb = (const char*)(Bt + ((long)(br) * K + (long)(kt) * BK)); \
;     __builtin_amdgcn_global_load_lds((const unsigned*)(_gb + bofl0), (unsigned*)((char*)(P) + gtid_ * 16), 16, 0, 0); \
;     __builtin_amdgcn_global_load_lds((const unsigned*)(_gb + (long)K * 128 + bofl0), (unsigned*)((char*)(P) + gtid_ * 16 + 8192), 16, 0, 0); } while (0)
; #define LDA(dst, b, h) for (int m = 0; m < 4; ++m) for (int k = 0; k < 2; ++k) \
;     dst[m][k] = *reinterpret_cast<const bf16x8*>((char*)SA(b, h) + lds_byte(wr * 64 + m * 16 + fr, k * 32 + fq * 8))
; #define LDB(dst, b, h) for (int n = 0; n < 2; ++n) for (int k = 0; k < 2; ++k) \
;     dst[n][k] = *reinterpret_cast<const bf16x8*>((char*)SB(b, h) + lds_byte(wc * 32 + n * 16 + fr, k * 32 + fq * 8))
; #define MMA(ai, bj, At_, Bt_) do { __builtin_amdgcn_s_setprio(1); \
;     for (int m = 0; m < 4; ++m) for (int n = 0; n < 2; ++n) for (int k = 0; k < 2; ++k) \
;       acc[ai][bj][m][n] = __builtin_amdgcn_mfma_f32_16x16x32_bf16(At_[m][k], Bt_[n][k], acc[ai][bj][m][n], 0, 0, 0); \
;     __builtin_amdgcn_s_setprio(0); } while (0)
; #define WAIT_V(n) asm volatile("s_waitcnt vmcnt(" #n ")" ::: "memory")
; #define WAIT_L(n) asm volatile("s_waitcnt lgkmcnt(" #n ")" ::: "memory")
; #define BAR __builtin_amdgcn_s_barrier()
; #define SCHED __builtin_amdgcn_sched_barrier(0)
; template <int EPI>
; __device__ __forceinline__ void gemm_tile(const GemmArgs& g, int brow, int bcol, int parity, bool first, bool nvalid, int nbrow, int nbcol) {
;     ...
;   for (int t = 0; t < nt - 2; t += 2) {
;     LDB(B0, 0, 0); SCHED; LDA(At, 0, 0); STAGE_A(SA(1, 1), brow + HALF, t + 1);
;     WAIT_L(8); BAR; WAIT_L(0); MMA(0, 0, At, B0); BAR; SCHED;
;     LDB(B1, 0, 1); STAGE_B(SB(0, 0), bcol, t + 2);
;     BAR; WAIT_L(0); MMA(0, 1, At, B1); BAR; SCHED;
;     LDA(At, 0, 1); STAGE_A(SA(0, 0), brow, t + 2);
;     BAR; WAIT_L(0); MMA(1, 0, At, B0); BAR; SCHED;
;     STAGE_B(SB(0, 1), bcol + HALF, t + 2);
;     WAIT_V(6); BAR; MMA(1, 1, At, B1); BAR; SCHED;
.LBB0_133:
	ds_read_b128 v[164:167], v157
	ds_read_b128 v[168:171], v157 offset:1024
	ds_read_b128 v[172:175], v157 offset:2048
	ds_read_b128 v[176:179], v157 offset:3072
	ds_read_b128 v[180:183], v146
	ds_read_b128 v[184:187], v146 offset:1024
	ds_read_b128 v[188:191], v145
	ds_read_b128 v[192:195], v145 offset:1024
	ds_read_b128 v[196:199], v144
	ds_read_b128 v[202:205], v144 offset:1024
	ds_read_b128 v[206:209], v143
	ds_read_b128 v[216:219], v143 offset:1024
	s_waitcnt lgkmcnt(6)
	ds_read_b128 v[222:225], v154
	ds_read_b128 v[228:231], v154 offset:1024
	ds_read_b128 v[232:235], v154 offset:2048
	ds_read_b128 v[236:239], v154 offset:3072
	v_add_u32_e32 v161, 0xc000, v137
	v_lshl_add_u64 v[210:211], s[12:13], 0, v[130:131]
	v_readfirstlane_b32 s2, v161
	v_add_u32_e32 v162, 0xe000, v137
	v_lshl_add_u64 v[158:159], v[210:211], 0, s[24:25]
	s_mov_b32 m0, s2
	v_readfirstlane_b32 s2, v162
	global_load_lds_dwordx4 v[158:159], off
	v_lshl_add_u64 v[158:159], v[210:211], 0, s[34:35]
	s_mov_b32 m0, s2
	s_nop 0
	global_load_lds_dwordx4 v[158:159], off
	s_waitcnt vmcnt(8)
	s_barrier
	s_waitcnt lgkmcnt(0)
	v_mfma_f32_16x16x32_bf16 v[126:129], v[180:183], v[164:167], v[126:129]
	v_mfma_f32_16x16x32_bf16 v[122:125], v[180:183], v[172:175], v[122:125]
	v_mfma_f32_16x16x32_bf16 v[118:121], v[188:191], v[164:167], v[118:121]
	v_mfma_f32_16x16x32_bf16 v[114:117], v[188:191], v[172:175], v[114:117]
	v_mfma_f32_16x16x32_bf16 v[110:113], v[196:199], v[164:167], v[110:113]
	v_mfma_f32_16x16x32_bf16 v[106:109], v[196:199], v[172:175], v[106:109]
	v_mfma_f32_16x16x32_bf16 v[102:105], v[206:209], v[164:167], v[102:105]
	v_mfma_f32_16x16x32_bf16 v[98:101], v[206:209], v[172:175], v[98:101]
	v_mfma_f32_16x16x32_bf16 v[126:129], v[184:187], v[168:171], v[126:129]
	v_mfma_f32_16x16x32_bf16 v[122:125], v[184:187], v[176:179], v[122:125]
	v_mfma_f32_16x16x32_bf16 v[118:121], v[192:195], v[168:171], v[118:121]
	v_mfma_f32_16x16x32_bf16 v[114:117], v[192:195], v[176:179], v[114:117]
	v_mfma_f32_16x16x32_bf16 v[110:113], v[202:205], v[168:171], v[110:113]
	v_mfma_f32_16x16x32_bf16 v[106:109], v[202:205], v[176:179], v[106:109]
	v_mfma_f32_16x16x32_bf16 v[102:105], v[216:219], v[168:171], v[102:105]
	v_mfma_f32_16x16x32_bf16 v[98:101], v[216:219], v[176:179], v[98:101]
	v_mfma_f32_16x16x32_bf16 v[94:97], v[180:183], v[222:225], v[94:97]
	v_mfma_f32_16x16x32_bf16 v[90:93], v[180:183], v[232:235], v[90:93]
	v_mfma_f32_16x16x32_bf16 v[86:89], v[188:191], v[222:225], v[86:89]
	v_mfma_f32_16x16x32_bf16 v[82:85], v[188:191], v[232:235], v[82:85]
	v_mfma_f32_16x16x32_bf16 v[78:81], v[196:199], v[222:225], v[78:81]
	v_mfma_f32_16x16x32_bf16 v[74:77], v[196:199], v[232:235], v[74:77]
	v_mfma_f32_16x16x32_bf16 v[70:73], v[206:209], v[222:225], v[70:73]
	v_mfma_f32_16x16x32_bf16 v[66:69], v[206:209], v[232:235], v[66:69]
	v_mfma_f32_16x16x32_bf16 v[94:97], v[184:187], v[228:231], v[94:97]
	v_mfma_f32_16x16x32_bf16 v[90:93], v[184:187], v[236:239], v[90:93]
	v_mfma_f32_16x16x32_bf16 v[86:89], v[192:195], v[228:231], v[86:89]
	v_mfma_f32_16x16x32_bf16 v[82:85], v[192:195], v[236:239], v[82:85]
	v_mfma_f32_16x16x32_bf16 v[78:81], v[202:205], v[228:231], v[78:81]
	v_mfma_f32_16x16x32_bf16 v[74:77], v[202:205], v[236:239], v[74:77]
	v_mfma_f32_16x16x32_bf16 v[70:73], v[216:219], v[228:231], v[70:73]
	v_mfma_f32_16x16x32_bf16 v[66:69], v[216:219], v[236:239], v[66:69]
	s_barrier
	ds_read_b128 v[180:183], v146 offset:16384
	ds_read_b128 v[184:187], v146 offset:17408
	ds_read_b128 v[188:191], v145 offset:16384
	ds_read_b128 v[192:195], v145 offset:17408
	ds_read_b128 v[196:199], v144 offset:16384
	ds_read_b128 v[202:205], v144 offset:17408
	ds_read_b128 v[206:209], v143 offset:16384
	ds_read_b128 v[216:219], v143 offset:17408
	v_add_u32_e32 v158, s15, v141
	v_lshl_add_u64 v[212:213], s[0:1], 0, v[130:131]
	v_readfirstlane_b32 s2, v158
	v_add_u32_e32 v159, 0x2000, v158
	v_lshl_add_u64 v[240:241], v[212:213], 0, s[78:79]
	s_mov_b32 m0, s2
	v_readfirstlane_b32 s2, v159
	global_load_lds_dwordx4 v[240:241], off
	v_lshl_add_u64 v[240:241], v[212:213], 0, s[52:53]
	s_mov_b32 m0, s2
	s_nop 0
	global_load_lds_dwordx4 v[240:241], off
	v_readfirstlane_b32 s2, v137
	v_lshl_add_u64 v[240:241], v[210:211], 0, s[36:37]
	s_mov_b32 m0, s2
	v_readfirstlane_b32 s2, v136
	global_load_lds_dwordx4 v[240:241], off
	v_lshl_add_u64 v[240:241], v[210:211], 0, s[42:43]
	s_mov_b32 m0, s2
	s_nop 0
	global_load_lds_dwordx4 v[240:241], off
	v_readfirstlane_b32 s2, v135
	v_add_u32_e32 v160, 0x2000, v135
	v_lshl_add_u64 v[244:245], v[212:213], 0, s[56:57]
	s_mov_b32 m0, s2
	v_readfirstlane_b32 s2, v160
	global_load_lds_dwordx4 v[244:245], off
	v_lshl_add_u64 v[244:245], v[212:213], 0, s[66:67]
	s_mov_b32 m0, s2
	s_nop 0
	global_load_lds_dwordx4 v[244:245], off
	s_waitcnt vmcnt(8)
	s_barrier
; #define STAGE_B(P, br, kt) do { const char* _gb = (const char*)(Bt + ((long)(br) * K + (long)(kt) * BK)); \
;     __builtin_amdgcn_global_load_lds((const unsigned*)(_gb + bofl0), (unsigned*)((char*)(P) + gtid_ * 16), 16, 0, 0); \
;     __builtin_amdgcn_global_load_lds((const unsigned*)(_gb + (long)K * 128 + bofl0), (unsigned*)((char*)(P) + gtid_ * 16 + 8192), 16, 0, 0); } while (0)
; #define LDA(dst, b, h) for (int m = 0; m < 4; ++m) for (int k = 0; k < 2; ++k) \
;     dst[m][k] = *reinterpret_cast<const bf16x8*>((char*)SA(b, h) + lds_byte(wr * 64 + m * 16 + fr, k * 32 + fq * 8))
; #define LDB(dst, b, h) for (int n = 0; n < 2; ++n) for (int k = 0; k < 2; ++k) \
;     dst[n][k] = *reinterpret_cast<const bf16x8*>((char*)SB(b, h) + lds_byte(wc * 32 + n * 16 + fr, k * 32 + fq * 8))
; #define MMA(ai, bj, At_, Bt_) do { __builtin_amdgcn_s_setprio(1); \
;     for (int m = 0; m < 4; ++m) for (int n = 0; n < 2; ++n) for (int k = 0; k < 2; ++k) \
;       acc[ai][bj][m][n] = __builtin_amdgcn_mfma_f32_16x16x32_bf16(At_[m][k], Bt_[n][k], acc[ai][bj][m][n], 0, 0, 0); \
;     __builtin_amdgcn_s_setprio(0); } while (0)
; #define WAIT_V(n) asm volatile("s_waitcnt vmcnt(" #n ")" ::: "memory")
; #define WAIT_L(n) asm volatile("s_waitcnt lgkmcnt(" #n ")" ::: "memory")
; #define BAR __builtin_amdgcn_s_barrier()
; #define SCHED __builtin_amdgcn_sched_barrier(0)
; template <int EPI>
; __device__ __forceinline__ void gemm_tile(const GemmArgs& g, int brow, int bcol, int parity, bool first, bool nvalid, int nbrow, int nbcol) {
;     ...
;   for (int t = 0; t < nt - 2; t += 2) {
;     LDB(B0, 0, 0); SCHED; LDA(At, 0, 0); STAGE_A(SA(1, 1), brow + HALF, t + 1);
;     WAIT_L(8); BAR; WAIT_L(0); MMA(0, 0, At, B0); BAR; SCHED;
;     LDB(B1, 0, 1); STAGE_B(SB(0, 0), bcol, t + 2);
;     BAR; WAIT_L(0); MMA(0, 1, At, B1); BAR; SCHED;
;     LDA(At, 0, 1); STAGE_A(SA(0, 0), brow, t + 2);
;     BAR; WAIT_L(0); MMA(1, 0, At, B0); BAR; SCHED;
;     STAGE_B(SB(0, 1), bcol + HALF, t + 2);
;     WAIT_V(6); BAR; MMA(1, 1, At, B1); BAR; SCHED;
;     LDB(B0, 1, 0); SCHED; LDA(At, 1, 0); STAGE_A(SA(0, 1), brow + HALF, t + 2);
;     WAIT_L(8); BAR; WAIT_L(0); MMA(0, 0, At, B0); BAR; SCHED;
;     LDB(B1, 1, 1); STAGE_B(SB(1, 0), bcol, t + 3);
;     BAR; WAIT_L(0); MMA(0, 1, At, B1); BAR; SCHED;
;     LDA(At, 1, 1); STAGE_A(SA(1, 0), brow, t + 3);
;     BAR; WAIT_L(0); MMA(1, 0, At, B0); BAR; SCHED;
	s_waitcnt lgkmcnt(0)
	v_mfma_f32_16x16x32_bf16 v[62:65], v[180:183], v[164:167], v[62:65]
	v_mfma_f32_16x16x32_bf16 v[58:61], v[180:183], v[172:175], v[58:61]
	v_mfma_f32_16x16x32_bf16 v[54:57], v[188:191], v[164:167], v[54:57]
	v_mfma_f32_16x16x32_bf16 v[50:53], v[188:191], v[172:175], v[50:53]
	v_mfma_f32_16x16x32_bf16 v[46:49], v[196:199], v[164:167], v[46:49]
	v_mfma_f32_16x16x32_bf16 v[42:45], v[196:199], v[172:175], v[42:45]
	v_mfma_f32_16x16x32_bf16 v[38:41], v[206:209], v[164:167], v[38:41]
	v_mfma_f32_16x16x32_bf16 v[34:37], v[206:209], v[172:175], v[34:37]
	v_mfma_f32_16x16x32_bf16 v[62:65], v[184:187], v[168:171], v[62:65]
	v_mfma_f32_16x16x32_bf16 v[58:61], v[184:187], v[176:179], v[58:61]
	v_mfma_f32_16x16x32_bf16 v[54:57], v[192:195], v[168:171], v[54:57]
	v_mfma_f32_16x16x32_bf16 v[50:53], v[192:195], v[176:179], v[50:53]
	v_mfma_f32_16x16x32_bf16 v[46:49], v[202:205], v[168:171], v[46:49]
	v_mfma_f32_16x16x32_bf16 v[42:45], v[202:205], v[176:179], v[42:45]
	v_mfma_f32_16x16x32_bf16 v[38:41], v[216:219], v[168:171], v[38:41]
	v_mfma_f32_16x16x32_bf16 v[34:37], v[216:219], v[176:179], v[34:37]
	v_mfma_f32_16x16x32_bf16 v[30:33], v[180:183], v[222:225], v[30:33]
	v_mfma_f32_16x16x32_bf16 v[26:29], v[180:183], v[232:235], v[26:29]
	v_mfma_f32_16x16x32_bf16 v[22:25], v[188:191], v[222:225], v[22:25]
	v_mfma_f32_16x16x32_bf16 v[18:21], v[188:191], v[232:235], v[18:21]
	v_mfma_f32_16x16x32_bf16 v[14:17], v[196:199], v[222:225], v[14:17]
	v_mfma_f32_16x16x32_bf16 v[10:13], v[196:199], v[232:235], v[10:13]
	v_mfma_f32_16x16x32_bf16 v[6:9], v[206:209], v[222:225], v[6:9]
	v_mfma_f32_16x16x32_bf16 v[2:5], v[206:209], v[232:235], v[2:5]
	v_mfma_f32_16x16x32_bf16 v[30:33], v[184:187], v[228:231], v[30:33]
	v_mfma_f32_16x16x32_bf16 v[26:29], v[184:187], v[236:239], v[26:29]
	v_mfma_f32_16x16x32_bf16 v[22:25], v[192:195], v[228:231], v[22:25]
	v_mfma_f32_16x16x32_bf16 v[18:21], v[192:195], v[236:239], v[18:21]
	v_mfma_f32_16x16x32_bf16 v[14:17], v[202:205], v[228:231], v[14:17]
	v_mfma_f32_16x16x32_bf16 v[10:13], v[202:205], v[236:239], v[10:13]
	v_mfma_f32_16x16x32_bf16 v[6:9], v[216:219], v[228:231], v[6:9]
	v_mfma_f32_16x16x32_bf16 v[2:5], v[216:219], v[236:239], v[2:5]
	s_barrier
	ds_read_b128 v[164:167], v148
	ds_read_b128 v[168:171], v148 offset:1024
	ds_read_b128 v[172:175], v148 offset:2048
	ds_read_b128 v[176:179], v148 offset:3072
	ds_read_b128 v[180:183], v146 offset:32768
	ds_read_b128 v[184:187], v146 offset:33792
	ds_read_b128 v[188:191], v145 offset:32768
	ds_read_b128 v[192:195], v145 offset:33792
	ds_read_b128 v[196:199], v144 offset:32768
	ds_read_b128 v[202:205], v144 offset:33792
	ds_read_b128 v[206:209], v143 offset:32768
	ds_read_b128 v[216:219], v143 offset:33792
	s_waitcnt lgkmcnt(6)
	ds_read_b128 v[222:225], v147
	ds_read_b128 v[228:231], v147 offset:1024
	ds_read_b128 v[232:235], v147 offset:2048
	ds_read_b128 v[236:239], v147 offset:3072
	v_readfirstlane_b32 s2, v134
	v_lshl_add_u64 v[246:247], v[210:211], 0, s[44:45]
	s_mov_b32 m0, s2
	v_readfirstlane_b32 s2, v133
	global_load_lds_dwordx4 v[246:247], off
	v_lshl_add_u64 v[246:247], v[210:211], 0, s[46:47]
	s_mov_b32 m0, s2
	s_nop 0
	global_load_lds_dwordx4 v[246:247], off
	s_waitcnt vmcnt(8)
	s_barrier
	s_waitcnt lgkmcnt(0)
	v_mfma_f32_16x16x32_bf16 v[126:129], v[180:183], v[164:167], v[126:129]
	v_mfma_f32_16x16x32_bf16 v[122:125], v[180:183], v[172:175], v[122:125]
	v_mfma_f32_16x16x32_bf16 v[118:121], v[188:191], v[164:167], v[118:121]
	v_mfma_f32_16x16x32_bf16 v[114:117], v[188:191], v[172:175], v[114:117]
	v_mfma_f32_16x16x32_bf16 v[110:113], v[196:199], v[164:167], v[110:113]
	v_mfma_f32_16x16x32_bf16 v[106:109], v[196:199], v[172:175], v[106:109]
	v_mfma_f32_16x16x32_bf16 v[102:105], v[206:209], v[164:167], v[102:105]
	v_mfma_f32_16x16x32_bf16 v[98:101], v[206:209], v[172:175], v[98:101]
	v_mfma_f32_16x16x32_bf16 v[126:129], v[184:187], v[168:171], v[126:129]
	v_mfma_f32_16x16x32_bf16 v[122:125], v[184:187], v[176:179], v[122:125]
	v_mfma_f32_16x16x32_bf16 v[118:121], v[192:195], v[168:171], v[118:121]
	v_mfma_f32_16x16x32_bf16 v[114:117], v[192:195], v[176:179], v[114:117]
	v_mfma_f32_16x16x32_bf16 v[110:113], v[202:205], v[168:171], v[110:113]
	v_mfma_f32_16x16x32_bf16 v[106:109], v[202:205], v[176:179], v[106:109]
	v_mfma_f32_16x16x32_bf16 v[102:105], v[216:219], v[168:171], v[102:105]
	v_mfma_f32_16x16x32_bf16 v[98:101], v[216:219], v[176:179], v[98:101]
	v_mfma_f32_16x16x32_bf16 v[94:97], v[180:183], v[222:225], v[94:97]
	v_mfma_f32_16x16x32_bf16 v[90:93], v[180:183], v[232:235], v[90:93]
	v_mfma_f32_16x16x32_bf16 v[86:89], v[188:191], v[222:225], v[86:89]
	v_mfma_f32_16x16x32_bf16 v[82:85], v[188:191], v[232:235], v[82:85]
	v_mfma_f32_16x16x32_bf16 v[78:81], v[196:199], v[222:225], v[78:81]
	v_mfma_f32_16x16x32_bf16 v[74:77], v[196:199], v[232:235], v[74:77]
	v_mfma_f32_16x16x32_bf16 v[70:73], v[206:209], v[222:225], v[70:73]
	v_mfma_f32_16x16x32_bf16 v[66:69], v[206:209], v[232:235], v[66:69]
	v_mfma_f32_16x16x32_bf16 v[94:97], v[184:187], v[228:231], v[94:97]
	v_mfma_f32_16x16x32_bf16 v[90:93], v[184:187], v[236:239], v[90:93]
	v_mfma_f32_16x16x32_bf16 v[86:89], v[192:195], v[228:231], v[86:89]
	v_mfma_f32_16x16x32_bf16 v[82:85], v[192:195], v[236:239], v[82:85]
	v_mfma_f32_16x16x32_bf16 v[78:81], v[202:205], v[228:231], v[78:81]
	v_mfma_f32_16x16x32_bf16 v[74:77], v[202:205], v[236:239], v[74:77]
	v_mfma_f32_16x16x32_bf16 v[70:73], v[216:219], v[228:231], v[70:73]
	v_mfma_f32_16x16x32_bf16 v[66:69], v[216:219], v[236:239], v[66:69]
	s_barrier
; #define STAGE_B(P, br, kt) do { const char* _gb = (const char*)(Bt + ((long)(br) * K + (long)(kt) * BK)); \
;     __builtin_amdgcn_global_load_lds((const unsigned*)(_gb + bofl0), (unsigned*)((char*)(P) + gtid_ * 16), 16, 0, 0); \
;     __builtin_amdgcn_global_load_lds((const unsigned*)(_gb + (long)K * 128 + bofl0), (unsigned*)((char*)(P) + gtid_ * 16 + 8192), 16, 0, 0); } while (0)
; #define LDA(dst, b, h) for (int m = 0; m < 4; ++m) for (int k = 0; k < 2; ++k) \
;     dst[m][k] = *reinterpret_cast<const bf16x8*>((char*)SA(b, h) + lds_byte(wr * 64 + m * 16 + fr, k * 32 + fq * 8))
; #define LDB(dst, b, h) for (int n = 0; n < 2; ++n) for (int k = 0; k < 2; ++k) \
;     dst[n][k] = *reinterpret_cast<const bf16x8*>((char*)SB(b, h) + lds_byte(wc * 32 + n * 16 + fr, k * 32 + fq * 8))
; #define MMA(ai, bj, At_, Bt_) do { __builtin_amdgcn_s_setprio(1); \
;     for (int m = 0; m < 4; ++m) for (int n = 0; n < 2; ++n) for (int k = 0; k < 2; ++k) \
;       acc[ai][bj][m][n] = __builtin_amdgcn_mfma_f32_16x16x32_bf16(At_[m][k], Bt_[n][k], acc[ai][bj][m][n], 0, 0, 0); \
;     __builtin_amdgcn_s_setprio(0); } while (0)
; #define WAIT_V(n) asm volatile("s_waitcnt vmcnt(" #n ")" ::: "memory")
; #define WAIT_L(n) asm volatile("s_waitcnt lgkmcnt(" #n ")" ::: "memory")
; #define BAR __builtin_amdgcn_s_barrier()
; #define SCHED __builtin_amdgcn_sched_barrier(0)
; template <int EPI>
; __device__ __forceinline__ void gemm_tile(const GemmArgs& g, int brow, int bcol, int parity, bool first, bool nvalid, int nbrow, int nbcol) {
;     ...
;     LDA(At, 1, 1); STAGE_A(SA(1, 0), brow, t + 3);
;     BAR; WAIT_L(0); MMA(1, 0, At, B0); BAR; SCHED;
;     STAGE_B(SB(1, 1), bcol + HALF, t + 3);
;     WAIT_V(6); BAR; MMA(1, 1, At, B1); BAR; SCHED;
;   }
;   { LDB(B0, 0, 0); LDA(At, 0, 0); STAGE_A(SA(1, 1), brow + HALF, nt - 1);
;     BAR; WAIT_L(0); MMA(0, 0, At, B0); BAR;
	ds_read_b128 v[180:183], v146 offset:49152
	ds_read_b128 v[184:187], v146 offset:50176
	ds_read_b128 v[188:191], v145 offset:49152
	ds_read_b128 v[192:195], v145 offset:50176
	ds_read_b128 v[196:199], v144 offset:49152
	ds_read_b128 v[202:205], v144 offset:50176
	ds_read_b128 v[206:209], v143 offset:49152
	ds_read_b128 v[216:219], v143 offset:50176
	v_readfirstlane_b32 s2, v149
	v_lshl_add_u64 v[240:241], v[212:213], 0, s[58:59]
	s_mov_b32 m0, s2
	v_readfirstlane_b32 s2, v151
	global_load_lds_dwordx4 v[240:241], off
	v_lshl_add_u64 v[240:241], v[212:213], 0, s[76:77]
	s_mov_b32 m0, s2
	s_nop 0
	global_load_lds_dwordx4 v[240:241], off
	v_readfirstlane_b32 s2, v152
	v_lshl_add_u64 v[240:241], v[210:211], 0, s[48:49]
	s_mov_b32 m0, s2
	v_readfirstlane_b32 s2, v153
	global_load_lds_dwordx4 v[240:241], off
	v_lshl_add_u64 v[210:211], v[210:211], 0, s[50:51]
	s_mov_b32 m0, s2
	s_nop 0
	global_load_lds_dwordx4 v[210:211], off
	v_readfirstlane_b32 s2, v155
	v_lshl_add_u64 v[244:245], v[212:213], 0, s[96:97]
	s_mov_b32 m0, s2
	v_readfirstlane_b32 s2, v156
	global_load_lds_dwordx4 v[244:245], off
	v_lshl_add_u64 v[244:245], v[212:213], 0, s[60:61]
	s_mov_b32 m0, s2
	s_nop 0
	global_load_lds_dwordx4 v[244:245], off
	s_waitcnt vmcnt(8)
	s_barrier
	s_waitcnt lgkmcnt(0)
	v_mfma_f32_16x16x32_bf16 v[62:65], v[180:183], v[164:167], v[62:65]
	v_mfma_f32_16x16x32_bf16 v[58:61], v[180:183], v[172:175], v[58:61]
	v_mfma_f32_16x16x32_bf16 v[54:57], v[188:191], v[164:167], v[54:57]
	v_mfma_f32_16x16x32_bf16 v[50:53], v[188:191], v[172:175], v[50:53]
	v_mfma_f32_16x16x32_bf16 v[46:49], v[196:199], v[164:167], v[46:49]
	v_mfma_f32_16x16x32_bf16 v[42:45], v[196:199], v[172:175], v[42:45]
	v_mfma_f32_16x16x32_bf16 v[38:41], v[206:209], v[164:167], v[38:41]
	v_mfma_f32_16x16x32_bf16 v[34:37], v[206:209], v[172:175], v[34:37]
	v_mfma_f32_16x16x32_bf16 v[62:65], v[184:187], v[168:171], v[62:65]
	v_mfma_f32_16x16x32_bf16 v[58:61], v[184:187], v[176:179], v[58:61]
	v_mfma_f32_16x16x32_bf16 v[54:57], v[192:195], v[168:171], v[54:57]
	v_mfma_f32_16x16x32_bf16 v[50:53], v[192:195], v[176:179], v[50:53]
	v_mfma_f32_16x16x32_bf16 v[46:49], v[202:205], v[168:171], v[46:49]
	v_mfma_f32_16x16x32_bf16 v[42:45], v[202:205], v[176:179], v[42:45]
	v_mfma_f32_16x16x32_bf16 v[38:41], v[216:219], v[168:171], v[38:41]
	v_mfma_f32_16x16x32_bf16 v[34:37], v[216:219], v[176:179], v[34:37]
	v_mfma_f32_16x16x32_bf16 v[30:33], v[180:183], v[222:225], v[30:33]
	v_mfma_f32_16x16x32_bf16 v[26:29], v[180:183], v[232:235], v[26:29]
	v_mfma_f32_16x16x32_bf16 v[22:25], v[188:191], v[222:225], v[22:25]
	v_mfma_f32_16x16x32_bf16 v[18:21], v[188:191], v[232:235], v[18:21]
	v_mfma_f32_16x16x32_bf16 v[14:17], v[196:199], v[222:225], v[14:17]
	v_mfma_f32_16x16x32_bf16 v[10:13], v[196:199], v[232:235], v[10:13]
	v_mfma_f32_16x16x32_bf16 v[6:9], v[206:209], v[222:225], v[6:9]
	v_mfma_f32_16x16x32_bf16 v[2:5], v[206:209], v[232:235], v[2:5]
	v_mfma_f32_16x16x32_bf16 v[30:33], v[184:187], v[228:231], v[30:33]
	v_mfma_f32_16x16x32_bf16 v[26:29], v[184:187], v[236:239], v[26:29]
	v_mfma_f32_16x16x32_bf16 v[22:25], v[192:195], v[228:231], v[22:25]
	v_mfma_f32_16x16x32_bf16 v[18:21], v[192:195], v[236:239], v[18:21]
	v_mfma_f32_16x16x32_bf16 v[14:17], v[202:205], v[228:231], v[14:17]
	v_mfma_f32_16x16x32_bf16 v[10:13], v[202:205], v[236:239], v[10:13]
	v_mfma_f32_16x16x32_bf16 v[6:9], v[216:219], v[228:231], v[6:9]
	v_mfma_f32_16x16x32_bf16 v[2:5], v[216:219], v[236:239], v[2:5]
	s_barrier
	s_add_i32 s22, s22, 2
	s_add_u32 s12, s12, 0x100
	s_addc_u32 s13, s13, 0
	s_add_u32 s0, s0, 0x100
	s_addc_u32 s1, s1, 0
	s_cmp_lt_u32 s22, 12
	s_cbranch_scc1 .LBB0_133
	s_or_b32 s0, s40, 0x80
	s_ashr_i32 s1, s0, 31
	s_lshl_b64 s[0:1], s[0:1], 11
	s_add_u32 s0, s80, s0
	s_addc_u32 s1, s81, s1
	v_lshl_add_u64 v[130:131], s[0:1], 0, v[0:1]
	s_mov_b64 s[0:1], 0x780
	v_lshl_add_u64 v[152:153], v[130:131], 0, s[0:1]
	v_readfirstlane_b32 s0, v161
	s_mov_b32 m0, s0
	s_mov_b64 s[0:1], 0x20780
	v_lshl_add_u64 v[130:131], v[130:131], 0, s[0:1]
	v_readfirstlane_b32 s0, v162
	ds_read_b128 v[164:167], v157
	ds_read_b128 v[168:171], v157 offset:1024
	ds_read_b128 v[172:175], v157 offset:2048
	ds_read_b128 v[176:179], v157 offset:3072
	ds_read_b128 v[180:183], v146
	ds_read_b128 v[184:187], v146 offset:1024
	ds_read_b128 v[188:191], v145
	ds_read_b128 v[192:195], v145 offset:1024
	ds_read_b128 v[196:199], v144
	ds_read_b128 v[202:205], v144 offset:1024
	ds_read_b128 v[206:209], v143
	ds_read_b128 v[216:219], v143 offset:1024
	global_load_lds_dwordx4 v[152:153], off
	s_mov_b32 m0, s0
	s_nop 0
	global_load_lds_dwordx4 v[130:131], off
	s_waitcnt vmcnt(8)
	s_barrier
	s_waitcnt lgkmcnt(0)
	s_setprio 1
	s_waitcnt lgkmcnt(0)
	v_mfma_f32_16x16x32_bf16 v[126:129], v[180:183], v[164:167], v[126:129]
	v_mfma_f32_16x16x32_bf16 v[122:125], v[180:183], v[172:175], v[122:125]
	v_mfma_f32_16x16x32_bf16 v[110:113], v[196:199], v[164:167], v[110:113]
	v_mfma_f32_16x16x32_bf16 v[106:109], v[196:199], v[172:175], v[106:109]
	v_mfma_f32_16x16x32_bf16 v[126:129], v[184:187], v[168:171], v[126:129]
	v_mfma_f32_16x16x32_bf16 v[122:125], v[184:187], v[176:179], v[122:125]
	v_mfma_f32_16x16x32_bf16 v[118:121], v[188:191], v[164:167], v[118:121]
	v_mfma_f32_16x16x32_bf16 v[114:117], v[188:191], v[172:175], v[114:117]
	v_mfma_f32_16x16x32_bf16 v[110:113], v[202:205], v[168:171], v[110:113]
	v_mfma_f32_16x16x32_bf16 v[106:109], v[202:205], v[176:179], v[106:109]
	v_mfma_f32_16x16x32_bf16 v[102:105], v[206:209], v[164:167], v[102:105]
	v_mfma_f32_16x16x32_bf16 v[98:101], v[206:209], v[172:175], v[98:101]
	v_mfma_f32_16x16x32_bf16 v[222:225], v[192:195], v[168:171], v[118:121]
	v_mfma_f32_16x16x32_bf16 v[228:231], v[192:195], v[176:179], v[114:117]
	v_mfma_f32_16x16x32_bf16 v[232:235], v[216:219], v[168:171], v[102:105]
	v_mfma_f32_16x16x32_bf16 v[236:239], v[216:219], v[176:179], v[98:101]
	s_setprio 0
	s_barrier
; #define LDA(dst, b, h) for (int m = 0; m < 4; ++m) for (int k = 0; k < 2; ++k) \
;     dst[m][k] = *reinterpret_cast<const bf16x8*>((char*)SA(b, h) + lds_byte(wr * 64 + m * 16 + fr, k * 32 + fq * 8))
; #define LDB(dst, b, h) for (int n = 0; n < 2; ++n) for (int k = 0; k < 2; ++k) \
;     dst[n][k] = *reinterpret_cast<const bf16x8*>((char*)SB(b, h) + lds_byte(wc * 32 + n * 16 + fr, k * 32 + fq * 8))
; #define MMA(ai, bj, At_, Bt_) do { __builtin_amdgcn_s_setprio(1); \
;     for (int m = 0; m < 4; ++m) for (int n = 0; n < 2; ++n) for (int k = 0; k < 2; ++k) \
;       acc[ai][bj][m][n] = __builtin_amdgcn_mfma_f32_16x16x32_bf16(At_[m][k], Bt_[n][k], acc[ai][bj][m][n], 0, 0, 0); \
;     __builtin_amdgcn_s_setprio(0); } while (0)
; #define WAIT_V(n) asm volatile("s_waitcnt vmcnt(" #n ")" ::: "memory")
; #define WAIT_L(n) asm volatile("s_waitcnt lgkmcnt(" #n ")" ::: "memory")
; #define BAR __builtin_amdgcn_s_barrier()
; #define SCHED __builtin_amdgcn_sched_barrier(0)
; template <int EPI>
; __device__ __forceinline__ void gemm_tile(const GemmArgs& g, int brow, int bcol, int parity, bool first, bool nvalid, int nbrow, int nbcol) {
;     ...
;     BAR; WAIT_L(0); MMA(0, 0, At, B0); BAR;
;     LDB(B1, 0, 1); BAR; WAIT_L(0); MMA(0, 1, At, B1); BAR; SCHED;
;     LDA(At, 0, 1); WAIT_V(4); BAR; WAIT_L(0); MMA(1, 0, At, B0); MMA(1, 1, At, B1); BAR; }
;   { LDB(B0, 1, 0); LDA(At, 1, 0); WAIT_V(2); BAR; WAIT_L(0); MMA(0, 0, At, B0); BAR;
	s_nop 1
	ds_read_b128 v[98:101], v154
	ds_read_b128 v[102:105], v154 offset:1024
	ds_read_b128 v[114:117], v154 offset:2048
	ds_read_b128 v[118:121], v154 offset:3072
	s_barrier
	s_waitcnt lgkmcnt(0)
	s_setprio 1
	s_waitcnt lgkmcnt(0)
	v_mfma_f32_16x16x32_bf16 v[94:97], v[180:183], v[98:101], v[94:97]
	v_mfma_f32_16x16x32_bf16 v[90:93], v[180:183], v[114:117], v[90:93]
	v_mfma_f32_16x16x32_bf16 v[78:81], v[196:199], v[98:101], v[78:81]
	v_mfma_f32_16x16x32_bf16 v[74:77], v[196:199], v[114:117], v[74:77]
	v_mfma_f32_16x16x32_bf16 v[94:97], v[184:187], v[102:105], v[94:97]
	v_mfma_f32_16x16x32_bf16 v[90:93], v[184:187], v[118:121], v[90:93]
	v_mfma_f32_16x16x32_bf16 v[86:89], v[188:191], v[98:101], v[86:89]
	v_mfma_f32_16x16x32_bf16 v[82:85], v[188:191], v[114:117], v[82:85]
	v_mfma_f32_16x16x32_bf16 v[78:81], v[202:205], v[102:105], v[78:81]
	v_mfma_f32_16x16x32_bf16 v[74:77], v[202:205], v[118:121], v[74:77]
	v_mfma_f32_16x16x32_bf16 v[70:73], v[206:209], v[98:101], v[70:73]
	v_mfma_f32_16x16x32_bf16 v[66:69], v[206:209], v[114:117], v[66:69]
	v_mfma_f32_16x16x32_bf16 v[152:155], v[192:195], v[102:105], v[86:89]
	v_mfma_f32_16x16x32_bf16 v[180:183], v[192:195], v[118:121], v[82:85]
	v_mfma_f32_16x16x32_bf16 v[184:187], v[216:219], v[102:105], v[70:73]
	v_mfma_f32_16x16x32_bf16 v[188:191], v[216:219], v[118:121], v[66:69]
	s_setprio 0
	s_barrier
	s_nop 1
	ds_read_b128 v[66:69], v146 offset:16384
	ds_read_b128 v[70:73], v146 offset:17408
	ds_read_b128 v[82:85], v145 offset:16384
	ds_read_b128 v[86:89], v145 offset:17408
	ds_read_b128 v[192:195], v144 offset:16384
	ds_read_b128 v[196:199], v144 offset:17408
	ds_read_b128 v[202:205], v143 offset:16384
	ds_read_b128 v[206:209], v143 offset:17408
	s_waitcnt vmcnt(4)
	s_barrier
	s_waitcnt lgkmcnt(0)
	s_setprio 1
	s_waitcnt lgkmcnt(0)
	v_mfma_f32_16x16x32_bf16 v[62:65], v[66:69], v[164:167], v[62:65]
	v_mfma_f32_16x16x32_bf16 v[58:61], v[66:69], v[172:175], v[58:61]
	v_mfma_f32_16x16x32_bf16 v[46:49], v[192:195], v[164:167], v[46:49]
	v_mfma_f32_16x16x32_bf16 v[42:45], v[192:195], v[172:175], v[42:45]
	v_mfma_f32_16x16x32_bf16 v[62:65], v[70:73], v[168:171], v[62:65]
	v_mfma_f32_16x16x32_bf16 v[58:61], v[70:73], v[176:179], v[58:61]
	v_mfma_f32_16x16x32_bf16 v[54:57], v[82:85], v[164:167], v[54:57]
	v_mfma_f32_16x16x32_bf16 v[50:53], v[82:85], v[172:175], v[50:53]
	v_mfma_f32_16x16x32_bf16 v[46:49], v[196:199], v[168:171], v[46:49]
	v_mfma_f32_16x16x32_bf16 v[42:45], v[196:199], v[176:179], v[42:45]
	v_mfma_f32_16x16x32_bf16 v[38:41], v[202:205], v[164:167], v[38:41]
	v_mfma_f32_16x16x32_bf16 v[34:37], v[202:205], v[172:175], v[34:37]
	v_mfma_f32_16x16x32_bf16 v[216:219], v[86:89], v[168:171], v[54:57]
	v_mfma_f32_16x16x32_bf16 v[240:243], v[86:89], v[176:179], v[50:53]
	v_mfma_f32_16x16x32_bf16 v[162:165], v[206:209], v[168:171], v[38:41]
	v_mfma_f32_16x16x32_bf16 v[166:169], v[206:209], v[176:179], v[34:37]
	s_setprio 0
	s_setprio 1
	v_mfma_f32_16x16x32_bf16 v[30:33], v[66:69], v[98:101], v[30:33]
	v_mfma_f32_16x16x32_bf16 v[26:29], v[66:69], v[114:117], v[26:29]
	v_mfma_f32_16x16x32_bf16 v[14:17], v[192:195], v[98:101], v[14:17]
	v_mfma_f32_16x16x32_bf16 v[10:13], v[192:195], v[114:117], v[10:13]
	v_mfma_f32_16x16x32_bf16 v[30:33], v[70:73], v[102:105], v[30:33]
	v_mfma_f32_16x16x32_bf16 v[26:29], v[70:73], v[118:121], v[26:29]
	v_mfma_f32_16x16x32_bf16 v[22:25], v[82:85], v[98:101], v[22:25]
	v_mfma_f32_16x16x32_bf16 v[18:21], v[82:85], v[114:117], v[18:21]
	v_mfma_f32_16x16x32_bf16 v[14:17], v[196:199], v[102:105], v[14:17]
	v_mfma_f32_16x16x32_bf16 v[10:13], v[196:199], v[118:121], v[10:13]
	v_mfma_f32_16x16x32_bf16 v[6:9], v[202:205], v[98:101], v[6:9]
	v_mfma_f32_16x16x32_bf16 v[2:5], v[202:205], v[114:117], v[2:5]
	v_mfma_f32_16x16x32_bf16 v[170:173], v[86:89], v[102:105], v[22:25]
	v_mfma_f32_16x16x32_bf16 v[174:177], v[86:89], v[118:121], v[18:21]
	v_mfma_f32_16x16x32_bf16 v[192:195], v[206:209], v[102:105], v[6:9]
	v_mfma_f32_16x16x32_bf16 v[196:199], v[206:209], v[118:121], v[2:5]
	s_setprio 0
	s_barrier
	s_nop 1
	ds_read_b128 v[2:5], v148
	ds_read_b128 v[6:9], v148 offset:1024
	ds_read_b128 v[202:205], v148 offset:2048
	ds_read_b128 v[206:209], v148 offset:3072
	ds_read_b128 v[18:21], v146 offset:32768
	ds_read_b128 v[22:25], v146 offset:33792
	ds_read_b128 v[34:37], v145 offset:32768
	ds_read_b128 v[38:41], v145 offset:33792
	ds_read_b128 v[50:53], v144 offset:32768
	ds_read_b128 v[54:57], v144 offset:33792
	ds_read_b128 v[244:247], v143 offset:32768
	ds_read_b128 v[248:251], v143 offset:33792
	s_waitcnt vmcnt(2)
	s_barrier
; #define LDA(dst, b, h) for (int m = 0; m < 4; ++m) for (int k = 0; k < 2; ++k) \
;     dst[m][k] = *reinterpret_cast<const bf16x8*>((char*)SA(b, h) + lds_byte(wr * 64 + m * 16 + fr, k * 32 + fq * 8))
; #define LDB(dst, b, h) for (int n = 0; n < 2; ++n) for (int k = 0; k < 2; ++k) \
;     dst[n][k] = *reinterpret_cast<const bf16x8*>((char*)SB(b, h) + lds_byte(wc * 32 + n * 16 + fr, k * 32 + fq * 8))
; #define MMA(ai, bj, At_, Bt_) do { __builtin_amdgcn_s_setprio(1); \
;     for (int m = 0; m < 4; ++m) for (int n = 0; n < 2; ++n) for (int k = 0; k < 2; ++k) \
;       acc[ai][bj][m][n] = __builtin_amdgcn_mfma_f32_16x16x32_bf16(At_[m][k], Bt_[n][k], acc[ai][bj][m][n], 0, 0, 0); \
;     __builtin_amdgcn_s_setprio(0); } while (0)
; #define WAIT_V(n) asm volatile("s_waitcnt vmcnt(" #n ")" ::: "memory")
; #define WAIT_L(n) asm volatile("s_waitcnt lgkmcnt(" #n ")" ::: "memory")
; #define BAR __builtin_amdgcn_s_barrier()
; #define SCHED __builtin_amdgcn_sched_barrier(0)
; template <int EPI>
; __device__ __forceinline__ void gemm_tile(const GemmArgs& g, int brow, int bcol, int parity, bool first, bool nvalid, int nbrow, int nbcol) {
;     ...
;   { LDB(B0, 1, 0); LDA(At, 1, 0); WAIT_V(2); BAR; WAIT_L(0); MMA(0, 0, At, B0); BAR;
;     LDB(B1, 1, 1); WAIT_V(0); BAR; WAIT_L(0); MMA(0, 1, At, B1); BAR; SCHED;
;     LDA(At, 1, 1); BAR; WAIT_L(0); MMA(1, 0, At, B0); MMA(1, 1, At, B1); BAR; }
;   if (wr == 0) BAR;
	s_waitcnt lgkmcnt(0)
	s_setprio 1
	s_waitcnt lgkmcnt(0)
	v_mfma_f32_16x16x32_bf16 v[66:69], v[18:21], v[2:5], v[126:129]
	v_mfma_f32_16x16x32_bf16 v[114:117], v[22:25], v[6:9], v[66:69]
	v_mfma_f32_16x16x32_bf16 v[66:69], v[18:21], v[202:205], v[122:125]
	v_mfma_f32_16x16x32_bf16 v[118:121], v[22:25], v[206:209], v[66:69]
	v_mfma_f32_16x16x32_bf16 v[66:69], v[34:37], v[2:5], v[222:225]
	v_mfma_f32_16x16x32_bf16 v[98:101], v[38:41], v[6:9], v[66:69]
	v_mfma_f32_16x16x32_bf16 v[66:69], v[34:37], v[202:205], v[228:231]
	v_mfma_f32_16x16x32_bf16 v[102:105], v[38:41], v[206:209], v[66:69]
	v_mfma_f32_16x16x32_bf16 v[66:69], v[50:53], v[2:5], v[110:113]
	v_mfma_f32_16x16x32_bf16 v[82:85], v[54:57], v[6:9], v[66:69]
	v_mfma_f32_16x16x32_bf16 v[66:69], v[50:53], v[202:205], v[106:109]
	v_mfma_f32_16x16x32_bf16 v[86:89], v[54:57], v[206:209], v[66:69]
	v_mfma_f32_16x16x32_bf16 v[66:69], v[244:247], v[2:5], v[232:235]
	v_mfma_f32_16x16x32_bf16 v[70:73], v[244:247], v[202:205], v[236:239]
	v_mfma_f32_16x16x32_bf16 v[66:69], v[248:251], v[6:9], v[66:69]
	v_mfma_f32_16x16x32_bf16 v[70:73], v[248:251], v[206:209], v[70:73]
	s_setprio 0
	s_barrier
	ds_read_b128 v[222:225], v147
	ds_read_b128 v[228:231], v147 offset:1024
	ds_read_b128 v[232:235], v147 offset:2048
	ds_read_b128 v[236:239], v147 offset:3072
	s_waitcnt vmcnt(0)
	s_barrier
	s_waitcnt lgkmcnt(0)
	s_setprio 1
	s_waitcnt lgkmcnt(0)
	v_mfma_f32_16x16x32_bf16 v[94:97], v[18:21], v[222:225], v[94:97]
	v_mfma_f32_16x16x32_bf16 v[18:21], v[18:21], v[232:235], v[90:93]
	v_mfma_f32_16x16x32_bf16 v[122:125], v[22:25], v[236:239], v[18:21]
	v_mfma_f32_16x16x32_bf16 v[18:21], v[34:37], v[222:225], v[152:155]
	v_mfma_f32_16x16x32_bf16 v[110:113], v[38:41], v[228:231], v[18:21]
	v_mfma_f32_16x16x32_bf16 v[18:21], v[34:37], v[232:235], v[180:183]
	v_mfma_f32_16x16x32_bf16 v[106:109], v[38:41], v[236:239], v[18:21]
	v_mfma_f32_16x16x32_bf16 v[18:21], v[50:53], v[222:225], v[78:81]
	v_mfma_f32_16x16x32_bf16 v[126:129], v[22:25], v[228:231], v[94:97]
	v_mfma_f32_16x16x32_bf16 v[94:97], v[54:57], v[228:231], v[18:21]
	v_mfma_f32_16x16x32_bf16 v[18:21], v[50:53], v[232:235], v[74:77]
	v_mfma_f32_16x16x32_bf16 v[90:93], v[54:57], v[236:239], v[18:21]
	v_mfma_f32_16x16x32_bf16 v[18:21], v[244:247], v[222:225], v[184:187]
	v_mfma_f32_16x16x32_bf16 v[78:81], v[248:251], v[228:231], v[18:21]
	v_mfma_f32_16x16x32_bf16 v[18:21], v[244:247], v[232:235], v[188:191]
	v_mfma_f32_16x16x32_bf16 v[74:77], v[248:251], v[236:239], v[18:21]
	s_setprio 0
	s_barrier
	ds_read_b128 v[152:155], v146 offset:49152
	ds_read_b128 v[146:149], v146 offset:50176
	ds_read_b128 v[178:181], v145 offset:49152
	ds_read_b128 v[182:185], v145 offset:50176
	ds_read_b128 v[186:189], v144 offset:49152
	ds_read_b128 v[244:247], v144 offset:50176
	ds_read_b128 v[248:251], v143 offset:49152
	ds_read_b128 v[210:213], v143 offset:50176
	s_barrier
	s_waitcnt lgkmcnt(0)
	s_setprio 1
	s_waitcnt lgkmcnt(0)
	v_mfma_f32_16x16x32_bf16 v[18:21], v[152:155], v[2:5], v[62:65]
	v_mfma_f32_16x16x32_bf16 v[50:53], v[146:149], v[6:9], v[18:21]
	v_mfma_f32_16x16x32_bf16 v[18:21], v[152:155], v[202:205], v[58:61]
	v_mfma_f32_16x16x32_bf16 v[54:57], v[146:149], v[206:209], v[18:21]
	v_mfma_f32_16x16x32_bf16 v[18:21], v[178:181], v[2:5], v[216:219]
	v_mfma_f32_16x16x32_bf16 v[34:37], v[182:185], v[6:9], v[18:21]
	v_mfma_f32_16x16x32_bf16 v[18:21], v[178:181], v[202:205], v[240:243]
	v_mfma_f32_16x16x32_bf16 v[38:41], v[182:185], v[206:209], v[18:21]
	v_mfma_f32_16x16x32_bf16 v[18:21], v[186:189], v[2:5], v[46:49]
	v_mfma_f32_16x16x32_bf16 v[2:5], v[248:251], v[2:5], v[162:165]
	v_mfma_f32_16x16x32_bf16 v[18:21], v[244:247], v[6:9], v[18:21]
	v_mfma_f32_16x16x32_bf16 v[22:25], v[186:189], v[202:205], v[42:45]
	v_mfma_f32_16x16x32_bf16 v[2:5], v[210:213], v[6:9], v[2:5]
	v_mfma_f32_16x16x32_bf16 v[6:9], v[248:251], v[202:205], v[166:169]
	v_mfma_f32_16x16x32_bf16 v[22:25], v[244:247], v[206:209], v[22:25]
	v_mfma_f32_16x16x32_bf16 v[6:9], v[210:213], v[206:209], v[6:9]
	s_setprio 0
	s_setprio 1
	v_mfma_f32_16x16x32_bf16 v[26:29], v[152:155], v[232:235], v[26:29]
	v_mfma_f32_16x16x32_bf16 v[58:61], v[146:149], v[236:239], v[26:29]
	v_mfma_f32_16x16x32_bf16 v[26:29], v[178:181], v[222:225], v[170:173]
	v_mfma_f32_16x16x32_bf16 v[46:49], v[182:185], v[228:231], v[26:29]
	v_mfma_f32_16x16x32_bf16 v[26:29], v[178:181], v[232:235], v[174:177]
	v_mfma_f32_16x16x32_bf16 v[10:13], v[186:189], v[232:235], v[10:13]
	v_mfma_f32_16x16x32_bf16 v[30:33], v[152:155], v[222:225], v[30:33]
	v_mfma_f32_16x16x32_bf16 v[42:45], v[182:185], v[236:239], v[26:29]
	v_mfma_f32_16x16x32_bf16 v[14:17], v[186:189], v[222:225], v[14:17]
	v_mfma_f32_16x16x32_bf16 v[26:29], v[244:247], v[236:239], v[10:13]
	v_mfma_f32_16x16x32_bf16 v[10:13], v[248:251], v[222:225], v[192:195]
	v_mfma_f32_16x16x32_bf16 v[62:65], v[146:149], v[228:231], v[30:33]
	v_mfma_f32_16x16x32_bf16 v[30:33], v[244:247], v[228:231], v[14:17]
	v_mfma_f32_16x16x32_bf16 v[14:17], v[210:213], v[228:231], v[10:13]
	v_mfma_f32_16x16x32_bf16 v[10:13], v[248:251], v[232:235], v[196:199]
	v_mfma_f32_16x16x32_bf16 v[10:13], v[210:213], v[236:239], v[10:13]
	s_setprio 0
	s_movk_i32 s0, 0x100
	v_cmp_gt_u32_e32 vcc, s0, v138
	s_barrier
	s_and_saveexec_b64 s[0:1], vcc
	s_cbranch_execz .LBB0_136
	s_barrier

; #define STAGE_B(P, br, kt) do { const char* _gb = (const char*)(Bt + ((long)(br) * K + (long)(kt) * BK)); \
;     __builtin_amdgcn_global_load_lds((const unsigned*)(_gb + bofl0), (unsigned*)((char*)(P) + gtid_ * 16), 16, 0, 0); \
;     __builtin_amdgcn_global_load_lds((const unsigned*)(_gb + (long)K * 128 + bofl0), (unsigned*)((char*)(P) + gtid_ * 16 + 8192), 16, 0, 0); } while (0)
; #define LDA(dst, b, h) for (int m = 0; m < 4; ++m) for (int k = 0; k < 2; ++k) \
;     dst[m][k] = *reinterpret_cast<const bf16x8*>((char*)SA(b, h) + lds_byte(wr * 64 + m * 16 + fr, k * 32 + fq * 8))
; #define LDB(dst, b, h) for (int n = 0; n < 2; ++n) for (int k = 0; k < 2; ++k) \
;     dst[n][k] = *reinterpret_cast<const bf16x8*>((char*)SB(b, h) + lds_byte(wc * 32 + n * 16 + fr, k * 32 + fq * 8))
; #define MMA(ai, bj, At_, Bt_) do { __builtin_amdgcn_s_setprio(1); \
;     for (int m = 0; m < 4; ++m) for (int n = 0; n < 2; ++n) for (int k = 0; k < 2; ++k) \
;       acc[ai][bj][m][n] = __builtin_amdgcn_mfma_f32_16x16x32_bf16(At_[m][k], Bt_[n][k], acc[ai][bj][m][n], 0, 0, 0); \
;     __builtin_amdgcn_s_setprio(0); } while (0)
; #define WAIT_V(n) asm volatile("s_waitcnt vmcnt(" #n ")" ::: "memory")
; #define WAIT_L(n) asm volatile("s_waitcnt lgkmcnt(" #n ")" ::: "memory")
; #define BAR __builtin_amdgcn_s_barrier()
; #define SCHED __builtin_amdgcn_sched_barrier(0)
; template <int EPI>
; __device__ __forceinline__ void gemm_tile(const GemmArgs& g, int brow, int bcol, int parity, bool first, bool nvalid, int nbrow, int nbcol) {
;     ...
;     LDB(B0, 0, 0); SCHED; LDA(At, 0, 0); STAGE_A(SA(1, 1), brow + HALF, t + 1);
;     WAIT_L(8); BAR; WAIT_L(0); MMA(0, 0, At, B0); BAR; SCHED;
;     LDB(B1, 0, 1); STAGE_B(SB(0, 0), bcol, t + 2);
;     BAR; WAIT_L(0); MMA(0, 1, At, B1); BAR; SCHED;
;     LDA(At, 0, 1); STAGE_A(SA(0, 0), brow, t + 2);
;     BAR; WAIT_L(0); MMA(1, 0, At, B0); BAR; SCHED;
;     STAGE_B(SB(0, 1), bcol + HALF, t + 2);
;     WAIT_V(6); BAR; MMA(1, 1, At, B1); BAR; SCHED;
.LBB0_166:
	ds_read_b128 v[164:167], v157
	ds_read_b128 v[168:171], v157 offset:1024
	ds_read_b128 v[172:175], v157 offset:2048
	ds_read_b128 v[176:179], v157 offset:3072
	ds_read_b128 v[180:183], v147
	ds_read_b128 v[184:187], v147 offset:1024
	ds_read_b128 v[188:191], v146
	ds_read_b128 v[192:195], v146 offset:1024
	ds_read_b128 v[196:199], v145
	ds_read_b128 v[202:205], v145 offset:1024
	ds_read_b128 v[206:209], v144
	ds_read_b128 v[216:219], v144 offset:1024
	s_waitcnt lgkmcnt(6)
	ds_read_b128 v[222:225], v154
	ds_read_b128 v[228:231], v154 offset:1024
	ds_read_b128 v[232:235], v154 offset:2048
	ds_read_b128 v[236:239], v154 offset:3072
	v_add_u32_e32 v161, 0xc000, v137
	v_lshl_add_u64 v[210:211], s[0:1], 0, v[130:131]
	v_readfirstlane_b32 s2, v161
	v_add_u32_e32 v162, 0xe000, v137
	v_lshl_add_u64 v[158:159], v[210:211], 0, s[26:27]
	s_mov_b32 m0, s2
	v_readfirstlane_b32 s2, v162
	global_load_lds_dwordx4 v[158:159], off
	v_lshl_add_u64 v[158:159], v[210:211], 0, s[42:43]
	s_mov_b32 m0, s2
	s_nop 0
	global_load_lds_dwordx4 v[158:159], off
	s_waitcnt vmcnt(8)
	s_barrier
	s_waitcnt lgkmcnt(0)
	v_mfma_f32_16x16x32_bf16 v[126:129], v[164:167], v[180:183], v[126:129]
	v_mfma_f32_16x16x32_bf16 v[122:125], v[172:175], v[180:183], v[122:125]
	v_mfma_f32_16x16x32_bf16 v[118:121], v[164:167], v[188:191], v[118:121]
	v_mfma_f32_16x16x32_bf16 v[114:117], v[172:175], v[188:191], v[114:117]
	v_mfma_f32_16x16x32_bf16 v[110:113], v[164:167], v[196:199], v[110:113]
	v_mfma_f32_16x16x32_bf16 v[106:109], v[172:175], v[196:199], v[106:109]
	v_mfma_f32_16x16x32_bf16 v[102:105], v[164:167], v[206:209], v[102:105]
	v_mfma_f32_16x16x32_bf16 v[98:101], v[172:175], v[206:209], v[98:101]
	v_mfma_f32_16x16x32_bf16 v[126:129], v[168:171], v[184:187], v[126:129]
	v_mfma_f32_16x16x32_bf16 v[122:125], v[176:179], v[184:187], v[122:125]
	v_mfma_f32_16x16x32_bf16 v[118:121], v[168:171], v[192:195], v[118:121]
	v_mfma_f32_16x16x32_bf16 v[114:117], v[176:179], v[192:195], v[114:117]
	v_mfma_f32_16x16x32_bf16 v[110:113], v[168:171], v[202:205], v[110:113]
	v_mfma_f32_16x16x32_bf16 v[106:109], v[176:179], v[202:205], v[106:109]
	v_mfma_f32_16x16x32_bf16 v[102:105], v[168:171], v[216:219], v[102:105]
	v_mfma_f32_16x16x32_bf16 v[98:101], v[176:179], v[216:219], v[98:101]
	v_mfma_f32_16x16x32_bf16 v[94:97], v[222:225], v[180:183], v[94:97]
	v_mfma_f32_16x16x32_bf16 v[90:93], v[232:235], v[180:183], v[90:93]
	v_mfma_f32_16x16x32_bf16 v[86:89], v[222:225], v[188:191], v[86:89]
	v_mfma_f32_16x16x32_bf16 v[82:85], v[232:235], v[188:191], v[82:85]
	v_mfma_f32_16x16x32_bf16 v[78:81], v[222:225], v[196:199], v[78:81]
	v_mfma_f32_16x16x32_bf16 v[74:77], v[232:235], v[196:199], v[74:77]
	v_mfma_f32_16x16x32_bf16 v[70:73], v[222:225], v[206:209], v[70:73]
	v_mfma_f32_16x16x32_bf16 v[66:69], v[232:235], v[206:209], v[66:69]
	v_mfma_f32_16x16x32_bf16 v[94:97], v[228:231], v[184:187], v[94:97]
	v_mfma_f32_16x16x32_bf16 v[90:93], v[236:239], v[184:187], v[90:93]
	v_mfma_f32_16x16x32_bf16 v[86:89], v[228:231], v[192:195], v[86:89]
	v_mfma_f32_16x16x32_bf16 v[82:85], v[236:239], v[192:195], v[82:85]
	v_mfma_f32_16x16x32_bf16 v[78:81], v[228:231], v[202:205], v[78:81]
	v_mfma_f32_16x16x32_bf16 v[74:77], v[236:239], v[202:205], v[74:77]
	v_mfma_f32_16x16x32_bf16 v[70:73], v[228:231], v[216:219], v[70:73]
	v_mfma_f32_16x16x32_bf16 v[66:69], v[236:239], v[216:219], v[66:69]
	s_barrier
	ds_read_b128 v[180:183], v147 offset:16384
	ds_read_b128 v[184:187], v147 offset:17408
	ds_read_b128 v[188:191], v146 offset:16384
	ds_read_b128 v[192:195], v146 offset:17408
	ds_read_b128 v[196:199], v145 offset:16384
	ds_read_b128 v[202:205], v145 offset:17408
	ds_read_b128 v[206:209], v144 offset:16384
	ds_read_b128 v[216:219], v144 offset:17408
	v_add_u32_e32 v158, s15, v142
	v_lshl_add_u64 v[212:213], s[12:13], 0, v[130:131]
	v_readfirstlane_b32 s2, v158
	v_add_u32_e32 v159, 0x2000, v158
	v_lshl_add_u64 v[240:241], v[212:213], 0, s[78:79]
	s_mov_b32 m0, s2
	v_readfirstlane_b32 s2, v159
	global_load_lds_dwordx4 v[240:241], off
	v_lshl_add_u64 v[240:241], v[212:213], 0, s[66:67]
	s_mov_b32 m0, s2
	s_nop 0
	global_load_lds_dwordx4 v[240:241], off
	v_readfirstlane_b32 s2, v137
	v_lshl_add_u64 v[240:241], v[210:211], 0, s[44:45]
	s_mov_b32 m0, s2
	v_readfirstlane_b32 s2, v136
	global_load_lds_dwordx4 v[240:241], off
	v_lshl_add_u64 v[240:241], v[210:211], 0, s[46:47]
	s_mov_b32 m0, s2
	s_nop 0
	global_load_lds_dwordx4 v[240:241], off
	v_readfirstlane_b32 s2, v135
	v_add_u32_e32 v160, 0x2000, v135
	v_lshl_add_u64 v[244:245], v[212:213], 0, s[76:77]
	s_mov_b32 m0, s2
	v_readfirstlane_b32 s2, v160
	global_load_lds_dwordx4 v[244:245], off
	v_lshl_add_u64 v[244:245], v[212:213], 0, s[96:97]
	s_mov_b32 m0, s2
	s_nop 0
	global_load_lds_dwordx4 v[244:245], off
	s_waitcnt vmcnt(8)
	s_barrier
; #define STAGE_B(P, br, kt) do { const char* _gb = (const char*)(Bt + ((long)(br) * K + (long)(kt) * BK)); \
;     __builtin_amdgcn_global_load_lds((const unsigned*)(_gb + bofl0), (unsigned*)((char*)(P) + gtid_ * 16), 16, 0, 0); \
;     __builtin_amdgcn_global_load_lds((const unsigned*)(_gb + (long)K * 128 + bofl0), (unsigned*)((char*)(P) + gtid_ * 16 + 8192), 16, 0, 0); } while (0)
; #define LDA(dst, b, h) for (int m = 0; m < 4; ++m) for (int k = 0; k < 2; ++k) \
;     dst[m][k] = *reinterpret_cast<const bf16x8*>((char*)SA(b, h) + lds_byte(wr * 64 + m * 16 + fr, k * 32 + fq * 8))
; #define LDB(dst, b, h) for (int n = 0; n < 2; ++n) for (int k = 0; k < 2; ++k) \
;     dst[n][k] = *reinterpret_cast<const bf16x8*>((char*)SB(b, h) + lds_byte(wc * 32 + n * 16 + fr, k * 32 + fq * 8))
; #define MMA(ai, bj, At_, Bt_) do { __builtin_amdgcn_s_setprio(1); \
;     for (int m = 0; m < 4; ++m) for (int n = 0; n < 2; ++n) for (int k = 0; k < 2; ++k) \
;       acc[ai][bj][m][n] = __builtin_amdgcn_mfma_f32_16x16x32_bf16(At_[m][k], Bt_[n][k], acc[ai][bj][m][n], 0, 0, 0); \
;     __builtin_amdgcn_s_setprio(0); } while (0)
; #define WAIT_V(n) asm volatile("s_waitcnt vmcnt(" #n ")" ::: "memory")
; #define WAIT_L(n) asm volatile("s_waitcnt lgkmcnt(" #n ")" ::: "memory")
; #define BAR __builtin_amdgcn_s_barrier()
; #define SCHED __builtin_amdgcn_sched_barrier(0)
; template <int EPI>
; __device__ __forceinline__ void gemm_tile(const GemmArgs& g, int brow, int bcol, int parity, bool first, bool nvalid, int nbrow, int nbcol) {
;     ...
;     WAIT_V(6); BAR; MMA(1, 1, At, B1); BAR; SCHED;
;     LDB(B0, 1, 0); SCHED; LDA(At, 1, 0); STAGE_A(SA(0, 1), brow + HALF, t + 2);
;     WAIT_L(8); BAR; WAIT_L(0); MMA(0, 0, At, B0); BAR; SCHED;
;     LDB(B1, 1, 1); STAGE_B(SB(1, 0), bcol, t + 3);
;     BAR; WAIT_L(0); MMA(0, 1, At, B1); BAR; SCHED;
	s_waitcnt lgkmcnt(0)
	v_mfma_f32_16x16x32_bf16 v[62:65], v[164:167], v[180:183], v[62:65]
	v_mfma_f32_16x16x32_bf16 v[58:61], v[172:175], v[180:183], v[58:61]
	v_mfma_f32_16x16x32_bf16 v[54:57], v[164:167], v[188:191], v[54:57]
	v_mfma_f32_16x16x32_bf16 v[50:53], v[172:175], v[188:191], v[50:53]
	v_mfma_f32_16x16x32_bf16 v[46:49], v[164:167], v[196:199], v[46:49]
	v_mfma_f32_16x16x32_bf16 v[42:45], v[172:175], v[196:199], v[42:45]
	v_mfma_f32_16x16x32_bf16 v[38:41], v[164:167], v[206:209], v[38:41]
	v_mfma_f32_16x16x32_bf16 v[34:37], v[172:175], v[206:209], v[34:37]
	v_mfma_f32_16x16x32_bf16 v[62:65], v[168:171], v[184:187], v[62:65]
	v_mfma_f32_16x16x32_bf16 v[58:61], v[176:179], v[184:187], v[58:61]
	v_mfma_f32_16x16x32_bf16 v[54:57], v[168:171], v[192:195], v[54:57]
	v_mfma_f32_16x16x32_bf16 v[50:53], v[176:179], v[192:195], v[50:53]
	v_mfma_f32_16x16x32_bf16 v[46:49], v[168:171], v[202:205], v[46:49]
	v_mfma_f32_16x16x32_bf16 v[42:45], v[176:179], v[202:205], v[42:45]
	v_mfma_f32_16x16x32_bf16 v[38:41], v[168:171], v[216:219], v[38:41]
	v_mfma_f32_16x16x32_bf16 v[34:37], v[176:179], v[216:219], v[34:37]
	v_mfma_f32_16x16x32_bf16 v[30:33], v[222:225], v[180:183], v[30:33]
	v_mfma_f32_16x16x32_bf16 v[26:29], v[232:235], v[180:183], v[26:29]
	v_mfma_f32_16x16x32_bf16 v[22:25], v[222:225], v[188:191], v[22:25]
	v_mfma_f32_16x16x32_bf16 v[18:21], v[232:235], v[188:191], v[18:21]
	v_mfma_f32_16x16x32_bf16 v[14:17], v[222:225], v[196:199], v[14:17]
	v_mfma_f32_16x16x32_bf16 v[10:13], v[232:235], v[196:199], v[10:13]
	v_mfma_f32_16x16x32_bf16 v[6:9], v[222:225], v[206:209], v[6:9]
	v_mfma_f32_16x16x32_bf16 v[2:5], v[232:235], v[206:209], v[2:5]
	v_mfma_f32_16x16x32_bf16 v[30:33], v[228:231], v[184:187], v[30:33]
	v_mfma_f32_16x16x32_bf16 v[26:29], v[236:239], v[184:187], v[26:29]
	v_mfma_f32_16x16x32_bf16 v[22:25], v[228:231], v[192:195], v[22:25]
	v_mfma_f32_16x16x32_bf16 v[18:21], v[236:239], v[192:195], v[18:21]
	v_mfma_f32_16x16x32_bf16 v[14:17], v[228:231], v[202:205], v[14:17]
	v_mfma_f32_16x16x32_bf16 v[10:13], v[236:239], v[202:205], v[10:13]
	v_mfma_f32_16x16x32_bf16 v[6:9], v[228:231], v[216:219], v[6:9]
	v_mfma_f32_16x16x32_bf16 v[2:5], v[236:239], v[216:219], v[2:5]
	s_barrier
	ds_read_b128 v[164:167], v149
	ds_read_b128 v[168:171], v149 offset:1024
	ds_read_b128 v[172:175], v149 offset:2048
	ds_read_b128 v[176:179], v149 offset:3072
	ds_read_b128 v[180:183], v147 offset:32768
	ds_read_b128 v[184:187], v147 offset:33792
	ds_read_b128 v[188:191], v146 offset:32768
	ds_read_b128 v[192:195], v146 offset:33792
	ds_read_b128 v[196:199], v145 offset:32768
	ds_read_b128 v[202:205], v145 offset:33792
	ds_read_b128 v[206:209], v144 offset:32768
	ds_read_b128 v[216:219], v144 offset:33792
	s_waitcnt lgkmcnt(6)
	ds_read_b128 v[222:225], v148
	ds_read_b128 v[228:231], v148 offset:1024
	ds_read_b128 v[232:235], v148 offset:2048
	ds_read_b128 v[236:239], v148 offset:3072
	v_readfirstlane_b32 s2, v134
	v_lshl_add_u64 v[246:247], v[210:211], 0, s[48:49]
	s_mov_b32 m0, s2
	v_readfirstlane_b32 s2, v133
	global_load_lds_dwordx4 v[246:247], off
	v_lshl_add_u64 v[246:247], v[210:211], 0, s[50:51]
	s_mov_b32 m0, s2
	s_nop 0
	global_load_lds_dwordx4 v[246:247], off
	s_waitcnt vmcnt(8)
	s_barrier
	s_waitcnt lgkmcnt(0)
	v_mfma_f32_16x16x32_bf16 v[126:129], v[164:167], v[180:183], v[126:129]
	v_mfma_f32_16x16x32_bf16 v[122:125], v[172:175], v[180:183], v[122:125]
	v_mfma_f32_16x16x32_bf16 v[118:121], v[164:167], v[188:191], v[118:121]
	v_mfma_f32_16x16x32_bf16 v[114:117], v[172:175], v[188:191], v[114:117]
	v_mfma_f32_16x16x32_bf16 v[110:113], v[164:167], v[196:199], v[110:113]
	v_mfma_f32_16x16x32_bf16 v[106:109], v[172:175], v[196:199], v[106:109]
	v_mfma_f32_16x16x32_bf16 v[102:105], v[164:167], v[206:209], v[102:105]
	v_mfma_f32_16x16x32_bf16 v[98:101], v[172:175], v[206:209], v[98:101]
	v_mfma_f32_16x16x32_bf16 v[126:129], v[168:171], v[184:187], v[126:129]
	v_mfma_f32_16x16x32_bf16 v[122:125], v[176:179], v[184:187], v[122:125]
	v_mfma_f32_16x16x32_bf16 v[118:121], v[168:171], v[192:195], v[118:121]
	v_mfma_f32_16x16x32_bf16 v[114:117], v[176:179], v[192:195], v[114:117]
	v_mfma_f32_16x16x32_bf16 v[110:113], v[168:171], v[202:205], v[110:113]
	v_mfma_f32_16x16x32_bf16 v[106:109], v[176:179], v[202:205], v[106:109]
	v_mfma_f32_16x16x32_bf16 v[102:105], v[168:171], v[216:219], v[102:105]
	v_mfma_f32_16x16x32_bf16 v[98:101], v[176:179], v[216:219], v[98:101]
	v_mfma_f32_16x16x32_bf16 v[94:97], v[222:225], v[180:183], v[94:97]
	v_mfma_f32_16x16x32_bf16 v[90:93], v[232:235], v[180:183], v[90:93]
	v_mfma_f32_16x16x32_bf16 v[86:89], v[222:225], v[188:191], v[86:89]
	v_mfma_f32_16x16x32_bf16 v[82:85], v[232:235], v[188:191], v[82:85]
	v_mfma_f32_16x16x32_bf16 v[78:81], v[222:225], v[196:199], v[78:81]
	v_mfma_f32_16x16x32_bf16 v[74:77], v[232:235], v[196:199], v[74:77]
	v_mfma_f32_16x16x32_bf16 v[70:73], v[222:225], v[206:209], v[70:73]
	v_mfma_f32_16x16x32_bf16 v[66:69], v[232:235], v[206:209], v[66:69]
	v_mfma_f32_16x16x32_bf16 v[94:97], v[228:231], v[184:187], v[94:97]
	v_mfma_f32_16x16x32_bf16 v[90:93], v[236:239], v[184:187], v[90:93]
	v_mfma_f32_16x16x32_bf16 v[86:89], v[228:231], v[192:195], v[86:89]
	v_mfma_f32_16x16x32_bf16 v[82:85], v[236:239], v[192:195], v[82:85]
	v_mfma_f32_16x16x32_bf16 v[78:81], v[228:231], v[202:205], v[78:81]
	v_mfma_f32_16x16x32_bf16 v[74:77], v[236:239], v[202:205], v[74:77]
	v_mfma_f32_16x16x32_bf16 v[70:73], v[228:231], v[216:219], v[70:73]
	v_mfma_f32_16x16x32_bf16 v[66:69], v[236:239], v[216:219], v[66:69]
	s_barrier
; #define STAGE_B(P, br, kt) do { const char* _gb = (const char*)(Bt + ((long)(br) * K + (long)(kt) * BK)); \
;     __builtin_amdgcn_global_load_lds((const unsigned*)(_gb + bofl0), (unsigned*)((char*)(P) + gtid_ * 16), 16, 0, 0); \
;     __builtin_amdgcn_global_load_lds((const unsigned*)(_gb + (long)K * 128 + bofl0), (unsigned*)((char*)(P) + gtid_ * 16 + 8192), 16, 0, 0); } while (0)
; #define LDA(dst, b, h) for (int m = 0; m < 4; ++m) for (int k = 0; k < 2; ++k) \
;     dst[m][k] = *reinterpret_cast<const bf16x8*>((char*)SA(b, h) + lds_byte(wr * 64 + m * 16 + fr, k * 32 + fq * 8))
; #define LDB(dst, b, h) for (int n = 0; n < 2; ++n) for (int k = 0; k < 2; ++k) \
;     dst[n][k] = *reinterpret_cast<const bf16x8*>((char*)SB(b, h) + lds_byte(wc * 32 + n * 16 + fr, k * 32 + fq * 8))
; #define MMA(ai, bj, At_, Bt_) do { __builtin_amdgcn_s_setprio(1); \
;     for (int m = 0; m < 4; ++m) for (int n = 0; n < 2; ++n) for (int k = 0; k < 2; ++k) \
;       acc[ai][bj][m][n] = __builtin_amdgcn_mfma_f32_16x16x32_bf16(At_[m][k], Bt_[n][k], acc[ai][bj][m][n], 0, 0, 0); \
;     __builtin_amdgcn_s_setprio(0); } while (0)
; #define WAIT_V(n) asm volatile("s_waitcnt vmcnt(" #n ")" ::: "memory")
; #define WAIT_L(n) asm volatile("s_waitcnt lgkmcnt(" #n ")" ::: "memory")
; #define BAR __builtin_amdgcn_s_barrier()
; #define SCHED __builtin_amdgcn_sched_barrier(0)
; template <int EPI>
; __device__ __forceinline__ void gemm_tile(const GemmArgs& g, int brow, int bcol, int parity, bool first, bool nvalid, int nbrow, int nbcol) {
;     ...
;     LDA(At, 1, 1); STAGE_A(SA(1, 0), brow, t + 3);
;     BAR; WAIT_L(0); MMA(1, 0, At, B0); BAR; SCHED;
;     STAGE_B(SB(1, 1), bcol + HALF, t + 3);
;     WAIT_V(6); BAR; MMA(1, 1, At, B1); BAR; SCHED;
;   }
;   { LDB(B0, 0, 0); LDA(At, 0, 0); STAGE_A(SA(1, 1), brow + HALF, nt - 1);
;     BAR; WAIT_L(0); MMA(0, 0, At, B0); BAR;
	ds_read_b128 v[180:183], v147 offset:49152
	ds_read_b128 v[184:187], v147 offset:50176
	ds_read_b128 v[188:191], v146 offset:49152
	ds_read_b128 v[192:195], v146 offset:50176
	ds_read_b128 v[196:199], v145 offset:49152
	ds_read_b128 v[202:205], v145 offset:50176
	ds_read_b128 v[206:209], v144 offset:49152
	ds_read_b128 v[216:219], v144 offset:50176
	v_readfirstlane_b32 s2, v150
	v_lshl_add_u64 v[240:241], v[212:213], 0, s[58:59]
	s_mov_b32 m0, s2
	v_readfirstlane_b32 s2, v151
	global_load_lds_dwordx4 v[240:241], off
	v_lshl_add_u64 v[240:241], v[212:213], 0, vcc
	s_mov_b32 m0, s2
	s_nop 0
	global_load_lds_dwordx4 v[240:241], off
	v_readfirstlane_b32 s2, v152
	v_lshl_add_u64 v[240:241], v[210:211], 0, s[52:53]
	s_mov_b32 m0, s2
	v_readfirstlane_b32 s2, v153
	global_load_lds_dwordx4 v[240:241], off
	v_lshl_add_u64 v[210:211], v[210:211], 0, s[56:57]
	s_mov_b32 m0, s2
	s_nop 0
	global_load_lds_dwordx4 v[210:211], off
	v_readfirstlane_b32 s2, v155
	v_lshl_add_u64 v[244:245], v[212:213], 0, s[60:61]
	s_mov_b32 m0, s2
	v_readfirstlane_b32 s2, v156
	global_load_lds_dwordx4 v[244:245], off
	v_lshl_add_u64 v[244:245], v[212:213], 0, s[94:95]
	s_mov_b32 m0, s2
	s_nop 0
	global_load_lds_dwordx4 v[244:245], off
	s_waitcnt vmcnt(8)
	s_barrier
	s_waitcnt lgkmcnt(0)
	v_mfma_f32_16x16x32_bf16 v[62:65], v[164:167], v[180:183], v[62:65]
	v_mfma_f32_16x16x32_bf16 v[58:61], v[172:175], v[180:183], v[58:61]
	v_mfma_f32_16x16x32_bf16 v[54:57], v[164:167], v[188:191], v[54:57]
	v_mfma_f32_16x16x32_bf16 v[50:53], v[172:175], v[188:191], v[50:53]
	v_mfma_f32_16x16x32_bf16 v[46:49], v[164:167], v[196:199], v[46:49]
	v_mfma_f32_16x16x32_bf16 v[42:45], v[172:175], v[196:199], v[42:45]
	v_mfma_f32_16x16x32_bf16 v[38:41], v[164:167], v[206:209], v[38:41]
	v_mfma_f32_16x16x32_bf16 v[34:37], v[172:175], v[206:209], v[34:37]
	v_mfma_f32_16x16x32_bf16 v[62:65], v[168:171], v[184:187], v[62:65]
	v_mfma_f32_16x16x32_bf16 v[58:61], v[176:179], v[184:187], v[58:61]
	v_mfma_f32_16x16x32_bf16 v[54:57], v[168:171], v[192:195], v[54:57]
	v_mfma_f32_16x16x32_bf16 v[50:53], v[176:179], v[192:195], v[50:53]
	v_mfma_f32_16x16x32_bf16 v[46:49], v[168:171], v[202:205], v[46:49]
	v_mfma_f32_16x16x32_bf16 v[42:45], v[176:179], v[202:205], v[42:45]
	v_mfma_f32_16x16x32_bf16 v[38:41], v[168:171], v[216:219], v[38:41]
	v_mfma_f32_16x16x32_bf16 v[34:37], v[176:179], v[216:219], v[34:37]
	v_mfma_f32_16x16x32_bf16 v[30:33], v[222:225], v[180:183], v[30:33]
	v_mfma_f32_16x16x32_bf16 v[26:29], v[232:235], v[180:183], v[26:29]
	v_mfma_f32_16x16x32_bf16 v[22:25], v[222:225], v[188:191], v[22:25]
	v_mfma_f32_16x16x32_bf16 v[18:21], v[232:235], v[188:191], v[18:21]
	v_mfma_f32_16x16x32_bf16 v[14:17], v[222:225], v[196:199], v[14:17]
	v_mfma_f32_16x16x32_bf16 v[10:13], v[232:235], v[196:199], v[10:13]
	v_mfma_f32_16x16x32_bf16 v[6:9], v[222:225], v[206:209], v[6:9]
	v_mfma_f32_16x16x32_bf16 v[2:5], v[232:235], v[206:209], v[2:5]
	v_mfma_f32_16x16x32_bf16 v[30:33], v[228:231], v[184:187], v[30:33]
	v_mfma_f32_16x16x32_bf16 v[26:29], v[236:239], v[184:187], v[26:29]
	v_mfma_f32_16x16x32_bf16 v[22:25], v[228:231], v[192:195], v[22:25]
	v_mfma_f32_16x16x32_bf16 v[18:21], v[236:239], v[192:195], v[18:21]
	v_mfma_f32_16x16x32_bf16 v[14:17], v[228:231], v[202:205], v[14:17]
	v_mfma_f32_16x16x32_bf16 v[10:13], v[236:239], v[202:205], v[10:13]
	v_mfma_f32_16x16x32_bf16 v[6:9], v[228:231], v[216:219], v[6:9]
	v_mfma_f32_16x16x32_bf16 v[2:5], v[236:239], v[216:219], v[2:5]
	s_barrier
	s_add_i32 s25, s25, 2
	s_add_u32 s0, s0, 0x100
	s_addc_u32 s1, s1, 0
	s_add_u32 s12, s12, 0x100
	s_addc_u32 s13, s13, 0
	s_cmp_lt_u32 s25, 12
	s_cbranch_scc1 .LBB0_166
	s_or_b32 s0, s38, 0x80
	s_ashr_i32 s1, s0, 31
	s_lshl_b64 s[0:1], s[0:1], 11
	s_add_u32 s0, s80, s0
	s_addc_u32 s1, s81, s1
	v_lshl_add_u64 v[130:131], s[0:1], 0, v[0:1]
	s_mov_b64 s[0:1], 0x780
	ds_read_b128 v[150:153], v157
	ds_read_b128 v[164:167], v157 offset:1024
	ds_read_b128 v[168:171], v157 offset:2048
	ds_read_b128 v[172:175], v157 offset:3072
	ds_read_b128 v[176:179], v147
	ds_read_b128 v[180:183], v147 offset:1024
	ds_read_b128 v[184:187], v146
	ds_read_b128 v[188:191], v146 offset:1024
	ds_read_b128 v[192:195], v145
	ds_read_b128 v[196:199], v145 offset:1024
	ds_read_b128 v[202:205], v144
	ds_read_b128 v[206:209], v144 offset:1024
	v_lshl_add_u64 v[156:157], v[130:131], 0, s[0:1]
	v_readfirstlane_b32 s0, v161
	s_mov_b32 m0, s0
	s_mov_b64 s[0:1], 0x20780
	v_lshl_add_u64 v[130:131], v[130:131], 0, s[0:1]
	v_readfirstlane_b32 s0, v162
	global_load_lds_dwordx4 v[156:157], off
	s_mov_b32 m0, s0
	s_nop 0
	global_load_lds_dwordx4 v[130:131], off
	s_waitcnt vmcnt(8)
	s_barrier
	s_waitcnt lgkmcnt(0)
	s_setprio 1
	s_waitcnt lgkmcnt(0)
	v_mfma_f32_16x16x32_bf16 v[126:129], v[150:153], v[176:179], v[126:129]
	v_mfma_f32_16x16x32_bf16 v[118:121], v[150:153], v[184:187], v[118:121]
	v_mfma_f32_16x16x32_bf16 v[110:113], v[150:153], v[192:195], v[110:113]
	v_mfma_f32_16x16x32_bf16 v[102:105], v[150:153], v[202:205], v[102:105]
	v_mfma_f32_16x16x32_bf16 v[126:129], v[164:167], v[180:183], v[126:129]
	v_mfma_f32_16x16x32_bf16 v[122:125], v[168:171], v[176:179], v[122:125]
	v_mfma_f32_16x16x32_bf16 v[118:121], v[164:167], v[188:191], v[118:121]
	v_mfma_f32_16x16x32_bf16 v[114:117], v[168:171], v[184:187], v[114:117]
	v_mfma_f32_16x16x32_bf16 v[110:113], v[164:167], v[196:199], v[110:113]
	v_mfma_f32_16x16x32_bf16 v[106:109], v[168:171], v[192:195], v[106:109]
	v_mfma_f32_16x16x32_bf16 v[102:105], v[164:167], v[206:209], v[102:105]
	v_mfma_f32_16x16x32_bf16 v[98:101], v[168:171], v[202:205], v[98:101]
	v_mfma_f32_16x16x32_bf16 v[216:219], v[172:175], v[180:183], v[122:125]
	v_mfma_f32_16x16x32_bf16 v[222:225], v[172:175], v[188:191], v[114:117]
	v_mfma_f32_16x16x32_bf16 v[228:231], v[172:175], v[196:199], v[106:109]
	v_mfma_f32_16x16x32_bf16 v[232:235], v[172:175], v[206:209], v[98:101]
	s_setprio 0
	s_barrier
; #define LDA(dst, b, h) for (int m = 0; m < 4; ++m) for (int k = 0; k < 2; ++k) \
;     dst[m][k] = *reinterpret_cast<const bf16x8*>((char*)SA(b, h) + lds_byte(wr * 64 + m * 16 + fr, k * 32 + fq * 8))
; #define LDB(dst, b, h) for (int n = 0; n < 2; ++n) for (int k = 0; k < 2; ++k) \
;     dst[n][k] = *reinterpret_cast<const bf16x8*>((char*)SB(b, h) + lds_byte(wc * 32 + n * 16 + fr, k * 32 + fq * 8))
; #define MMA(ai, bj, At_, Bt_) do { __builtin_amdgcn_s_setprio(1); \
;     for (int m = 0; m < 4; ++m) for (int n = 0; n < 2; ++n) for (int k = 0; k < 2; ++k) \
;       acc[ai][bj][m][n] = __builtin_amdgcn_mfma_f32_16x16x32_bf16(At_[m][k], Bt_[n][k], acc[ai][bj][m][n], 0, 0, 0); \
;     __builtin_amdgcn_s_setprio(0); } while (0)
; #define WAIT_V(n) asm volatile("s_waitcnt vmcnt(" #n ")" ::: "memory")
; #define WAIT_L(n) asm volatile("s_waitcnt lgkmcnt(" #n ")" ::: "memory")
; #define BAR __builtin_amdgcn_s_barrier()
; #define SCHED __builtin_amdgcn_sched_barrier(0)
; template <int EPI>
; __device__ __forceinline__ void gemm_tile(const GemmArgs& g, int brow, int bcol, int parity, bool first, bool nvalid, int nbrow, int nbcol) {
;     ...
;     BAR; WAIT_L(0); MMA(0, 0, At, B0); BAR;
;     LDB(B1, 0, 1); BAR; WAIT_L(0); MMA(0, 1, At, B1); BAR; SCHED;
;     LDA(At, 0, 1); WAIT_V(4); BAR; WAIT_L(0); MMA(1, 0, At, B0); MMA(1, 1, At, B1); BAR; }
;   { LDB(B0, 1, 0); LDA(At, 1, 0); WAIT_V(2); BAR; WAIT_L(0); MMA(0, 0, At, B0); BAR;
	s_nop 1
	ds_read_b128 v[98:101], v154
	ds_read_b128 v[106:109], v154 offset:1024
	ds_read_b128 v[114:117], v154 offset:2048
	ds_read_b128 v[122:125], v154 offset:3072
	s_barrier
	s_waitcnt lgkmcnt(0)
	s_setprio 1
	s_waitcnt lgkmcnt(0)
	v_mfma_f32_16x16x32_bf16 v[94:97], v[98:101], v[176:179], v[94:97]
	v_mfma_f32_16x16x32_bf16 v[86:89], v[98:101], v[184:187], v[86:89]
	v_mfma_f32_16x16x32_bf16 v[78:81], v[98:101], v[192:195], v[78:81]
	v_mfma_f32_16x16x32_bf16 v[74:77], v[114:117], v[192:195], v[74:77]
	v_mfma_f32_16x16x32_bf16 v[94:97], v[106:109], v[180:183], v[94:97]
	v_mfma_f32_16x16x32_bf16 v[90:93], v[114:117], v[176:179], v[90:93]
	v_mfma_f32_16x16x32_bf16 v[86:89], v[106:109], v[188:191], v[86:89]
	v_mfma_f32_16x16x32_bf16 v[82:85], v[114:117], v[184:187], v[82:85]
	v_mfma_f32_16x16x32_bf16 v[78:81], v[106:109], v[196:199], v[78:81]
	v_mfma_f32_16x16x32_bf16 v[74:77], v[122:125], v[196:199], v[74:77]
	v_mfma_f32_16x16x32_bf16 v[70:73], v[98:101], v[202:205], v[70:73]
	v_mfma_f32_16x16x32_bf16 v[66:69], v[114:117], v[202:205], v[66:69]
	v_mfma_f32_16x16x32_bf16 v[154:157], v[122:125], v[180:183], v[90:93]
	v_mfma_f32_16x16x32_bf16 v[176:179], v[122:125], v[188:191], v[82:85]
	v_mfma_f32_16x16x32_bf16 v[180:183], v[106:109], v[206:209], v[70:73]
	v_mfma_f32_16x16x32_bf16 v[184:187], v[122:125], v[206:209], v[66:69]
	s_setprio 0
	s_barrier
	s_nop 1
	ds_read_b128 v[66:69], v147 offset:16384
	ds_read_b128 v[70:73], v147 offset:17408
	ds_read_b128 v[82:85], v146 offset:16384
	ds_read_b128 v[90:93], v146 offset:17408
	ds_read_b128 v[188:191], v145 offset:16384
	ds_read_b128 v[192:195], v145 offset:17408
	ds_read_b128 v[196:199], v144 offset:16384
	ds_read_b128 v[202:205], v144 offset:17408
	s_waitcnt vmcnt(4)
	s_barrier
	s_waitcnt lgkmcnt(0)
	s_setprio 1
	s_waitcnt lgkmcnt(0)
	v_mfma_f32_16x16x32_bf16 v[62:65], v[150:153], v[66:69], v[62:65]
	v_mfma_f32_16x16x32_bf16 v[54:57], v[150:153], v[82:85], v[54:57]
	v_mfma_f32_16x16x32_bf16 v[46:49], v[150:153], v[188:191], v[46:49]
	v_mfma_f32_16x16x32_bf16 v[38:41], v[150:153], v[196:199], v[38:41]
	v_mfma_f32_16x16x32_bf16 v[62:65], v[164:167], v[70:73], v[62:65]
	v_mfma_f32_16x16x32_bf16 v[58:61], v[168:171], v[66:69], v[58:61]
	v_mfma_f32_16x16x32_bf16 v[54:57], v[164:167], v[90:93], v[54:57]
	v_mfma_f32_16x16x32_bf16 v[50:53], v[168:171], v[82:85], v[50:53]
	v_mfma_f32_16x16x32_bf16 v[46:49], v[164:167], v[192:195], v[46:49]
	v_mfma_f32_16x16x32_bf16 v[42:45], v[168:171], v[188:191], v[42:45]
	v_mfma_f32_16x16x32_bf16 v[38:41], v[164:167], v[202:205], v[38:41]
	v_mfma_f32_16x16x32_bf16 v[34:37], v[168:171], v[196:199], v[34:37]
	v_mfma_f32_16x16x32_bf16 v[206:209], v[172:175], v[70:73], v[58:61]
	v_mfma_f32_16x16x32_bf16 v[236:239], v[172:175], v[90:93], v[50:53]
	v_mfma_f32_16x16x32_bf16 v[240:243], v[172:175], v[192:195], v[42:45]
	v_mfma_f32_16x16x32_bf16 v[150:153], v[172:175], v[202:205], v[34:37]
	s_setprio 0
	s_setprio 1
	v_mfma_f32_16x16x32_bf16 v[30:33], v[98:101], v[66:69], v[30:33]
	v_mfma_f32_16x16x32_bf16 v[22:25], v[98:101], v[82:85], v[22:25]
	v_mfma_f32_16x16x32_bf16 v[14:17], v[98:101], v[188:191], v[14:17]
	v_mfma_f32_16x16x32_bf16 v[10:13], v[114:117], v[188:191], v[10:13]
	v_mfma_f32_16x16x32_bf16 v[30:33], v[106:109], v[70:73], v[30:33]
	v_mfma_f32_16x16x32_bf16 v[26:29], v[114:117], v[66:69], v[26:29]
	v_mfma_f32_16x16x32_bf16 v[22:25], v[106:109], v[90:93], v[22:25]
	v_mfma_f32_16x16x32_bf16 v[18:21], v[114:117], v[82:85], v[18:21]
	v_mfma_f32_16x16x32_bf16 v[14:17], v[106:109], v[192:195], v[14:17]
	v_mfma_f32_16x16x32_bf16 v[10:13], v[122:125], v[192:195], v[10:13]
	v_mfma_f32_16x16x32_bf16 v[6:9], v[98:101], v[196:199], v[6:9]
	v_mfma_f32_16x16x32_bf16 v[2:5], v[114:117], v[196:199], v[2:5]
	v_mfma_f32_16x16x32_bf16 v[162:165], v[122:125], v[70:73], v[26:29]
	v_mfma_f32_16x16x32_bf16 v[166:169], v[122:125], v[90:93], v[18:21]
	v_mfma_f32_16x16x32_bf16 v[170:173], v[106:109], v[202:205], v[6:9]
	v_mfma_f32_16x16x32_bf16 v[188:191], v[122:125], v[202:205], v[2:5]
	s_setprio 0
	s_barrier
	s_nop 1
	ds_read_b128 v[2:5], v149
	ds_read_b128 v[6:9], v149 offset:1024
	ds_read_b128 v[192:195], v149 offset:2048
	ds_read_b128 v[196:199], v149 offset:3072
	ds_read_b128 v[18:21], v147 offset:32768
	ds_read_b128 v[26:29], v147 offset:33792
	ds_read_b128 v[34:37], v146 offset:32768
	ds_read_b128 v[42:45], v146 offset:33792
	ds_read_b128 v[50:53], v145 offset:32768
	ds_read_b128 v[58:61], v145 offset:33792
	ds_read_b128 v[202:205], v144 offset:32768
	ds_read_b128 v[244:247], v144 offset:33792
	s_waitcnt vmcnt(2)
	s_barrier
; #define LDA(dst, b, h) for (int m = 0; m < 4; ++m) for (int k = 0; k < 2; ++k) \
;     dst[m][k] = *reinterpret_cast<const bf16x8*>((char*)SA(b, h) + lds_byte(wr * 64 + m * 16 + fr, k * 32 + fq * 8))
; #define LDB(dst, b, h) for (int n = 0; n < 2; ++n) for (int k = 0; k < 2; ++k) \
;     dst[n][k] = *reinterpret_cast<const bf16x8*>((char*)SB(b, h) + lds_byte(wc * 32 + n * 16 + fr, k * 32 + fq * 8))
; #define MMA(ai, bj, At_, Bt_) do { __builtin_amdgcn_s_setprio(1); \
;     for (int m = 0; m < 4; ++m) for (int n = 0; n < 2; ++n) for (int k = 0; k < 2; ++k) \
;       acc[ai][bj][m][n] = __builtin_amdgcn_mfma_f32_16x16x32_bf16(At_[m][k], Bt_[n][k], acc[ai][bj][m][n], 0, 0, 0); \
;     __builtin_amdgcn_s_setprio(0); } while (0)
; #define WAIT_V(n) asm volatile("s_waitcnt vmcnt(" #n ")" ::: "memory")
; #define WAIT_L(n) asm volatile("s_waitcnt lgkmcnt(" #n ")" ::: "memory")
; #define BAR __builtin_amdgcn_s_barrier()
; #define SCHED __builtin_amdgcn_sched_barrier(0)
; template <int EPI>
; __device__ __forceinline__ void gemm_tile(const GemmArgs& g, int brow, int bcol, int parity, bool first, bool nvalid, int nbrow, int nbcol) {
;     ...
;   { LDB(B0, 1, 0); LDA(At, 1, 0); WAIT_V(2); BAR; WAIT_L(0); MMA(0, 0, At, B0); BAR;
;     LDB(B1, 1, 1); WAIT_V(0); BAR; WAIT_L(0); MMA(0, 1, At, B1); BAR; SCHED;
;     LDA(At, 1, 1); BAR; WAIT_L(0); MMA(1, 0, At, B0); MMA(1, 1, At, B1); BAR; }
;   if (wr == 0) BAR;
	s_waitcnt lgkmcnt(0)
	s_setprio 1
	s_waitcnt lgkmcnt(0)
	v_mfma_f32_16x16x32_bf16 v[66:69], v[2:5], v[18:21], v[126:129]
	v_mfma_f32_16x16x32_bf16 v[122:125], v[6:9], v[26:29], v[66:69]
	v_mfma_f32_16x16x32_bf16 v[66:69], v[192:195], v[18:21], v[216:219]
	v_mfma_f32_16x16x32_bf16 v[114:117], v[196:199], v[26:29], v[66:69]
	v_mfma_f32_16x16x32_bf16 v[66:69], v[2:5], v[34:37], v[118:121]
	v_mfma_f32_16x16x32_bf16 v[106:109], v[6:9], v[42:45], v[66:69]
	v_mfma_f32_16x16x32_bf16 v[66:69], v[192:195], v[34:37], v[222:225]
	v_mfma_f32_16x16x32_bf16 v[98:101], v[196:199], v[42:45], v[66:69]
	v_mfma_f32_16x16x32_bf16 v[66:69], v[2:5], v[50:53], v[110:113]
	v_mfma_f32_16x16x32_bf16 v[90:93], v[6:9], v[58:61], v[66:69]
	v_mfma_f32_16x16x32_bf16 v[66:69], v[192:195], v[50:53], v[228:231]
	v_mfma_f32_16x16x32_bf16 v[82:85], v[196:199], v[58:61], v[66:69]
	v_mfma_f32_16x16x32_bf16 v[66:69], v[2:5], v[202:205], v[102:105]
	v_mfma_f32_16x16x32_bf16 v[70:73], v[6:9], v[244:247], v[66:69]
	v_mfma_f32_16x16x32_bf16 v[66:69], v[192:195], v[202:205], v[232:235]
	v_mfma_f32_16x16x32_bf16 v[66:69], v[196:199], v[244:247], v[66:69]
	s_setprio 0
	s_barrier
	ds_read_b128 v[216:219], v148
	ds_read_b128 v[222:225], v148 offset:1024
	ds_read_b128 v[228:231], v148 offset:2048
	ds_read_b128 v[232:235], v148 offset:3072
	s_waitcnt vmcnt(0)
	s_barrier
	s_waitcnt lgkmcnt(0)
	s_setprio 1
	s_waitcnt lgkmcnt(0)
	v_mfma_f32_16x16x32_bf16 v[94:97], v[216:219], v[18:21], v[94:97]
	v_mfma_f32_16x16x32_bf16 v[18:21], v[228:231], v[18:21], v[154:157]
	v_mfma_f32_16x16x32_bf16 v[118:121], v[232:235], v[26:29], v[18:21]
	v_mfma_f32_16x16x32_bf16 v[18:21], v[216:219], v[34:37], v[86:89]
	v_mfma_f32_16x16x32_bf16 v[110:113], v[222:225], v[42:45], v[18:21]
	v_mfma_f32_16x16x32_bf16 v[18:21], v[228:231], v[34:37], v[176:179]
	v_mfma_f32_16x16x32_bf16 v[102:105], v[232:235], v[42:45], v[18:21]
	v_mfma_f32_16x16x32_bf16 v[18:21], v[216:219], v[50:53], v[78:81]
	v_mfma_f32_16x16x32_bf16 v[126:129], v[222:225], v[26:29], v[94:97]
	v_mfma_f32_16x16x32_bf16 v[94:97], v[222:225], v[58:61], v[18:21]
	v_mfma_f32_16x16x32_bf16 v[18:21], v[228:231], v[50:53], v[74:77]
	v_mfma_f32_16x16x32_bf16 v[86:89], v[232:235], v[58:61], v[18:21]
	v_mfma_f32_16x16x32_bf16 v[18:21], v[216:219], v[202:205], v[180:183]
	v_mfma_f32_16x16x32_bf16 v[78:81], v[222:225], v[244:247], v[18:21]
	v_mfma_f32_16x16x32_bf16 v[18:21], v[228:231], v[202:205], v[184:187]
	v_mfma_f32_16x16x32_bf16 v[74:77], v[232:235], v[244:247], v[18:21]
	s_setprio 0
	s_barrier
	ds_read_b128 v[154:157], v147 offset:49152
	ds_read_b128 v[174:177], v147 offset:50176
	ds_read_b128 v[178:181], v146 offset:49152
	ds_read_b128 v[146:149], v146 offset:50176
	ds_read_b128 v[182:185], v145 offset:49152
	ds_read_b128 v[202:205], v145 offset:50176
	ds_read_b128 v[244:247], v144 offset:49152
	ds_read_b128 v[248:251], v144 offset:50176
	s_barrier
	s_waitcnt lgkmcnt(0)
	s_setprio 1
	s_waitcnt lgkmcnt(0)
	v_mfma_f32_16x16x32_bf16 v[18:21], v[2:5], v[154:157], v[62:65]
	v_mfma_f32_16x16x32_bf16 v[58:61], v[6:9], v[174:177], v[18:21]
	v_mfma_f32_16x16x32_bf16 v[18:21], v[192:195], v[154:157], v[206:209]
	v_mfma_f32_16x16x32_bf16 v[50:53], v[196:199], v[174:177], v[18:21]
	v_mfma_f32_16x16x32_bf16 v[18:21], v[2:5], v[178:181], v[54:57]
	v_mfma_f32_16x16x32_bf16 v[42:45], v[6:9], v[146:149], v[18:21]
	v_mfma_f32_16x16x32_bf16 v[18:21], v[192:195], v[178:181], v[236:239]
	v_mfma_f32_16x16x32_bf16 v[34:37], v[196:199], v[146:149], v[18:21]
	v_mfma_f32_16x16x32_bf16 v[18:21], v[2:5], v[182:185], v[46:49]
	v_mfma_f32_16x16x32_bf16 v[2:5], v[2:5], v[244:247], v[38:41]
	v_mfma_f32_16x16x32_bf16 v[26:29], v[6:9], v[202:205], v[18:21]
	v_mfma_f32_16x16x32_bf16 v[18:21], v[192:195], v[182:185], v[240:243]
	v_mfma_f32_16x16x32_bf16 v[6:9], v[6:9], v[248:251], v[2:5]
	v_mfma_f32_16x16x32_bf16 v[2:5], v[192:195], v[244:247], v[150:153]
	v_mfma_f32_16x16x32_bf16 v[18:21], v[196:199], v[202:205], v[18:21]
	v_mfma_f32_16x16x32_bf16 v[2:5], v[196:199], v[248:251], v[2:5]
	s_setprio 0
	s_setprio 1
	v_mfma_f32_16x16x32_bf16 v[22:25], v[216:219], v[178:181], v[22:25]
	v_mfma_f32_16x16x32_bf16 v[30:33], v[216:219], v[154:157], v[30:33]
	v_mfma_f32_16x16x32_bf16 v[46:49], v[222:225], v[146:149], v[22:25]
	v_mfma_f32_16x16x32_bf16 v[22:25], v[228:231], v[178:181], v[166:169]
	v_mfma_f32_16x16x32_bf16 v[10:13], v[228:231], v[182:185], v[10:13]
	v_mfma_f32_16x16x32_bf16 v[62:65], v[222:225], v[174:177], v[30:33]
	v_mfma_f32_16x16x32_bf16 v[30:33], v[228:231], v[154:157], v[162:165]
	v_mfma_f32_16x16x32_bf16 v[38:41], v[232:235], v[146:149], v[22:25]
	v_mfma_f32_16x16x32_bf16 v[14:17], v[216:219], v[182:185], v[14:17]
	v_mfma_f32_16x16x32_bf16 v[22:25], v[232:235], v[202:205], v[10:13]
	v_mfma_f32_16x16x32_bf16 v[10:13], v[216:219], v[244:247], v[170:173]
	v_mfma_f32_16x16x32_bf16 v[54:57], v[232:235], v[174:177], v[30:33]
	v_mfma_f32_16x16x32_bf16 v[30:33], v[222:225], v[202:205], v[14:17]
	v_mfma_f32_16x16x32_bf16 v[14:17], v[222:225], v[248:251], v[10:13]
	v_mfma_f32_16x16x32_bf16 v[10:13], v[228:231], v[244:247], v[188:191]
	v_mfma_f32_16x16x32_bf16 v[10:13], v[232:235], v[248:251], v[10:13]
	s_setprio 0
	s_movk_i32 s0, 0x100
	v_cmp_gt_u32_e32 vcc, s0, v138
	s_barrier
	s_and_saveexec_b64 s[0:1], vcc
	s_cbranch_execz .LBB0_169
	s_barrier

; #define STAGE_B(P, br, kt) do { const char* _gb = (const char*)(Bt + ((long)(br) * K + (long)(kt) * BK)); \
;     __builtin_amdgcn_global_load_lds((const unsigned*)(_gb + bofl0), (unsigned*)((char*)(P) + gtid_ * 16), 16, 0, 0); \
;     __builtin_amdgcn_global_load_lds((const unsigned*)(_gb + (long)K * 128 + bofl0), (unsigned*)((char*)(P) + gtid_ * 16 + 8192), 16, 0, 0); } while (0)
; #define LDA(dst, b, h) for (int m = 0; m < 4; ++m) for (int k = 0; k < 2; ++k) \
;     dst[m][k] = *reinterpret_cast<const bf16x8*>((char*)SA(b, h) + lds_byte(wr * 64 + m * 16 + fr, k * 32 + fq * 8))
; #define LDB(dst, b, h) for (int n = 0; n < 2; ++n) for (int k = 0; k < 2; ++k) \
;     dst[n][k] = *reinterpret_cast<const bf16x8*>((char*)SB(b, h) + lds_byte(wc * 32 + n * 16 + fr, k * 32 + fq * 8))
; #define MMA(ai, bj, At_, Bt_) do { __builtin_amdgcn_s_setprio(1); \
;     for (int m = 0; m < 4; ++m) for (int n = 0; n < 2; ++n) for (int k = 0; k < 2; ++k) \
;       acc[ai][bj][m][n] = __builtin_amdgcn_mfma_f32_16x16x32_bf16(At_[m][k], Bt_[n][k], acc[ai][bj][m][n], 0, 0, 0); \
;     __builtin_amdgcn_s_setprio(0); } while (0)
; #define WAIT_V(n) asm volatile("s_waitcnt vmcnt(" #n ")" ::: "memory")
; #define WAIT_L(n) asm volatile("s_waitcnt lgkmcnt(" #n ")" ::: "memory")
; #define BAR __builtin_amdgcn_s_barrier()
; #define SCHED __builtin_amdgcn_sched_barrier(0)
; template <int EPI>
; __device__ __forceinline__ void gemm_tile(const GemmArgs& g, int brow, int bcol, int parity, bool first, bool nvalid, int nbrow, int nbcol) {
;     ...
;     LDB(B0, 0, 0); SCHED; LDA(At, 0, 0); STAGE_A(SA(1, 1), brow + HALF, t + 1);
;     WAIT_L(8); BAR; WAIT_L(0); MMA(0, 0, At, B0); BAR; SCHED;
;     LDB(B1, 0, 1); STAGE_B(SB(0, 0), bcol, t + 2);
;     BAR; WAIT_L(0); MMA(0, 1, At, B1); BAR; SCHED;
;     LDA(At, 0, 1); STAGE_A(SA(0, 0), brow, t + 2);
;     BAR; WAIT_L(0); MMA(1, 0, At, B0); BAR; SCHED;
;     STAGE_B(SB(0, 1), bcol + HALF, t + 2);
;     WAIT_V(6); BAR; MMA(1, 1, At, B1); BAR; SCHED;
;     LDB(B0, 1, 0); SCHED; LDA(At, 1, 0); STAGE_A(SA(0, 1), brow + HALF, t + 2);
.LBB0_191:
	ds_read_b128 v[166:169], v160
	ds_read_b128 v[170:173], v160 offset:1024
	ds_read_b128 v[174:177], v160 offset:2048
	ds_read_b128 v[178:181], v160 offset:3072
	ds_read_b128 v[182:185], v150
	ds_read_b128 v[186:189], v150 offset:1024
	ds_read_b128 v[190:193], v149
	ds_read_b128 v[194:197], v149 offset:1024
	ds_read_b128 v[202:205], v148
	ds_read_b128 v[206:209], v148 offset:1024
	ds_read_b128 v[216:219], v147
	ds_read_b128 v[222:225], v147 offset:1024
	s_waitcnt lgkmcnt(6)
	ds_read_b128 v[228:231], v159
	ds_read_b128 v[232:235], v159 offset:1024
	ds_read_b128 v[236:239], v159 offset:2048
	ds_read_b128 v[240:243], v159 offset:3072
	s_add_i32 s2, s61, 0xffffff80
	s_cmp_lt_u32 s2, s35
	s_cselect_b32 s3, s36, s57
	s_add_i32 s2, s2, s3
	s_ashr_i32 s3, s2, 31
	s_lshl_b64 s[2:3], s[2:3], 1
	s_add_u32 s2, s41, s2
	s_addc_u32 s3, s44, s3
	v_add_u32_e32 v165, 0xc000, v140
	v_lshl_add_u64 v[162:163], s[2:3], 0, v[130:131]
	v_readfirstlane_b32 s26, v165
	s_add_u32 s2, s2, s53
	s_mov_b32 m0, s26
	s_addc_u32 s3, s3, 0
	v_add_u32_e32 v164, 0xe000, v140
	global_load_lds_dwordx4 v[162:163], off
	v_lshl_add_u64 v[162:163], s[2:3], 0, v[130:131]
	v_readfirstlane_b32 s2, v164
	s_mov_b32 m0, s2
	s_nop 0
	global_load_lds_dwordx4 v[162:163], off
	s_waitcnt vmcnt(8)
	s_barrier
	s_waitcnt lgkmcnt(0)
	v_mfma_f32_16x16x32_bf16 v[126:129], v[166:169], v[182:185], v[126:129]
	v_mfma_f32_16x16x32_bf16 v[122:125], v[174:177], v[182:185], v[122:125]
	v_mfma_f32_16x16x32_bf16 v[118:121], v[166:169], v[190:193], v[118:121]
	v_mfma_f32_16x16x32_bf16 v[114:117], v[174:177], v[190:193], v[114:117]
	v_mfma_f32_16x16x32_bf16 v[110:113], v[166:169], v[202:205], v[110:113]
	v_mfma_f32_16x16x32_bf16 v[106:109], v[174:177], v[202:205], v[106:109]
	v_mfma_f32_16x16x32_bf16 v[102:105], v[166:169], v[216:219], v[102:105]
	v_mfma_f32_16x16x32_bf16 v[98:101], v[174:177], v[216:219], v[98:101]
	v_mfma_f32_16x16x32_bf16 v[126:129], v[170:173], v[186:189], v[126:129]
	v_mfma_f32_16x16x32_bf16 v[122:125], v[178:181], v[186:189], v[122:125]
	v_mfma_f32_16x16x32_bf16 v[118:121], v[170:173], v[194:197], v[118:121]
	v_mfma_f32_16x16x32_bf16 v[114:117], v[178:181], v[194:197], v[114:117]
	v_mfma_f32_16x16x32_bf16 v[110:113], v[170:173], v[206:209], v[110:113]
	v_mfma_f32_16x16x32_bf16 v[106:109], v[178:181], v[206:209], v[106:109]
	v_mfma_f32_16x16x32_bf16 v[102:105], v[170:173], v[222:225], v[102:105]
	v_mfma_f32_16x16x32_bf16 v[98:101], v[178:181], v[222:225], v[98:101]
	v_mfma_f32_16x16x32_bf16 v[94:97], v[228:231], v[182:185], v[94:97]
	v_mfma_f32_16x16x32_bf16 v[90:93], v[236:239], v[182:185], v[90:93]
	v_mfma_f32_16x16x32_bf16 v[86:89], v[228:231], v[190:193], v[86:89]
	v_mfma_f32_16x16x32_bf16 v[82:85], v[236:239], v[190:193], v[82:85]
	v_mfma_f32_16x16x32_bf16 v[78:81], v[228:231], v[202:205], v[78:81]
	v_mfma_f32_16x16x32_bf16 v[74:77], v[236:239], v[202:205], v[74:77]
	v_mfma_f32_16x16x32_bf16 v[70:73], v[228:231], v[216:219], v[70:73]
	v_mfma_f32_16x16x32_bf16 v[66:69], v[236:239], v[216:219], v[66:69]
	v_mfma_f32_16x16x32_bf16 v[94:97], v[232:235], v[186:189], v[94:97]
	v_mfma_f32_16x16x32_bf16 v[90:93], v[240:243], v[186:189], v[90:93]
	v_mfma_f32_16x16x32_bf16 v[86:89], v[232:235], v[194:197], v[86:89]
	v_mfma_f32_16x16x32_bf16 v[82:85], v[240:243], v[194:197], v[82:85]
	v_mfma_f32_16x16x32_bf16 v[78:81], v[232:235], v[206:209], v[78:81]
	v_mfma_f32_16x16x32_bf16 v[74:77], v[240:243], v[206:209], v[74:77]
	v_mfma_f32_16x16x32_bf16 v[70:73], v[232:235], v[222:225], v[70:73]
	v_mfma_f32_16x16x32_bf16 v[66:69], v[240:243], v[222:225], v[66:69]
	s_barrier
	ds_read_b128 v[182:185], v150 offset:16384
	ds_read_b128 v[186:189], v150 offset:17408
	ds_read_b128 v[190:193], v149 offset:16384
	ds_read_b128 v[194:197], v149 offset:17408
	ds_read_b128 v[202:205], v148 offset:16384
	ds_read_b128 v[206:209], v148 offset:17408
	ds_read_b128 v[216:219], v147 offset:16384
	ds_read_b128 v[222:225], v147 offset:17408
	v_add_u32_e32 v162, s40, v146
	v_lshl_add_u64 v[198:199], s[14:15], 0, v[132:133]
	v_readfirstlane_b32 s2, v162
	v_lshl_add_u64 v[210:211], v[198:199], 0, s[78:79]
	s_mov_b32 m0, s2
	v_add_u32_e32 v161, 0x2000, v162
	global_load_lds_dwordx4 v[210:211], off
	v_lshl_add_u64 v[210:211], s[18:19], 0, v[132:133]
	v_readfirstlane_b32 s2, v161
	v_lshl_add_u64 v[212:213], v[210:211], 0, s[78:79]
	s_mov_b32 m0, s2
	s_add_i32 s45, s45, 2
	global_load_lds_dwordx4 v[212:213], off
	s_sub_i32 s2, s61, 64
	s_cmp_lt_u32 s2, s35
	s_cselect_b32 s3, s36, s57
	s_add_i32 s2, s2, s3
	s_ashr_i32 s3, s2, 31
	s_lshl_b64 s[2:3], s[2:3], 1
	s_add_u32 s26, s25, s2
	s_addc_u32 s27, s39, s3
	v_lshl_add_u64 v[212:213], s[26:27], 0, v[130:131]
	v_readfirstlane_b32 s63, v140
	s_add_u32 s26, s26, s53
	s_mov_b32 m0, s63
	s_addc_u32 s27, s27, 0
	global_load_lds_dwordx4 v[212:213], off
	v_lshl_add_u64 v[212:213], s[26:27], 0, v[130:131]
	v_readfirstlane_b32 s26, v139
	s_mov_b32 m0, s26
	s_nop 0
	global_load_lds_dwordx4 v[212:213], off
	v_lshl_add_u64 v[212:213], s[20:21], 0, v[132:133]
	v_readfirstlane_b32 s26, v136
	v_add_u32_e32 v163, 0x2000, v136
	v_lshl_add_u64 v[246:247], v[212:213], 0, s[78:79]
	s_mov_b32 m0, s26
	v_lshl_add_u64 v[244:245], s[22:23], 0, v[132:133]
	v_readfirstlane_b32 s26, v163
	global_load_lds_dwordx4 v[246:247], off
	v_lshl_add_u64 v[246:247], v[244:245], 0, s[78:79]
	s_mov_b32 m0, s26
	s_nop 0
	global_load_lds_dwordx4 v[246:247], off
	s_waitcnt vmcnt(8)
	s_barrier
; #define STAGE_B(P, br, kt) do { const char* _gb = (const char*)(Bt + ((long)(br) * K + (long)(kt) * BK)); \
;     __builtin_amdgcn_global_load_lds((const unsigned*)(_gb + bofl0), (unsigned*)((char*)(P) + gtid_ * 16), 16, 0, 0); \
;     __builtin_amdgcn_global_load_lds((const unsigned*)(_gb + (long)K * 128 + bofl0), (unsigned*)((char*)(P) + gtid_ * 16 + 8192), 16, 0, 0); } while (0)
; #define LDA(dst, b, h) for (int m = 0; m < 4; ++m) for (int k = 0; k < 2; ++k) \
;     dst[m][k] = *reinterpret_cast<const bf16x8*>((char*)SA(b, h) + lds_byte(wr * 64 + m * 16 + fr, k * 32 + fq * 8))
; #define LDB(dst, b, h) for (int n = 0; n < 2; ++n) for (int k = 0; k < 2; ++k) \
;     dst[n][k] = *reinterpret_cast<const bf16x8*>((char*)SB(b, h) + lds_byte(wc * 32 + n * 16 + fr, k * 32 + fq * 8))
; #define MMA(ai, bj, At_, Bt_) do { __builtin_amdgcn_s_setprio(1); \
;     for (int m = 0; m < 4; ++m) for (int n = 0; n < 2; ++n) for (int k = 0; k < 2; ++k) \
;       acc[ai][bj][m][n] = __builtin_amdgcn_mfma_f32_16x16x32_bf16(At_[m][k], Bt_[n][k], acc[ai][bj][m][n], 0, 0, 0); \
;     __builtin_amdgcn_s_setprio(0); } while (0)
; #define WAIT_L(n) asm volatile("s_waitcnt lgkmcnt(" #n ")" ::: "memory")
; #define BAR __builtin_amdgcn_s_barrier()
; #define SCHED __builtin_amdgcn_sched_barrier(0)
; template <int EPI>
; __device__ __forceinline__ void gemm_tile(const GemmArgs& g, int brow, int bcol, int parity, bool first, bool nvalid, int nbrow, int nbcol) {
;     ...
;     LDB(B0, 1, 0); SCHED; LDA(At, 1, 0); STAGE_A(SA(0, 1), brow + HALF, t + 2);
;     WAIT_L(8); BAR; WAIT_L(0); MMA(0, 0, At, B0); BAR; SCHED;
;     LDB(B1, 1, 1); STAGE_B(SB(1, 0), bcol, t + 3);
;     BAR; WAIT_L(0); MMA(0, 1, At, B1); BAR; SCHED;
;     LDA(At, 1, 1); STAGE_A(SA(1, 0), brow, t + 3);
	s_waitcnt lgkmcnt(0)
	v_mfma_f32_16x16x32_bf16 v[62:65], v[166:169], v[182:185], v[62:65]
	v_mfma_f32_16x16x32_bf16 v[58:61], v[174:177], v[182:185], v[58:61]
	v_mfma_f32_16x16x32_bf16 v[54:57], v[166:169], v[190:193], v[54:57]
	v_mfma_f32_16x16x32_bf16 v[50:53], v[174:177], v[190:193], v[50:53]
	v_mfma_f32_16x16x32_bf16 v[46:49], v[166:169], v[202:205], v[46:49]
	v_mfma_f32_16x16x32_bf16 v[42:45], v[174:177], v[202:205], v[42:45]
	v_mfma_f32_16x16x32_bf16 v[38:41], v[166:169], v[216:219], v[38:41]
	v_mfma_f32_16x16x32_bf16 v[34:37], v[174:177], v[216:219], v[34:37]
	v_mfma_f32_16x16x32_bf16 v[62:65], v[170:173], v[186:189], v[62:65]
	v_mfma_f32_16x16x32_bf16 v[58:61], v[178:181], v[186:189], v[58:61]
	v_mfma_f32_16x16x32_bf16 v[54:57], v[170:173], v[194:197], v[54:57]
	v_mfma_f32_16x16x32_bf16 v[50:53], v[178:181], v[194:197], v[50:53]
	v_mfma_f32_16x16x32_bf16 v[46:49], v[170:173], v[206:209], v[46:49]
	v_mfma_f32_16x16x32_bf16 v[42:45], v[178:181], v[206:209], v[42:45]
	v_mfma_f32_16x16x32_bf16 v[38:41], v[170:173], v[222:225], v[38:41]
	v_mfma_f32_16x16x32_bf16 v[34:37], v[178:181], v[222:225], v[34:37]
	v_mfma_f32_16x16x32_bf16 v[30:33], v[228:231], v[182:185], v[30:33]
	v_mfma_f32_16x16x32_bf16 v[26:29], v[236:239], v[182:185], v[26:29]
	v_mfma_f32_16x16x32_bf16 v[22:25], v[228:231], v[190:193], v[22:25]
	v_mfma_f32_16x16x32_bf16 v[18:21], v[236:239], v[190:193], v[18:21]
	v_mfma_f32_16x16x32_bf16 v[14:17], v[228:231], v[202:205], v[14:17]
	v_mfma_f32_16x16x32_bf16 v[10:13], v[236:239], v[202:205], v[10:13]
	v_mfma_f32_16x16x32_bf16 v[6:9], v[228:231], v[216:219], v[6:9]
	v_mfma_f32_16x16x32_bf16 v[2:5], v[236:239], v[216:219], v[2:5]
	v_mfma_f32_16x16x32_bf16 v[30:33], v[232:235], v[186:189], v[30:33]
	v_mfma_f32_16x16x32_bf16 v[26:29], v[240:243], v[186:189], v[26:29]
	v_mfma_f32_16x16x32_bf16 v[22:25], v[232:235], v[194:197], v[22:25]
	v_mfma_f32_16x16x32_bf16 v[18:21], v[240:243], v[194:197], v[18:21]
	v_mfma_f32_16x16x32_bf16 v[14:17], v[232:235], v[206:209], v[14:17]
	v_mfma_f32_16x16x32_bf16 v[10:13], v[240:243], v[206:209], v[10:13]
	v_mfma_f32_16x16x32_bf16 v[6:9], v[232:235], v[222:225], v[6:9]
	v_mfma_f32_16x16x32_bf16 v[2:5], v[240:243], v[222:225], v[2:5]
	s_barrier
	ds_read_b128 v[166:169], v154
	ds_read_b128 v[170:173], v154 offset:1024
	ds_read_b128 v[174:177], v154 offset:2048
	ds_read_b128 v[178:181], v154 offset:3072
	ds_read_b128 v[182:185], v150 offset:32768
	ds_read_b128 v[186:189], v150 offset:33792
	ds_read_b128 v[190:193], v149 offset:32768
	ds_read_b128 v[194:197], v149 offset:33792
	ds_read_b128 v[202:205], v148 offset:32768
	ds_read_b128 v[206:209], v148 offset:33792
	ds_read_b128 v[216:219], v147 offset:32768
	ds_read_b128 v[222:225], v147 offset:33792
	s_waitcnt lgkmcnt(6)
	ds_read_b128 v[228:231], v151
	ds_read_b128 v[232:235], v151 offset:1024
	ds_read_b128 v[236:239], v151 offset:2048
	ds_read_b128 v[240:243], v151 offset:3072
	s_add_u32 s2, s41, s2
	s_addc_u32 s3, s44, s3
	v_lshl_add_u64 v[248:249], s[2:3], 0, v[130:131]
	v_readfirstlane_b32 s26, v135
	s_add_u32 s2, s2, s53
	s_mov_b32 m0, s26
	s_addc_u32 s3, s3, 0
	global_load_lds_dwordx4 v[248:249], off
	v_lshl_add_u64 v[248:249], s[2:3], 0, v[130:131]
	v_readfirstlane_b32 s2, v134
	s_mov_b32 m0, s2
	s_nop 0
	global_load_lds_dwordx4 v[248:249], off
	s_waitcnt vmcnt(8)
	s_barrier
	s_waitcnt lgkmcnt(0)
	v_mfma_f32_16x16x32_bf16 v[126:129], v[166:169], v[182:185], v[126:129]
	v_mfma_f32_16x16x32_bf16 v[122:125], v[174:177], v[182:185], v[122:125]
	v_mfma_f32_16x16x32_bf16 v[118:121], v[166:169], v[190:193], v[118:121]
	v_mfma_f32_16x16x32_bf16 v[114:117], v[174:177], v[190:193], v[114:117]
	v_mfma_f32_16x16x32_bf16 v[110:113], v[166:169], v[202:205], v[110:113]
	v_mfma_f32_16x16x32_bf16 v[106:109], v[174:177], v[202:205], v[106:109]
	v_mfma_f32_16x16x32_bf16 v[102:105], v[166:169], v[216:219], v[102:105]
	v_mfma_f32_16x16x32_bf16 v[98:101], v[174:177], v[216:219], v[98:101]
	v_mfma_f32_16x16x32_bf16 v[126:129], v[170:173], v[186:189], v[126:129]
	v_mfma_f32_16x16x32_bf16 v[122:125], v[178:181], v[186:189], v[122:125]
	v_mfma_f32_16x16x32_bf16 v[118:121], v[170:173], v[194:197], v[118:121]
	v_mfma_f32_16x16x32_bf16 v[114:117], v[178:181], v[194:197], v[114:117]
	v_mfma_f32_16x16x32_bf16 v[110:113], v[170:173], v[206:209], v[110:113]
	v_mfma_f32_16x16x32_bf16 v[106:109], v[178:181], v[206:209], v[106:109]
	v_mfma_f32_16x16x32_bf16 v[102:105], v[170:173], v[222:225], v[102:105]
	v_mfma_f32_16x16x32_bf16 v[98:101], v[178:181], v[222:225], v[98:101]
	v_mfma_f32_16x16x32_bf16 v[94:97], v[228:231], v[182:185], v[94:97]
	v_mfma_f32_16x16x32_bf16 v[90:93], v[236:239], v[182:185], v[90:93]
	v_mfma_f32_16x16x32_bf16 v[86:89], v[228:231], v[190:193], v[86:89]
	v_mfma_f32_16x16x32_bf16 v[82:85], v[236:239], v[190:193], v[82:85]
	v_mfma_f32_16x16x32_bf16 v[78:81], v[228:231], v[202:205], v[78:81]
	v_mfma_f32_16x16x32_bf16 v[74:77], v[236:239], v[202:205], v[74:77]
	v_mfma_f32_16x16x32_bf16 v[70:73], v[228:231], v[216:219], v[70:73]
	v_mfma_f32_16x16x32_bf16 v[66:69], v[236:239], v[216:219], v[66:69]
	v_mfma_f32_16x16x32_bf16 v[94:97], v[232:235], v[186:189], v[94:97]
	v_mfma_f32_16x16x32_bf16 v[90:93], v[240:243], v[186:189], v[90:93]
	v_mfma_f32_16x16x32_bf16 v[86:89], v[232:235], v[194:197], v[86:89]
	v_mfma_f32_16x16x32_bf16 v[82:85], v[240:243], v[194:197], v[82:85]
	v_mfma_f32_16x16x32_bf16 v[78:81], v[232:235], v[206:209], v[78:81]
	v_mfma_f32_16x16x32_bf16 v[74:77], v[240:243], v[206:209], v[74:77]
	v_mfma_f32_16x16x32_bf16 v[70:73], v[232:235], v[222:225], v[70:73]
	v_mfma_f32_16x16x32_bf16 v[66:69], v[240:243], v[222:225], v[66:69]
	s_barrier
; #define STAGE_B(P, br, kt) do { const char* _gb = (const char*)(Bt + ((long)(br) * K + (long)(kt) * BK)); \
;     __builtin_amdgcn_global_load_lds((const unsigned*)(_gb + bofl0), (unsigned*)((char*)(P) + gtid_ * 16), 16, 0, 0); \
;     __builtin_amdgcn_global_load_lds((const unsigned*)(_gb + (long)K * 128 + bofl0), (unsigned*)((char*)(P) + gtid_ * 16 + 8192), 16, 0, 0); } while (0)
; #define LDA(dst, b, h) for (int m = 0; m < 4; ++m) for (int k = 0; k < 2; ++k) \
;     dst[m][k] = *reinterpret_cast<const bf16x8*>((char*)SA(b, h) + lds_byte(wr * 64 + m * 16 + fr, k * 32 + fq * 8))
; #define LDB(dst, b, h) for (int n = 0; n < 2; ++n) for (int k = 0; k < 2; ++k) \
;     dst[n][k] = *reinterpret_cast<const bf16x8*>((char*)SB(b, h) + lds_byte(wc * 32 + n * 16 + fr, k * 32 + fq * 8))
; #define MMA(ai, bj, At_, Bt_) do { __builtin_amdgcn_s_setprio(1); \
;     for (int m = 0; m < 4; ++m) for (int n = 0; n < 2; ++n) for (int k = 0; k < 2; ++k) \
;       acc[ai][bj][m][n] = __builtin_amdgcn_mfma_f32_16x16x32_bf16(At_[m][k], Bt_[n][k], acc[ai][bj][m][n], 0, 0, 0); \
;     __builtin_amdgcn_s_setprio(0); } while (0)
; #define WAIT_V(n) asm volatile("s_waitcnt vmcnt(" #n ")" ::: "memory")
; #define WAIT_L(n) asm volatile("s_waitcnt lgkmcnt(" #n ")" ::: "memory")
; #define BAR __builtin_amdgcn_s_barrier()
; #define SCHED __builtin_amdgcn_sched_barrier(0)
; template <int EPI>
; __device__ __forceinline__ void gemm_tile(const GemmArgs& g, int brow, int bcol, int parity, bool first, bool nvalid, int nbrow, int nbcol) {
;     ...
;     LDA(At, 1, 1); STAGE_A(SA(1, 0), brow, t + 3);
;     BAR; WAIT_L(0); MMA(1, 0, At, B0); BAR; SCHED;
;     STAGE_B(SB(1, 1), bcol + HALF, t + 3);
;     WAIT_V(6); BAR; MMA(1, 1, At, B1); BAR; SCHED;
;   }
;   { LDB(B0, 0, 0); LDA(At, 0, 0); STAGE_A(SA(1, 1), brow + HALF, nt - 1);
;     BAR; WAIT_L(0); MMA(0, 0, At, B0); BAR;
;     LDB(B1, 0, 1); BAR; WAIT_L(0); MMA(0, 1, At, B1); BAR; SCHED;
;     LDA(At, 0, 1); WAIT_V(4); BAR; WAIT_L(0); MMA(1, 0, At, B0); MMA(1, 1, At, B1); BAR; }
;   { LDB(B0, 1, 0); LDA(At, 1, 0); WAIT_V(2); BAR; WAIT_L(0); MMA(0, 0, At, B0); BAR;
	ds_read_b128 v[182:185], v150 offset:49152
	ds_read_b128 v[186:189], v150 offset:50176
	ds_read_b128 v[190:193], v149 offset:49152
	ds_read_b128 v[194:197], v149 offset:50176
	ds_read_b128 v[202:205], v148 offset:49152
	ds_read_b128 v[206:209], v148 offset:50176
	ds_read_b128 v[216:219], v147 offset:49152
	ds_read_b128 v[222:225], v147 offset:50176
	v_readfirstlane_b32 s2, v152
	v_lshl_add_u64 v[198:199], v[198:199], 0, s[58:59]
	s_mov_b32 m0, s2
	v_readfirstlane_b32 s2, v153
	global_load_lds_dwordx4 v[198:199], off
	v_lshl_add_u64 v[198:199], v[210:211], 0, s[58:59]
	s_mov_b32 m0, s2
	s_nop 0
	global_load_lds_dwordx4 v[198:199], off
	s_cmp_lt_u32 s61, s35
	s_cselect_b32 s2, s36, s57
	s_add_i32 s2, s2, s61
	s_ashr_i32 s3, s2, 31
	s_lshl_b64 s[2:3], s[2:3], 1
	s_add_u32 s2, s25, s2
	s_addc_u32 s3, s39, s3
	v_lshl_add_u64 v[198:199], s[2:3], 0, v[130:131]
	v_readfirstlane_b32 s26, v155
	s_add_u32 s2, s2, s53
	s_mov_b32 m0, s26
	s_addc_u32 s3, s3, 0
	global_load_lds_dwordx4 v[198:199], off
	v_lshl_add_u64 v[198:199], s[2:3], 0, v[130:131]
	v_readfirstlane_b32 s2, v156
	s_mov_b32 m0, s2
	s_nop 0
	global_load_lds_dwordx4 v[198:199], off
	v_readfirstlane_b32 s2, v157
	v_lshl_add_u64 v[246:247], v[212:213], 0, s[58:59]
	s_mov_b32 m0, s2
	v_readfirstlane_b32 s2, v158
	global_load_lds_dwordx4 v[246:247], off
	v_lshl_add_u64 v[246:247], v[244:245], 0, s[58:59]
	s_mov_b32 m0, s2
	s_nop 0
	global_load_lds_dwordx4 v[246:247], off
	s_waitcnt vmcnt(8)
	s_barrier
	s_waitcnt lgkmcnt(0)
	v_mfma_f32_16x16x32_bf16 v[62:65], v[166:169], v[182:185], v[62:65]
	v_mfma_f32_16x16x32_bf16 v[58:61], v[174:177], v[182:185], v[58:61]
	v_mfma_f32_16x16x32_bf16 v[54:57], v[166:169], v[190:193], v[54:57]
	v_mfma_f32_16x16x32_bf16 v[50:53], v[174:177], v[190:193], v[50:53]
	v_mfma_f32_16x16x32_bf16 v[46:49], v[166:169], v[202:205], v[46:49]
	v_mfma_f32_16x16x32_bf16 v[42:45], v[174:177], v[202:205], v[42:45]
	v_mfma_f32_16x16x32_bf16 v[38:41], v[166:169], v[216:219], v[38:41]
	v_mfma_f32_16x16x32_bf16 v[34:37], v[174:177], v[216:219], v[34:37]
	v_mfma_f32_16x16x32_bf16 v[62:65], v[170:173], v[186:189], v[62:65]
	v_mfma_f32_16x16x32_bf16 v[58:61], v[178:181], v[186:189], v[58:61]
	v_mfma_f32_16x16x32_bf16 v[54:57], v[170:173], v[194:197], v[54:57]
	v_mfma_f32_16x16x32_bf16 v[50:53], v[178:181], v[194:197], v[50:53]
	v_mfma_f32_16x16x32_bf16 v[46:49], v[170:173], v[206:209], v[46:49]
	v_mfma_f32_16x16x32_bf16 v[42:45], v[178:181], v[206:209], v[42:45]
	v_mfma_f32_16x16x32_bf16 v[38:41], v[170:173], v[222:225], v[38:41]
	v_mfma_f32_16x16x32_bf16 v[34:37], v[178:181], v[222:225], v[34:37]
	v_mfma_f32_16x16x32_bf16 v[30:33], v[228:231], v[182:185], v[30:33]
	v_mfma_f32_16x16x32_bf16 v[26:29], v[236:239], v[182:185], v[26:29]
	v_mfma_f32_16x16x32_bf16 v[22:25], v[228:231], v[190:193], v[22:25]
	v_mfma_f32_16x16x32_bf16 v[18:21], v[236:239], v[190:193], v[18:21]
	v_mfma_f32_16x16x32_bf16 v[14:17], v[228:231], v[202:205], v[14:17]
	v_mfma_f32_16x16x32_bf16 v[10:13], v[236:239], v[202:205], v[10:13]
	v_mfma_f32_16x16x32_bf16 v[6:9], v[228:231], v[216:219], v[6:9]
	v_mfma_f32_16x16x32_bf16 v[2:5], v[236:239], v[216:219], v[2:5]
	v_mfma_f32_16x16x32_bf16 v[30:33], v[232:235], v[186:189], v[30:33]
	v_mfma_f32_16x16x32_bf16 v[26:29], v[240:243], v[186:189], v[26:29]
	v_mfma_f32_16x16x32_bf16 v[22:25], v[232:235], v[194:197], v[22:25]
	v_mfma_f32_16x16x32_bf16 v[18:21], v[240:243], v[194:197], v[18:21]
	v_mfma_f32_16x16x32_bf16 v[14:17], v[232:235], v[206:209], v[14:17]
	v_mfma_f32_16x16x32_bf16 v[10:13], v[240:243], v[206:209], v[10:13]
	v_mfma_f32_16x16x32_bf16 v[6:9], v[232:235], v[222:225], v[6:9]
	v_mfma_f32_16x16x32_bf16 v[2:5], v[240:243], v[222:225], v[2:5]
	s_barrier
	s_addk_i32 s61, 0x80
	s_add_u32 s14, s14, 0x100
	s_addc_u32 s15, s15, 0
	s_add_u32 s18, s18, 0x100
	s_addc_u32 s19, s19, 0
	s_add_u32 s20, s20, 0x100
	s_addc_u32 s21, s21, 0
	s_add_u32 s22, s22, 0x100
	s_addc_u32 s23, s23, 0
	s_cmp_lt_i32 s45, s56
	s_cbranch_scc1 .LBB0_191
	s_add_u32 s2, s76, s12
	s_addc_u32 s3, s77, s13
	s_movk_i32 s14, 0xff80
	v_lshl_add_u64 v[132:133], s[2:3], 0, v[130:131]
	s_mov_b32 s15, -1
	v_readfirstlane_b32 s12, v165
	s_add_u32 s2, s2, s53
	v_lshl_add_u64 v[132:133], v[132:133], 0, s[14:15]
	s_mov_b32 m0, s12
	s_addc_u32 s3, s3, 0
	ds_read_b128 v[166:169], v160
	ds_read_b128 v[170:173], v160 offset:1024
	ds_read_b128 v[174:177], v160 offset:2048
	ds_read_b128 v[178:181], v160 offset:3072
	ds_read_b128 v[182:185], v150
	ds_read_b128 v[186:189], v150 offset:1024
	ds_read_b128 v[190:193], v149
	ds_read_b128 v[194:197], v149 offset:1024
	ds_read_b128 v[202:205], v148
	ds_read_b128 v[206:209], v148 offset:1024
	ds_read_b128 v[216:219], v147
	ds_read_b128 v[222:225], v147 offset:1024
	global_load_lds_dwordx4 v[132:133], off
	v_lshl_add_u64 v[132:133], s[2:3], 0, v[130:131]
	v_readfirstlane_b32 s2, v164
	v_lshl_add_u64 v[132:133], v[132:133], 0, s[14:15]
	s_mov_b32 m0, s2
	s_nop 0
	global_load_lds_dwordx4 v[132:133], off
	s_waitcnt vmcnt(8)
	s_barrier
	s_waitcnt lgkmcnt(0)
	s_setprio 1
	s_waitcnt lgkmcnt(0)
	v_mfma_f32_16x16x32_bf16 v[126:129], v[166:169], v[182:185], v[126:129]
	v_mfma_f32_16x16x32_bf16 v[122:125], v[174:177], v[182:185], v[122:125]
	v_mfma_f32_16x16x32_bf16 v[118:121], v[166:169], v[190:193], v[118:121]
	v_mfma_f32_16x16x32_bf16 v[106:109], v[174:177], v[202:205], v[106:109]
	v_mfma_f32_16x16x32_bf16 v[126:129], v[170:173], v[186:189], v[126:129]
	v_mfma_f32_16x16x32_bf16 v[122:125], v[178:181], v[186:189], v[122:125]
	v_mfma_f32_16x16x32_bf16 v[118:121], v[170:173], v[194:197], v[118:121]
	v_mfma_f32_16x16x32_bf16 v[114:117], v[174:177], v[190:193], v[114:117]
	v_mfma_f32_16x16x32_bf16 v[110:113], v[166:169], v[202:205], v[110:113]
	v_mfma_f32_16x16x32_bf16 v[106:109], v[178:181], v[206:209], v[106:109]
	v_mfma_f32_16x16x32_bf16 v[102:105], v[166:169], v[216:219], v[102:105]
	v_mfma_f32_16x16x32_bf16 v[98:101], v[174:177], v[216:219], v[98:101]
	v_mfma_f32_16x16x32_bf16 v[228:231], v[178:181], v[194:197], v[114:117]
	v_mfma_f32_16x16x32_bf16 v[232:235], v[170:173], v[206:209], v[110:113]
	v_mfma_f32_16x16x32_bf16 v[236:239], v[170:173], v[222:225], v[102:105]
	v_mfma_f32_16x16x32_bf16 v[240:243], v[178:181], v[222:225], v[98:101]
	s_setprio 0
	s_barrier
; #define LDA(dst, b, h) for (int m = 0; m < 4; ++m) for (int k = 0; k < 2; ++k) \
;     dst[m][k] = *reinterpret_cast<const bf16x8*>((char*)SA(b, h) + lds_byte(wr * 64 + m * 16 + fr, k * 32 + fq * 8))
; #define LDB(dst, b, h) for (int n = 0; n < 2; ++n) for (int k = 0; k < 2; ++k) \
;     dst[n][k] = *reinterpret_cast<const bf16x8*>((char*)SB(b, h) + lds_byte(wc * 32 + n * 16 + fr, k * 32 + fq * 8))
; #define MMA(ai, bj, At_, Bt_) do { __builtin_amdgcn_s_setprio(1); \
;     for (int m = 0; m < 4; ++m) for (int n = 0; n < 2; ++n) for (int k = 0; k < 2; ++k) \
;       acc[ai][bj][m][n] = __builtin_amdgcn_mfma_f32_16x16x32_bf16(At_[m][k], Bt_[n][k], acc[ai][bj][m][n], 0, 0, 0); \
;     __builtin_amdgcn_s_setprio(0); } while (0)
; #define WAIT_V(n) asm volatile("s_waitcnt vmcnt(" #n ")" ::: "memory")
; #define WAIT_L(n) asm volatile("s_waitcnt lgkmcnt(" #n ")" ::: "memory")
; #define BAR __builtin_amdgcn_s_barrier()
; #define SCHED __builtin_amdgcn_sched_barrier(0)
; template <int EPI>
; __device__ __forceinline__ void gemm_tile(const GemmArgs& g, int brow, int bcol, int parity, bool first, bool nvalid, int nbrow, int nbcol) {
;     ...
;   { LDB(B0, 0, 0); LDA(At, 0, 0); STAGE_A(SA(1, 1), brow + HALF, nt - 1);
;     BAR; WAIT_L(0); MMA(0, 0, At, B0); BAR;
;     LDB(B1, 0, 1); BAR; WAIT_L(0); MMA(0, 1, At, B1); BAR; SCHED;
;     LDA(At, 0, 1); WAIT_V(4); BAR; WAIT_L(0); MMA(1, 0, At, B0); MMA(1, 1, At, B1); BAR; }
;   { LDB(B0, 1, 0); LDA(At, 1, 0); WAIT_V(2); BAR; WAIT_L(0); MMA(0, 0, At, B0); BAR;
	s_nop 1
	ds_read_b128 v[98:101], v159
	ds_read_b128 v[102:105], v159 offset:1024
	ds_read_b128 v[110:113], v159 offset:2048
	ds_read_b128 v[114:117], v159 offset:3072
	s_barrier
	s_waitcnt lgkmcnt(0)
	s_setprio 1
	s_waitcnt lgkmcnt(0)
	v_mfma_f32_16x16x32_bf16 v[94:97], v[98:101], v[182:185], v[94:97]
	v_mfma_f32_16x16x32_bf16 v[90:93], v[110:113], v[182:185], v[90:93]
	v_mfma_f32_16x16x32_bf16 v[86:89], v[98:101], v[190:193], v[86:89]
	v_mfma_f32_16x16x32_bf16 v[78:81], v[98:101], v[202:205], v[78:81]
	v_mfma_f32_16x16x32_bf16 v[94:97], v[102:105], v[186:189], v[94:97]
	v_mfma_f32_16x16x32_bf16 v[90:93], v[114:117], v[186:189], v[90:93]
	v_mfma_f32_16x16x32_bf16 v[86:89], v[102:105], v[194:197], v[86:89]
	v_mfma_f32_16x16x32_bf16 v[82:85], v[110:113], v[190:193], v[82:85]
	v_mfma_f32_16x16x32_bf16 v[78:81], v[102:105], v[206:209], v[78:81]
	v_mfma_f32_16x16x32_bf16 v[74:77], v[110:113], v[202:205], v[74:77]
	v_mfma_f32_16x16x32_bf16 v[70:73], v[98:101], v[216:219], v[70:73]
	v_mfma_f32_16x16x32_bf16 v[66:69], v[110:113], v[216:219], v[66:69]
	v_mfma_f32_16x16x32_bf16 v[156:159], v[114:117], v[194:197], v[82:85]
	v_mfma_f32_16x16x32_bf16 v[182:185], v[114:117], v[206:209], v[74:77]
	v_mfma_f32_16x16x32_bf16 v[186:189], v[102:105], v[222:225], v[70:73]
	v_mfma_f32_16x16x32_bf16 v[190:193], v[114:117], v[222:225], v[66:69]
	s_setprio 0
	s_barrier
	s_nop 1
	ds_read_b128 v[66:69], v150 offset:16384
	ds_read_b128 v[70:73], v150 offset:17408
	ds_read_b128 v[74:77], v149 offset:16384
	ds_read_b128 v[82:85], v149 offset:17408
	ds_read_b128 v[194:197], v148 offset:16384
	ds_read_b128 v[202:205], v148 offset:17408
	ds_read_b128 v[206:209], v147 offset:16384
	ds_read_b128 v[216:219], v147 offset:17408
	s_waitcnt vmcnt(4)
	s_barrier
	s_waitcnt lgkmcnt(0)
	s_setprio 1
	s_waitcnt lgkmcnt(0)
	v_mfma_f32_16x16x32_bf16 v[62:65], v[166:169], v[66:69], v[62:65]
	v_mfma_f32_16x16x32_bf16 v[58:61], v[174:177], v[66:69], v[58:61]
	v_mfma_f32_16x16x32_bf16 v[54:57], v[166:169], v[74:77], v[54:57]
	v_mfma_f32_16x16x32_bf16 v[46:49], v[166:169], v[194:197], v[46:49]
	v_mfma_f32_16x16x32_bf16 v[62:65], v[170:173], v[70:73], v[62:65]
	v_mfma_f32_16x16x32_bf16 v[58:61], v[178:181], v[70:73], v[58:61]
	v_mfma_f32_16x16x32_bf16 v[54:57], v[170:173], v[82:85], v[54:57]
	v_mfma_f32_16x16x32_bf16 v[50:53], v[174:177], v[74:77], v[50:53]
	v_mfma_f32_16x16x32_bf16 v[46:49], v[170:173], v[202:205], v[46:49]
	v_mfma_f32_16x16x32_bf16 v[42:45], v[174:177], v[194:197], v[42:45]
	v_mfma_f32_16x16x32_bf16 v[38:41], v[166:169], v[206:209], v[38:41]
	v_mfma_f32_16x16x32_bf16 v[34:37], v[174:177], v[206:209], v[34:37]
	v_mfma_f32_16x16x32_bf16 v[222:225], v[178:181], v[82:85], v[50:53]
	v_mfma_f32_16x16x32_bf16 v[244:247], v[178:181], v[202:205], v[42:45]
	v_mfma_f32_16x16x32_bf16 v[164:167], v[170:173], v[216:219], v[38:41]
	v_mfma_f32_16x16x32_bf16 v[168:171], v[178:181], v[216:219], v[34:37]
	s_setprio 0
	s_setprio 1
	v_mfma_f32_16x16x32_bf16 v[30:33], v[98:101], v[66:69], v[30:33]
	v_mfma_f32_16x16x32_bf16 v[26:29], v[110:113], v[66:69], v[26:29]
	v_mfma_f32_16x16x32_bf16 v[22:25], v[98:101], v[74:77], v[22:25]
	v_mfma_f32_16x16x32_bf16 v[14:17], v[98:101], v[194:197], v[14:17]
	v_mfma_f32_16x16x32_bf16 v[30:33], v[102:105], v[70:73], v[30:33]
	v_mfma_f32_16x16x32_bf16 v[26:29], v[114:117], v[70:73], v[26:29]
	v_mfma_f32_16x16x32_bf16 v[22:25], v[102:105], v[82:85], v[22:25]
	v_mfma_f32_16x16x32_bf16 v[18:21], v[110:113], v[74:77], v[18:21]
	v_mfma_f32_16x16x32_bf16 v[14:17], v[102:105], v[202:205], v[14:17]
	v_mfma_f32_16x16x32_bf16 v[10:13], v[110:113], v[194:197], v[10:13]
	v_mfma_f32_16x16x32_bf16 v[6:9], v[98:101], v[206:209], v[6:9]
	v_mfma_f32_16x16x32_bf16 v[2:5], v[110:113], v[206:209], v[2:5]
	v_mfma_f32_16x16x32_bf16 v[172:175], v[114:117], v[82:85], v[18:21]
	v_mfma_f32_16x16x32_bf16 v[176:179], v[114:117], v[202:205], v[10:13]
	v_mfma_f32_16x16x32_bf16 v[194:197], v[102:105], v[216:219], v[6:9]
	v_mfma_f32_16x16x32_bf16 v[202:205], v[114:117], v[216:219], v[2:5]
	s_setprio 0
	s_barrier
	s_nop 1
	ds_read_b128 v[2:5], v154
	ds_read_b128 v[6:9], v154 offset:1024
	ds_read_b128 v[10:13], v154 offset:2048
	ds_read_b128 v[18:21], v154 offset:3072
	ds_read_b128 v[34:37], v150 offset:32768
	ds_read_b128 v[38:41], v150 offset:33792
	ds_read_b128 v[42:45], v149 offset:32768
	ds_read_b128 v[50:53], v149 offset:33792
	ds_read_b128 v[152:155], v148 offset:32768
	ds_read_b128 v[206:209], v148 offset:33792
	ds_read_b128 v[216:219], v147 offset:32768
	ds_read_b128 v[248:251], v147 offset:33792
	s_waitcnt vmcnt(2)
	s_barrier
; #define LDA(dst, b, h) for (int m = 0; m < 4; ++m) for (int k = 0; k < 2; ++k) \
;     dst[m][k] = *reinterpret_cast<const bf16x8*>((char*)SA(b, h) + lds_byte(wr * 64 + m * 16 + fr, k * 32 + fq * 8))
; #define LDB(dst, b, h) for (int n = 0; n < 2; ++n) for (int k = 0; k < 2; ++k) \
;     dst[n][k] = *reinterpret_cast<const bf16x8*>((char*)SB(b, h) + lds_byte(wc * 32 + n * 16 + fr, k * 32 + fq * 8))
; #define MMA(ai, bj, At_, Bt_) do { __builtin_amdgcn_s_setprio(1); \
;     for (int m = 0; m < 4; ++m) for (int n = 0; n < 2; ++n) for (int k = 0; k < 2; ++k) \
;       acc[ai][bj][m][n] = __builtin_amdgcn_mfma_f32_16x16x32_bf16(At_[m][k], Bt_[n][k], acc[ai][bj][m][n], 0, 0, 0); \
;     __builtin_amdgcn_s_setprio(0); } while (0)
; #define WAIT_V(n) asm volatile("s_waitcnt vmcnt(" #n ")" ::: "memory")
; #define WAIT_L(n) asm volatile("s_waitcnt lgkmcnt(" #n ")" ::: "memory")
; #define BAR __builtin_amdgcn_s_barrier()
; #define SCHED __builtin_amdgcn_sched_barrier(0)
; template <int EPI>
; __device__ __forceinline__ void gemm_tile(const GemmArgs& g, int brow, int bcol, int parity, bool first, bool nvalid, int nbrow, int nbcol) {
;     ...
;     LDA(At, 0, 1); WAIT_V(4); BAR; WAIT_L(0); MMA(1, 0, At, B0); MMA(1, 1, At, B1); BAR; }
;   { LDB(B0, 1, 0); LDA(At, 1, 0); WAIT_V(2); BAR; WAIT_L(0); MMA(0, 0, At, B0); BAR;
;     LDB(B1, 1, 1); WAIT_V(0); BAR; WAIT_L(0); MMA(0, 1, At, B1); BAR; SCHED;
;     LDA(At, 1, 1); BAR; WAIT_L(0); MMA(1, 0, At, B0); MMA(1, 1, At, B1); BAR; }
;   if (wr == 0) BAR;
	s_waitcnt lgkmcnt(0)
	s_setprio 1
	s_waitcnt lgkmcnt(0)
	v_mfma_f32_16x16x32_bf16 v[66:69], v[2:5], v[34:37], v[126:129]
	v_mfma_f32_16x16x32_bf16 v[114:117], v[6:9], v[38:41], v[66:69]
	v_mfma_f32_16x16x32_bf16 v[66:69], v[10:13], v[34:37], v[122:125]
	v_mfma_f32_16x16x32_bf16 v[126:129], v[18:21], v[38:41], v[66:69]
	v_mfma_f32_16x16x32_bf16 v[66:69], v[2:5], v[42:45], v[118:121]
	v_mfma_f32_16x16x32_bf16 v[110:113], v[6:9], v[50:53], v[66:69]
	v_mfma_f32_16x16x32_bf16 v[66:69], v[10:13], v[42:45], v[228:231]
	v_mfma_f32_16x16x32_bf16 v[122:125], v[18:21], v[50:53], v[66:69]
	v_mfma_f32_16x16x32_bf16 v[66:69], v[2:5], v[152:155], v[232:235]
	v_mfma_f32_16x16x32_bf16 v[102:105], v[6:9], v[206:209], v[66:69]
	v_mfma_f32_16x16x32_bf16 v[66:69], v[10:13], v[152:155], v[106:109]
	v_mfma_f32_16x16x32_bf16 v[118:121], v[18:21], v[206:209], v[66:69]
	v_mfma_f32_16x16x32_bf16 v[66:69], v[2:5], v[216:219], v[236:239]
	v_mfma_f32_16x16x32_bf16 v[98:101], v[6:9], v[248:251], v[66:69]
	v_mfma_f32_16x16x32_bf16 v[66:69], v[10:13], v[216:219], v[240:243]
	v_mfma_f32_16x16x32_bf16 v[106:109], v[18:21], v[248:251], v[66:69]
	s_setprio 0
	s_barrier
	ds_read_b128 v[228:231], v151
	ds_read_b128 v[232:235], v151 offset:1024
	ds_read_b128 v[236:239], v151 offset:2048
	ds_read_b128 v[240:243], v151 offset:3072
	s_waitcnt vmcnt(0)
	s_barrier
	s_waitcnt lgkmcnt(0)
	s_setprio 1
	s_waitcnt lgkmcnt(0)
	v_mfma_f32_16x16x32_bf16 v[66:69], v[228:231], v[34:37], v[94:97]
	v_mfma_f32_16x16x32_bf16 v[34:37], v[236:239], v[34:37], v[90:93]
	v_mfma_f32_16x16x32_bf16 v[82:85], v[240:243], v[38:41], v[34:37]
	v_mfma_f32_16x16x32_bf16 v[34:37], v[228:231], v[42:45], v[86:89]
	v_mfma_f32_16x16x32_bf16 v[70:73], v[232:235], v[50:53], v[34:37]
	v_mfma_f32_16x16x32_bf16 v[34:37], v[236:239], v[42:45], v[156:159]
	v_mfma_f32_16x16x32_bf16 v[86:89], v[240:243], v[50:53], v[34:37]
	v_mfma_f32_16x16x32_bf16 v[34:37], v[228:231], v[152:155], v[78:81]
	v_mfma_f32_16x16x32_bf16 v[74:77], v[232:235], v[206:209], v[34:37]
	v_mfma_f32_16x16x32_bf16 v[34:37], v[236:239], v[152:155], v[182:185]
	v_mfma_f32_16x16x32_bf16 v[90:93], v[240:243], v[206:209], v[34:37]
	v_mfma_f32_16x16x32_bf16 v[34:37], v[228:231], v[216:219], v[186:189]
	v_mfma_f32_16x16x32_bf16 v[78:81], v[232:235], v[248:251], v[34:37]
	v_mfma_f32_16x16x32_bf16 v[34:37], v[236:239], v[216:219], v[190:193]
	v_mfma_f32_16x16x32_bf16 v[66:69], v[232:235], v[38:41], v[66:69]
	v_mfma_f32_16x16x32_bf16 v[94:97], v[240:243], v[248:251], v[34:37]
	s_setprio 0
	s_barrier
	ds_read_b128 v[152:155], v150 offset:49152
	ds_read_b128 v[156:159], v150 offset:50176
	ds_read_b128 v[180:183], v149 offset:49152
	ds_read_b128 v[184:187], v149 offset:50176
	ds_read_b128 v[188:191], v148 offset:49152
	ds_read_b128 v[148:151], v148 offset:50176
	ds_read_b128 v[206:209], v147 offset:49152
	ds_read_b128 v[216:219], v147 offset:50176
	s_barrier
	s_waitcnt lgkmcnt(0)
	s_setprio 1
	s_waitcnt lgkmcnt(0)
	v_mfma_f32_16x16x32_bf16 v[38:41], v[10:13], v[152:155], v[58:61]
	v_mfma_f32_16x16x32_bf16 v[42:45], v[10:13], v[180:183], v[222:225]
	v_mfma_f32_16x16x32_bf16 v[34:37], v[2:5], v[152:155], v[62:65]
	v_mfma_f32_16x16x32_bf16 v[50:53], v[18:21], v[156:159], v[38:41]
	v_mfma_f32_16x16x32_bf16 v[38:41], v[2:5], v[180:183], v[54:57]
	v_mfma_f32_16x16x32_bf16 v[54:57], v[18:21], v[184:187], v[42:45]
	v_mfma_f32_16x16x32_bf16 v[42:45], v[2:5], v[188:191], v[46:49]
	v_mfma_f32_16x16x32_bf16 v[46:49], v[10:13], v[188:191], v[244:247]
	v_mfma_f32_16x16x32_bf16 v[2:5], v[2:5], v[206:209], v[164:167]
	v_mfma_f32_16x16x32_bf16 v[58:61], v[18:21], v[148:151], v[46:49]
	v_mfma_f32_16x16x32_bf16 v[46:49], v[6:9], v[216:219], v[2:5]
	v_mfma_f32_16x16x32_bf16 v[2:5], v[10:13], v[206:209], v[168:171]
	v_mfma_f32_16x16x32_bf16 v[34:37], v[6:9], v[156:159], v[34:37]
	v_mfma_f32_16x16x32_bf16 v[38:41], v[6:9], v[184:187], v[38:41]
	v_mfma_f32_16x16x32_bf16 v[42:45], v[6:9], v[148:151], v[42:45]
	v_mfma_f32_16x16x32_bf16 v[62:65], v[18:21], v[216:219], v[2:5]
	s_setprio 0
	s_setprio 1
	v_mfma_f32_16x16x32_bf16 v[6:9], v[236:239], v[152:155], v[26:29]
	v_mfma_f32_16x16x32_bf16 v[10:13], v[236:239], v[180:183], v[172:175]
	v_mfma_f32_16x16x32_bf16 v[18:21], v[240:243], v[156:159], v[6:9]
	v_mfma_f32_16x16x32_bf16 v[6:9], v[228:231], v[180:183], v[22:25]
	v_mfma_f32_16x16x32_bf16 v[22:25], v[240:243], v[184:187], v[10:13]
	v_mfma_f32_16x16x32_bf16 v[10:13], v[228:231], v[188:191], v[14:17]
	v_mfma_f32_16x16x32_bf16 v[14:17], v[236:239], v[188:191], v[176:179]
	v_mfma_f32_16x16x32_bf16 v[2:5], v[228:231], v[152:155], v[30:33]
	v_mfma_f32_16x16x32_bf16 v[26:29], v[240:243], v[148:151], v[14:17]
	v_mfma_f32_16x16x32_bf16 v[14:17], v[228:231], v[206:209], v[194:197]
	v_mfma_f32_16x16x32_bf16 v[30:33], v[236:239], v[206:209], v[202:205]
	v_mfma_f32_16x16x32_bf16 v[2:5], v[232:235], v[156:159], v[2:5]
	v_mfma_f32_16x16x32_bf16 v[6:9], v[232:235], v[184:187], v[6:9]
	v_mfma_f32_16x16x32_bf16 v[10:13], v[232:235], v[148:151], v[10:13]
	v_mfma_f32_16x16x32_bf16 v[14:17], v[232:235], v[216:219], v[14:17]
	v_mfma_f32_16x16x32_bf16 v[30:33], v[240:243], v[216:219], v[30:33]
	s_setprio 0
	s_movk_i32 s2, 0x100
	v_cmp_gt_u32_e32 vcc, s2, v141
	s_barrier
	s_and_saveexec_b64 s[12:13], vcc
	s_cbranch_execz .LBB0_194
	s_barrier

; #define GPTR(T, ptr) ((__attribute__((address_space(1))) T*)(ptr))
; __device__ __forceinline__ unsigned pack2(float a, float b) { return (unsigned)f2bf(a) | ((unsigned)f2bf(b) << 16); }
; #define SCHED __builtin_amdgcn_sched_barrier(0)
; template <int EPI>
; __device__ __forceinline__ void gemm_tile(const GemmArgs& g, int brow, int bcol, int parity, bool first, bool nvalid, int nbrow, int nbcol) {
;     ...
;   int rowb_ = brow + wr * 64 + fq * 4; asm volatile("" : "+v"(rowb_));
;   int colb_ = bcol + wc * 32 + fr; asm volatile("" : "+v"(colb_));
;   float* W = (float*)(smem + ((wid < 3) ? (32768 + wid * 9216) : (98304 + (wid - 3) * 9216)));
;   const int wrow0 = rowb_ - fq * 4;
;   const int wcol0 = colb_ - fr;
;   const int lrow0 = wrow0 - brow;
;     ...
;       _Pragma("unroll") for (int bj = 0; bj < 2; ++bj) {
;         SCHED;
;         _Pragma("unroll") for (int m = 0; m < 4; ++m) _Pragma("unroll") for (int j = 0; j < 4; ++j)
;           _Pragma("unroll") for (int n = 0; n < 2; ++n) W_WRITE(m, n, j, acc[ai][bj][m][n][j]);
;         const long obase = (long)(wrow0 + ai * HALF + (lane >> 3)) * 1024 + wcol0 + bj * HALF + (lane & 7) * 4;
;         if (g.res_bf16) {
;           u32x2 hrv[8];
;           _Pragma("unroll") for (int ps = 0; ps < 8; ++ps) hrv[ps] = *GPTR(const u32x2, g.hb + obase + (long)ps * 8 * 1024);
;           _Pragma("unroll") for (int ps = 0; ps < 8; ++ps) {
;             const int r_ = ps * 8 + (lane >> 3), c_ = (lane & 7) * 4;
;             float4 v = *(const float4*)(W + r_ * 36 + c_);
;             v.x += __uint_as_float(hrv[ps][0] << 16); v.y += __uint_as_float(hrv[ps][0] & 0xffff0000u);
;             v.z += __uint_as_float(hrv[ps][1] << 16); v.w += __uint_as_float(hrv[ps][1] & 0xffff0000u);
;             u32x2 hb2; hb2[0] = pack2(v.x, v.y); hb2[1] = pack2(v.z, v.w);
;             *GPTR(u32x2, g.hb + obase + (long)ps * 8 * 1024) = hb2;
;             ssp[ps] += v.x * v.x + v.y * v.y + v.z * v.z + v.w * v.w;
;           }
.LBB0_196:
	v_mbcnt_lo_u32_b32 v196, -1, 0
	v_mbcnt_hi_u32_b32 v196, -1, v196
	v_and_b32_e32 v197, 15, v196
	v_lshrrev_b32_e32 v198, 4, v196
	s_and_b32 s3, s97, 0x7fffff8
	s_lshl_b32 s3, s3, 5
	s_lshr_b32 s12, s33, 1
	s_and_b32 s12, s12, 0x60
	s_add_i32 s3, s3, s12
	s_lshr_b32 s12, s33, 2
	s_and_b32 s12, s12, 64
	s_add_i32 s12, s12, s38
	v_add_u32_e32 v199, s12, v197
	v_lshlrev_b32_e32 v202, 4, v198
	v_lshlrev_b32_e32 v203, 2, v198
	v_and_b32_e32 v202, 16, v202
	v_and_b32_e32 v203, 8, v203
	v_or_b32_e32 v202, v202, v203
	v_add_lshl_u32 v202, v202, s3, 1
	v_mov_b32_e32 v203, 0
	s_movk_i32 s2, 0x800
	v_mad_u64_u32 v[202:203], vcc, v199, s2, v[202:203]
	v_lshl_add_u64 v[202:203], s[10:11], 0, v[202:203]
	v_add_co_u32_e32 v202, vcc, 0x8200000, v202
	s_nop 1
	v_addc_co_u32_e32 v203, vcc, 0, v203, vcc
	v_lshl_add_u32 v204, v198, 2, s3
	v_lshlrev_b32_e32 v204, 2, v204
	v_mov_b32_e32 v205, 0
	s_movk_i32 s2, 0x1000
	v_mad_u64_u32 v[204:205], vcc, v199, s2, v[204:205]
	v_readlane_b32 s2, v253, 52
	v_readlane_b32 s3, v253, 53
	s_nop 1
	v_lshl_add_u64 v[204:205], s[2:3], 0, v[204:205]
	s_and_b32 s2, s97, 0x7fffff8
	s_lshr_b32 s2, s2, 1
	s_lshr_b32 s3, s33, 6
	s_and_b32 s3, s3, 3
	s_add_i32 s2, s2, s3
	v_lshl_add_u32 v206, v199, 4, s2
	v_lshlrev_b32_e32 v206, 2, v206
	v_mov_b32_e32 v207, 0
	v_lshl_add_u64 v[206:207], s[66:67], 0, v[206:207]
	s_mov_b64 s[12:13], 0x8000
	s_mov_b64 s[14:15], 0x28000
	s_and_b64 vcc, exec, s[42:43]
	s_cbranch_vccz .Lres_f32
	v_mov_b64_e32 v[222:223], v[202:203]
	global_load_dwordx4 v[132:135], v[222:223], off
	global_load_dwordx4 v[136:139], v[222:223], off offset:256
	v_lshl_add_u64 v[222:223], v[222:223], 0, s[12:13]
	global_load_dwordx4 v[140:143], v[222:223], off
	global_load_dwordx4 v[144:147], v[222:223], off offset:256
	v_lshl_add_u64 v[222:223], v[222:223], 0, s[12:13]
	global_load_dwordx4 v[148:151], v[222:223], off
	global_load_dwordx4 v[152:155], v[222:223], off offset:256
	v_lshl_add_u64 v[222:223], v[222:223], 0, s[12:13]
	global_load_dwordx4 v[156:159], v[222:223], off
	global_load_dwordx4 v[160:163], v[222:223], off offset:256
	v_lshl_add_u64 v[222:223], v[222:223], 0, s[14:15]
	global_load_dwordx4 v[164:167], v[222:223], off
	global_load_dwordx4 v[168:171], v[222:223], off offset:256
	v_lshl_add_u64 v[222:223], v[222:223], 0, s[12:13]
	global_load_dwordx4 v[172:175], v[222:223], off
	global_load_dwordx4 v[176:179], v[222:223], off offset:256
	v_lshl_add_u64 v[222:223], v[222:223], 0, s[12:13]
	global_load_dwordx4 v[180:183], v[222:223], off
	global_load_dwordx4 v[184:187], v[222:223], off offset:256
	v_lshl_add_u64 v[222:223], v[222:223], 0, s[12:13]
	global_load_dwordx4 v[188:191], v[222:223], off
	global_load_dwordx4 v[192:195], v[222:223], off offset:256
	s_waitcnt vmcnt(14)
	v_permlane16_swap_b32_e32 v132, v134
	v_permlane16_swap_b32_e32 v133, v135
	v_permlane16_swap_b32_e32 v136, v138
	v_permlane16_swap_b32_e32 v137, v139
	v_lshlrev_b32_e32 v222, 16, v132
	v_and_b32_e32 v223, 0xffff0000, v132
	v_lshlrev_b32_e32 v224, 16, v133
	v_and_b32_e32 v225, 0xffff0000, v133
	v_pk_add_f32 v[114:115], v[114:115], v[222:223]
	v_pk_add_f32 v[116:117], v[116:117], v[224:225]
	v_pk_mul_f32 v[236:237], v[114:115], v[114:115]
	v_pk_fma_f32 v[236:237], v[116:117], v[116:117], v[236:237]
	v_cvt_pk_bf16_f32 v208, v114, v115
	v_cvt_pk_bf16_f32 v209, v116, v117
	v_lshlrev_b32_e32 v222, 16, v134
	v_and_b32_e32 v223, 0xffff0000, v134
	v_lshlrev_b32_e32 v224, 16, v135
	v_and_b32_e32 v225, 0xffff0000, v135
	v_pk_add_f32 v[126:127], v[126:127], v[222:223]
	v_pk_add_f32 v[128:129], v[128:129], v[224:225]
	v_pk_fma_f32 v[236:237], v[126:127], v[126:127], v[236:237]
	v_pk_fma_f32 v[236:237], v[128:129], v[128:129], v[236:237]
	v_cvt_pk_bf16_f32 v210, v126, v127
	v_cvt_pk_bf16_f32 v211, v128, v129
	v_lshlrev_b32_e32 v222, 16, v136
	v_and_b32_e32 v223, 0xffff0000, v136
	v_lshlrev_b32_e32 v224, 16, v137
	v_and_b32_e32 v225, 0xffff0000, v137
	v_pk_add_f32 v[66:67], v[66:67], v[222:223]
	v_pk_add_f32 v[68:69], v[68:69], v[224:225]
	v_pk_fma_f32 v[236:237], v[66:67], v[66:67], v[236:237]
	v_pk_fma_f32 v[236:237], v[68:69], v[68:69], v[236:237]
	v_cvt_pk_bf16_f32 v216, v66, v67
	v_cvt_pk_bf16_f32 v217, v68, v69
	v_lshlrev_b32_e32 v222, 16, v138
	v_and_b32_e32 v223, 0xffff0000, v138
	v_lshlrev_b32_e32 v224, 16, v139
	v_and_b32_e32 v225, 0xffff0000, v139
	v_pk_add_f32 v[82:83], v[82:83], v[222:223]
	v_pk_add_f32 v[84:85], v[84:85], v[224:225]
	v_pk_fma_f32 v[236:237], v[82:83], v[82:83], v[236:237]
	v_pk_fma_f32 v[236:237], v[84:85], v[84:85], v[236:237]
	v_cvt_pk_bf16_f32 v218, v82, v83
	v_cvt_pk_bf16_f32 v219, v84, v85
	v_permlane16_swap_b32_e32 v208, v210
	v_permlane16_swap_b32_e32 v209, v211
	global_store_dwordx4 v[202:203], v[208:211], off
	v_permlane16_swap_b32_e32 v216, v218
	v_permlane16_swap_b32_e32 v217, v219
	global_store_dwordx4 v[202:203], v[216:219], off offset:256
	v_lshl_add_u64 v[202:203], v[202:203], 0, s[12:13]
	s_waitcnt vmcnt(14)
; #define GPTR(T, ptr) ((__attribute__((address_space(1))) T*)(ptr))
; __device__ __forceinline__ unsigned pack2(float a, float b) { return (unsigned)f2bf(a) | ((unsigned)f2bf(b) << 16); }
; template <int EPI>
; __device__ __forceinline__ void gemm_tile(const GemmArgs& g, int brow, int bcol, int parity, bool first, bool nvalid, int nbrow, int nbcol) {
;     ...
;           _Pragma("unroll") for (int ps = 0; ps < 8; ++ps) hrv[ps] = *GPTR(const u32x2, g.hb + obase + (long)ps * 8 * 1024);
;           _Pragma("unroll") for (int ps = 0; ps < 8; ++ps) {
;             const int r_ = ps * 8 + (lane >> 3), c_ = (lane & 7) * 4;
;             float4 v = *(const float4*)(W + r_ * 36 + c_);
;             v.x += __uint_as_float(hrv[ps][0] << 16); v.y += __uint_as_float(hrv[ps][0] & 0xffff0000u);
;             v.z += __uint_as_float(hrv[ps][1] << 16); v.w += __uint_as_float(hrv[ps][1] & 0xffff0000u);
;             u32x2 hb2; hb2[0] = pack2(v.x, v.y); hb2[1] = pack2(v.z, v.w);
;             *GPTR(u32x2, g.hb + obase + (long)ps * 8 * 1024) = hb2;
;             ssp[ps] += v.x * v.x + v.y * v.y + v.z * v.z + v.w * v.w;
;           }
	v_permlane16_swap_b32_e32 v140, v142
	v_permlane16_swap_b32_e32 v141, v143
	v_permlane16_swap_b32_e32 v144, v146
	v_permlane16_swap_b32_e32 v145, v147
	v_lshlrev_b32_e32 v222, 16, v140
	v_and_b32_e32 v223, 0xffff0000, v140
	v_lshlrev_b32_e32 v224, 16, v141
	v_and_b32_e32 v225, 0xffff0000, v141
	v_pk_add_f32 v[110:111], v[110:111], v[222:223]
	v_pk_add_f32 v[112:113], v[112:113], v[224:225]
	v_pk_mul_f32 v[238:239], v[110:111], v[110:111]
	v_pk_fma_f32 v[238:239], v[112:113], v[112:113], v[238:239]
	v_cvt_pk_bf16_f32 v208, v110, v111
	v_cvt_pk_bf16_f32 v209, v112, v113
	v_lshlrev_b32_e32 v222, 16, v142
	v_and_b32_e32 v223, 0xffff0000, v142
	v_lshlrev_b32_e32 v224, 16, v143
	v_and_b32_e32 v225, 0xffff0000, v143
	v_pk_add_f32 v[122:123], v[122:123], v[222:223]
	v_pk_add_f32 v[124:125], v[124:125], v[224:225]
	v_pk_fma_f32 v[238:239], v[122:123], v[122:123], v[238:239]
	v_pk_fma_f32 v[238:239], v[124:125], v[124:125], v[238:239]
	v_cvt_pk_bf16_f32 v210, v122, v123
	v_cvt_pk_bf16_f32 v211, v124, v125
	v_lshlrev_b32_e32 v222, 16, v144
	v_and_b32_e32 v223, 0xffff0000, v144
	v_lshlrev_b32_e32 v224, 16, v145
	v_and_b32_e32 v225, 0xffff0000, v145
	v_pk_add_f32 v[70:71], v[70:71], v[222:223]
	v_pk_add_f32 v[72:73], v[72:73], v[224:225]
	v_pk_fma_f32 v[238:239], v[70:71], v[70:71], v[238:239]
	v_pk_fma_f32 v[238:239], v[72:73], v[72:73], v[238:239]
	v_cvt_pk_bf16_f32 v216, v70, v71
	v_cvt_pk_bf16_f32 v217, v72, v73
	v_lshlrev_b32_e32 v222, 16, v146
	v_and_b32_e32 v223, 0xffff0000, v146
	v_lshlrev_b32_e32 v224, 16, v147
	v_and_b32_e32 v225, 0xffff0000, v147
	v_pk_add_f32 v[86:87], v[86:87], v[222:223]
	v_pk_add_f32 v[88:89], v[88:89], v[224:225]
	v_pk_fma_f32 v[238:239], v[86:87], v[86:87], v[238:239]
	v_pk_fma_f32 v[238:239], v[88:89], v[88:89], v[238:239]
	v_cvt_pk_bf16_f32 v218, v86, v87
	v_cvt_pk_bf16_f32 v219, v88, v89
	v_permlane16_swap_b32_e32 v208, v210
	v_permlane16_swap_b32_e32 v209, v211
	global_store_dwordx4 v[202:203], v[208:211], off
	v_permlane16_swap_b32_e32 v216, v218
	v_permlane16_swap_b32_e32 v217, v219
	global_store_dwordx4 v[202:203], v[216:219], off offset:256
	v_lshl_add_u64 v[202:203], v[202:203], 0, s[12:13]
	s_waitcnt vmcnt(14)
	v_permlane16_swap_b32_e32 v148, v150
	v_permlane16_swap_b32_e32 v149, v151
	v_permlane16_swap_b32_e32 v152, v154
	v_permlane16_swap_b32_e32 v153, v155
	v_lshlrev_b32_e32 v222, 16, v148
	v_and_b32_e32 v223, 0xffff0000, v148
	v_lshlrev_b32_e32 v224, 16, v149
	v_and_b32_e32 v225, 0xffff0000, v149
	v_pk_add_f32 v[102:103], v[102:103], v[222:223]
	v_pk_add_f32 v[104:105], v[104:105], v[224:225]
	v_pk_mul_f32 v[240:241], v[102:103], v[102:103]
	v_pk_fma_f32 v[240:241], v[104:105], v[104:105], v[240:241]
	v_cvt_pk_bf16_f32 v208, v102, v103
	v_cvt_pk_bf16_f32 v209, v104, v105
	v_lshlrev_b32_e32 v222, 16, v150
	v_and_b32_e32 v223, 0xffff0000, v150
	v_lshlrev_b32_e32 v224, 16, v151
	v_and_b32_e32 v225, 0xffff0000, v151
	v_pk_add_f32 v[118:119], v[118:119], v[222:223]
	v_pk_add_f32 v[120:121], v[120:121], v[224:225]
	v_pk_fma_f32 v[240:241], v[118:119], v[118:119], v[240:241]
	v_pk_fma_f32 v[240:241], v[120:121], v[120:121], v[240:241]
	v_cvt_pk_bf16_f32 v210, v118, v119
	v_cvt_pk_bf16_f32 v211, v120, v121
	v_lshlrev_b32_e32 v222, 16, v152
	v_and_b32_e32 v223, 0xffff0000, v152
	v_lshlrev_b32_e32 v224, 16, v153
	v_and_b32_e32 v225, 0xffff0000, v153
	v_pk_add_f32 v[74:75], v[74:75], v[222:223]
	v_pk_add_f32 v[76:77], v[76:77], v[224:225]
	v_pk_fma_f32 v[240:241], v[74:75], v[74:75], v[240:241]
	v_pk_fma_f32 v[240:241], v[76:77], v[76:77], v[240:241]
	v_cvt_pk_bf16_f32 v216, v74, v75
	v_cvt_pk_bf16_f32 v217, v76, v77
	v_lshlrev_b32_e32 v222, 16, v154
	v_and_b32_e32 v223, 0xffff0000, v154
	v_lshlrev_b32_e32 v224, 16, v155
	v_and_b32_e32 v225, 0xffff0000, v155
	v_pk_add_f32 v[90:91], v[90:91], v[222:223]
	v_pk_add_f32 v[92:93], v[92:93], v[224:225]
	v_pk_fma_f32 v[240:241], v[90:91], v[90:91], v[240:241]
	v_pk_fma_f32 v[240:241], v[92:93], v[92:93], v[240:241]
	v_cvt_pk_bf16_f32 v218, v90, v91
	v_cvt_pk_bf16_f32 v219, v92, v93
	v_permlane16_swap_b32_e32 v208, v210
	v_permlane16_swap_b32_e32 v209, v211
	global_store_dwordx4 v[202:203], v[208:211], off
	v_permlane16_swap_b32_e32 v216, v218
	v_permlane16_swap_b32_e32 v217, v219
	global_store_dwordx4 v[202:203], v[216:219], off offset:256
	v_lshl_add_u64 v[202:203], v[202:203], 0, s[12:13]
	s_waitcnt vmcnt(14)
	v_permlane16_swap_b32_e32 v156, v158
	v_permlane16_swap_b32_e32 v157, v159
	v_permlane16_swap_b32_e32 v160, v162
	v_permlane16_swap_b32_e32 v161, v163
	v_lshlrev_b32_e32 v222, 16, v156
	v_and_b32_e32 v223, 0xffff0000, v156
	v_lshlrev_b32_e32 v224, 16, v157
	v_and_b32_e32 v225, 0xffff0000, v157
	v_pk_add_f32 v[98:99], v[98:99], v[222:223]
	v_pk_add_f32 v[100:101], v[100:101], v[224:225]
	v_pk_mul_f32 v[242:243], v[98:99], v[98:99]
	v_pk_fma_f32 v[242:243], v[100:101], v[100:101], v[242:243]
	v_cvt_pk_bf16_f32 v208, v98, v99
	v_cvt_pk_bf16_f32 v209, v100, v101
	v_lshlrev_b32_e32 v222, 16, v158
	v_and_b32_e32 v223, 0xffff0000, v158
	v_lshlrev_b32_e32 v224, 16, v159
	v_and_b32_e32 v225, 0xffff0000, v159
	v_pk_add_f32 v[106:107], v[106:107], v[222:223]
	v_pk_add_f32 v[108:109], v[108:109], v[224:225]
	v_pk_fma_f32 v[242:243], v[106:107], v[106:107], v[242:243]
	v_pk_fma_f32 v[242:243], v[108:109], v[108:109], v[242:243]
	v_cvt_pk_bf16_f32 v210, v106, v107
	v_cvt_pk_bf16_f32 v211, v108, v109
	v_lshlrev_b32_e32 v222, 16, v160
	v_and_b32_e32 v223, 0xffff0000, v160
	v_lshlrev_b32_e32 v224, 16, v161
	v_and_b32_e32 v225, 0xffff0000, v161
	v_pk_add_f32 v[78:79], v[78:79], v[222:223]
	v_pk_add_f32 v[80:81], v[80:81], v[224:225]
	v_pk_fma_f32 v[242:243], v[78:79], v[78:79], v[242:243]
	v_pk_fma_f32 v[242:243], v[80:81], v[80:81], v[242:243]
	v_cvt_pk_bf16_f32 v216, v78, v79
	v_cvt_pk_bf16_f32 v217, v80, v81
	v_lshlrev_b32_e32 v222, 16, v162
	v_and_b32_e32 v223, 0xffff0000, v162
	v_lshlrev_b32_e32 v224, 16, v163
	v_and_b32_e32 v225, 0xffff0000, v163
	v_pk_add_f32 v[94:95], v[94:95], v[222:223]
	v_pk_add_f32 v[96:97], v[96:97], v[224:225]
	v_pk_fma_f32 v[242:243], v[94:95], v[94:95], v[242:243]
	v_pk_fma_f32 v[242:243], v[96:97], v[96:97], v[242:243]
	v_cvt_pk_bf16_f32 v218, v94, v95
	v_cvt_pk_bf16_f32 v219, v96, v97
	v_permlane16_swap_b32_e32 v208, v210
	v_permlane16_swap_b32_e32 v209, v211
	global_store_dwordx4 v[202:203], v[208:211], off
	v_permlane16_swap_b32_e32 v216, v218
	v_permlane16_swap_b32_e32 v217, v219
	global_store_dwordx4 v[202:203], v[216:219], off offset:256
	v_lshl_add_u64 v[202:203], v[202:203], 0, s[14:15]
	s_waitcnt vmcnt(14)
; #define GPTR(T, ptr) ((__attribute__((address_space(1))) T*)(ptr))
; __device__ __forceinline__ unsigned pack2(float a, float b) { return (unsigned)f2bf(a) | ((unsigned)f2bf(b) << 16); }
; template <int EPI>
; __device__ __forceinline__ void gemm_tile(const GemmArgs& g, int brow, int bcol, int parity, bool first, bool nvalid, int nbrow, int nbcol) {
;     ...
;           _Pragma("unroll") for (int ps = 0; ps < 8; ++ps) hrv[ps] = *GPTR(const u32x2, g.hb + obase + (long)ps * 8 * 1024);
;           _Pragma("unroll") for (int ps = 0; ps < 8; ++ps) {
;             const int r_ = ps * 8 + (lane >> 3), c_ = (lane & 7) * 4;
;             float4 v = *(const float4*)(W + r_ * 36 + c_);
;             v.x += __uint_as_float(hrv[ps][0] << 16); v.y += __uint_as_float(hrv[ps][0] & 0xffff0000u);
;             v.z += __uint_as_float(hrv[ps][1] << 16); v.w += __uint_as_float(hrv[ps][1] & 0xffff0000u);
;             u32x2 hb2; hb2[0] = pack2(v.x, v.y); hb2[1] = pack2(v.z, v.w);
;             *GPTR(u32x2, g.hb + obase + (long)ps * 8 * 1024) = hb2;
;             ssp[ps] += v.x * v.x + v.y * v.y + v.z * v.z + v.w * v.w;
;           }
	v_permlane16_swap_b32_e32 v164, v166
	v_permlane16_swap_b32_e32 v165, v167
	v_permlane16_swap_b32_e32 v168, v170
	v_permlane16_swap_b32_e32 v169, v171
	v_lshlrev_b32_e32 v222, 16, v164
	v_and_b32_e32 v223, 0xffff0000, v164
	v_lshlrev_b32_e32 v224, 16, v165
	v_and_b32_e32 v225, 0xffff0000, v165
	v_pk_add_f32 v[34:35], v[34:35], v[222:223]
	v_pk_add_f32 v[36:37], v[36:37], v[224:225]
	v_pk_mul_f32 v[244:245], v[34:35], v[34:35]
	v_pk_fma_f32 v[244:245], v[36:37], v[36:37], v[244:245]
	v_cvt_pk_bf16_f32 v208, v34, v35
	v_cvt_pk_bf16_f32 v209, v36, v37
	v_lshlrev_b32_e32 v222, 16, v166
	v_and_b32_e32 v223, 0xffff0000, v166
	v_lshlrev_b32_e32 v224, 16, v167
	v_and_b32_e32 v225, 0xffff0000, v167
	v_pk_add_f32 v[50:51], v[50:51], v[222:223]
	v_pk_add_f32 v[52:53], v[52:53], v[224:225]
	v_pk_fma_f32 v[244:245], v[50:51], v[50:51], v[244:245]
	v_pk_fma_f32 v[244:245], v[52:53], v[52:53], v[244:245]
	v_cvt_pk_bf16_f32 v210, v50, v51
	v_cvt_pk_bf16_f32 v211, v52, v53
	v_lshlrev_b32_e32 v222, 16, v168
	v_and_b32_e32 v223, 0xffff0000, v168
	v_lshlrev_b32_e32 v224, 16, v169
	v_and_b32_e32 v225, 0xffff0000, v169
	v_pk_add_f32 v[2:3], v[2:3], v[222:223]
	v_pk_add_f32 v[4:5], v[4:5], v[224:225]
	v_pk_fma_f32 v[244:245], v[2:3], v[2:3], v[244:245]
	v_pk_fma_f32 v[244:245], v[4:5], v[4:5], v[244:245]
	v_cvt_pk_bf16_f32 v216, v2, v3
	v_cvt_pk_bf16_f32 v217, v4, v5
	v_lshlrev_b32_e32 v222, 16, v170
	v_and_b32_e32 v223, 0xffff0000, v170
	v_lshlrev_b32_e32 v224, 16, v171
	v_and_b32_e32 v225, 0xffff0000, v171
	v_pk_add_f32 v[18:19], v[18:19], v[222:223]
	v_pk_add_f32 v[20:21], v[20:21], v[224:225]
	v_pk_fma_f32 v[244:245], v[18:19], v[18:19], v[244:245]
	v_pk_fma_f32 v[244:245], v[20:21], v[20:21], v[244:245]
	v_cvt_pk_bf16_f32 v218, v18, v19
	v_cvt_pk_bf16_f32 v219, v20, v21
	v_permlane16_swap_b32_e32 v208, v210
	v_permlane16_swap_b32_e32 v209, v211
	global_store_dwordx4 v[202:203], v[208:211], off
	v_permlane16_swap_b32_e32 v216, v218
	v_permlane16_swap_b32_e32 v217, v219
	global_store_dwordx4 v[202:203], v[216:219], off offset:256
	v_lshl_add_u64 v[202:203], v[202:203], 0, s[12:13]
	s_waitcnt vmcnt(14)
	v_permlane16_swap_b32_e32 v172, v174
	v_permlane16_swap_b32_e32 v173, v175
	v_permlane16_swap_b32_e32 v176, v178
	v_permlane16_swap_b32_e32 v177, v179
	v_lshlrev_b32_e32 v222, 16, v172
	v_and_b32_e32 v223, 0xffff0000, v172
	v_lshlrev_b32_e32 v224, 16, v173
	v_and_b32_e32 v225, 0xffff0000, v173
	v_pk_add_f32 v[38:39], v[38:39], v[222:223]
	v_pk_add_f32 v[40:41], v[40:41], v[224:225]
	v_pk_mul_f32 v[246:247], v[38:39], v[38:39]
	v_pk_fma_f32 v[246:247], v[40:41], v[40:41], v[246:247]
	v_cvt_pk_bf16_f32 v208, v38, v39
	v_cvt_pk_bf16_f32 v209, v40, v41
	v_lshlrev_b32_e32 v222, 16, v174
	v_and_b32_e32 v223, 0xffff0000, v174
	v_lshlrev_b32_e32 v224, 16, v175
	v_and_b32_e32 v225, 0xffff0000, v175
	v_pk_add_f32 v[54:55], v[54:55], v[222:223]
	v_pk_add_f32 v[56:57], v[56:57], v[224:225]
	v_pk_fma_f32 v[246:247], v[54:55], v[54:55], v[246:247]
	v_pk_fma_f32 v[246:247], v[56:57], v[56:57], v[246:247]
	v_cvt_pk_bf16_f32 v210, v54, v55
	v_cvt_pk_bf16_f32 v211, v56, v57
	v_lshlrev_b32_e32 v222, 16, v176
	v_and_b32_e32 v223, 0xffff0000, v176
	v_lshlrev_b32_e32 v224, 16, v177
	v_and_b32_e32 v225, 0xffff0000, v177
	v_pk_add_f32 v[6:7], v[6:7], v[222:223]
	v_pk_add_f32 v[8:9], v[8:9], v[224:225]
	v_pk_fma_f32 v[246:247], v[6:7], v[6:7], v[246:247]
	v_pk_fma_f32 v[246:247], v[8:9], v[8:9], v[246:247]
	v_cvt_pk_bf16_f32 v216, v6, v7
	v_cvt_pk_bf16_f32 v217, v8, v9
	v_lshlrev_b32_e32 v222, 16, v178
	v_and_b32_e32 v223, 0xffff0000, v178
	v_lshlrev_b32_e32 v224, 16, v179
	v_and_b32_e32 v225, 0xffff0000, v179
	v_pk_add_f32 v[22:23], v[22:23], v[222:223]
	v_pk_add_f32 v[24:25], v[24:25], v[224:225]
	v_pk_fma_f32 v[246:247], v[22:23], v[22:23], v[246:247]
	v_pk_fma_f32 v[246:247], v[24:25], v[24:25], v[246:247]
	v_cvt_pk_bf16_f32 v218, v22, v23
	v_cvt_pk_bf16_f32 v219, v24, v25
	v_permlane16_swap_b32_e32 v208, v210
	v_permlane16_swap_b32_e32 v209, v211
	global_store_dwordx4 v[202:203], v[208:211], off
	v_permlane16_swap_b32_e32 v216, v218
	v_permlane16_swap_b32_e32 v217, v219
	global_store_dwordx4 v[202:203], v[216:219], off offset:256
	v_lshl_add_u64 v[202:203], v[202:203], 0, s[12:13]
	s_waitcnt vmcnt(14)
	v_permlane16_swap_b32_e32 v180, v182
	v_permlane16_swap_b32_e32 v181, v183
	v_permlane16_swap_b32_e32 v184, v186
	v_permlane16_swap_b32_e32 v185, v187
	v_lshlrev_b32_e32 v222, 16, v180
	v_and_b32_e32 v223, 0xffff0000, v180
	v_lshlrev_b32_e32 v224, 16, v181
	v_and_b32_e32 v225, 0xffff0000, v181
	v_pk_add_f32 v[42:43], v[42:43], v[222:223]
	v_pk_add_f32 v[44:45], v[44:45], v[224:225]
	v_pk_mul_f32 v[248:249], v[42:43], v[42:43]
	v_pk_fma_f32 v[248:249], v[44:45], v[44:45], v[248:249]
	v_cvt_pk_bf16_f32 v208, v42, v43
	v_cvt_pk_bf16_f32 v209, v44, v45
	v_lshlrev_b32_e32 v222, 16, v182
	v_and_b32_e32 v223, 0xffff0000, v182
	v_lshlrev_b32_e32 v224, 16, v183
	v_and_b32_e32 v225, 0xffff0000, v183
	v_pk_add_f32 v[58:59], v[58:59], v[222:223]
	v_pk_add_f32 v[60:61], v[60:61], v[224:225]
	v_pk_fma_f32 v[248:249], v[58:59], v[58:59], v[248:249]
	v_pk_fma_f32 v[248:249], v[60:61], v[60:61], v[248:249]
	v_cvt_pk_bf16_f32 v210, v58, v59
	v_cvt_pk_bf16_f32 v211, v60, v61
	v_lshlrev_b32_e32 v222, 16, v184
	v_and_b32_e32 v223, 0xffff0000, v184
	v_lshlrev_b32_e32 v224, 16, v185
	v_and_b32_e32 v225, 0xffff0000, v185
	v_pk_add_f32 v[10:11], v[10:11], v[222:223]
	v_pk_add_f32 v[12:13], v[12:13], v[224:225]
	v_pk_fma_f32 v[248:249], v[10:11], v[10:11], v[248:249]
	v_pk_fma_f32 v[248:249], v[12:13], v[12:13], v[248:249]
	v_cvt_pk_bf16_f32 v216, v10, v11
	v_cvt_pk_bf16_f32 v217, v12, v13
	v_lshlrev_b32_e32 v222, 16, v186
	v_and_b32_e32 v223, 0xffff0000, v186
	v_lshlrev_b32_e32 v224, 16, v187
	v_and_b32_e32 v225, 0xffff0000, v187
	v_pk_add_f32 v[26:27], v[26:27], v[222:223]
	v_pk_add_f32 v[28:29], v[28:29], v[224:225]
	v_pk_fma_f32 v[248:249], v[26:27], v[26:27], v[248:249]
	v_pk_fma_f32 v[248:249], v[28:29], v[28:29], v[248:249]
	v_cvt_pk_bf16_f32 v218, v26, v27
	v_cvt_pk_bf16_f32 v219, v28, v29
	v_permlane16_swap_b32_e32 v208, v210
	v_permlane16_swap_b32_e32 v209, v211
	global_store_dwordx4 v[202:203], v[208:211], off
	v_permlane16_swap_b32_e32 v216, v218
	v_permlane16_swap_b32_e32 v217, v219
	global_store_dwordx4 v[202:203], v[216:219], off offset:256
	v_lshl_add_u64 v[202:203], v[202:203], 0, s[12:13]
	s_waitcnt vmcnt(14)
; #define GPTR(T, ptr) ((__attribute__((address_space(1))) T*)(ptr))
; __device__ __forceinline__ unsigned pack2(float a, float b) { return (unsigned)f2bf(a) | ((unsigned)f2bf(b) << 16); }
; template <int EPI>
; __device__ __forceinline__ void gemm_tile(const GemmArgs& g, int brow, int bcol, int parity, bool first, bool nvalid, int nbrow, int nbcol) {
;     ...
;         if (g.res_bf16) {
;           u32x2 hrv[8];
;           _Pragma("unroll") for (int ps = 0; ps < 8; ++ps) hrv[ps] = *GPTR(const u32x2, g.hb + obase + (long)ps * 8 * 1024);
;           _Pragma("unroll") for (int ps = 0; ps < 8; ++ps) {
;             const int r_ = ps * 8 + (lane >> 3), c_ = (lane & 7) * 4;
;             float4 v = *(const float4*)(W + r_ * 36 + c_);
;             v.x += __uint_as_float(hrv[ps][0] << 16); v.y += __uint_as_float(hrv[ps][0] & 0xffff0000u);
;             v.z += __uint_as_float(hrv[ps][1] << 16); v.w += __uint_as_float(hrv[ps][1] & 0xffff0000u);
;             u32x2 hb2; hb2[0] = pack2(v.x, v.y); hb2[1] = pack2(v.z, v.w);
;             *GPTR(u32x2, g.hb + obase + (long)ps * 8 * 1024) = hb2;
;             ssp[ps] += v.x * v.x + v.y * v.y + v.z * v.z + v.w * v.w;
;           }
;         } else {
;           _Pragma("unroll") for (int ps = 0; ps < 8; ++ps) {
;             const int r_ = ps * 8 + (lane >> 3), c_ = (lane & 7) * 4;
;             const long o = obase + (long)ps * 8 * 1024;
;             float4 v = *(const float4*)(W + r_ * 36 + c_);
;             const f32x4 hr = *GPTR(const f32x4, g.hres + o);
;             v.x += hr[0]; v.y += hr[1]; v.z += hr[2]; v.w += hr[3];
;             u32x2 hb2; hb2[0] = pack2(v.x, v.y); hb2[1] = pack2(v.z, v.w);
;             *GPTR(u32x2, g.hb + o) = hb2;
;             ssp[ps] += v.x * v.x + v.y * v.y + v.z * v.z + v.w * v.w;
;           }
	v_permlane16_swap_b32_e32 v188, v190
	v_permlane16_swap_b32_e32 v189, v191
	v_permlane16_swap_b32_e32 v192, v194
	v_permlane16_swap_b32_e32 v193, v195
	v_lshlrev_b32_e32 v222, 16, v188
	v_and_b32_e32 v223, 0xffff0000, v188
	v_lshlrev_b32_e32 v224, 16, v189
	v_and_b32_e32 v225, 0xffff0000, v189
	v_pk_add_f32 v[46:47], v[46:47], v[222:223]
	v_pk_add_f32 v[48:49], v[48:49], v[224:225]
	v_pk_mul_f32 v[250:251], v[46:47], v[46:47]
	v_pk_fma_f32 v[250:251], v[48:49], v[48:49], v[250:251]
	v_cvt_pk_bf16_f32 v208, v46, v47
	v_cvt_pk_bf16_f32 v209, v48, v49
	v_lshlrev_b32_e32 v222, 16, v190
	v_and_b32_e32 v223, 0xffff0000, v190
	v_lshlrev_b32_e32 v224, 16, v191
	v_and_b32_e32 v225, 0xffff0000, v191
	v_pk_add_f32 v[62:63], v[62:63], v[222:223]
	v_pk_add_f32 v[64:65], v[64:65], v[224:225]
	v_pk_fma_f32 v[250:251], v[62:63], v[62:63], v[250:251]
	v_pk_fma_f32 v[250:251], v[64:65], v[64:65], v[250:251]
	v_cvt_pk_bf16_f32 v210, v62, v63
	v_cvt_pk_bf16_f32 v211, v64, v65
	v_lshlrev_b32_e32 v222, 16, v192
	v_and_b32_e32 v223, 0xffff0000, v192
	v_lshlrev_b32_e32 v224, 16, v193
	v_and_b32_e32 v225, 0xffff0000, v193
	v_pk_add_f32 v[14:15], v[14:15], v[222:223]
	v_pk_add_f32 v[16:17], v[16:17], v[224:225]
	v_pk_fma_f32 v[250:251], v[14:15], v[14:15], v[250:251]
	v_pk_fma_f32 v[250:251], v[16:17], v[16:17], v[250:251]
	v_cvt_pk_bf16_f32 v216, v14, v15
	v_cvt_pk_bf16_f32 v217, v16, v17
	v_lshlrev_b32_e32 v222, 16, v194
	v_and_b32_e32 v223, 0xffff0000, v194
	v_lshlrev_b32_e32 v224, 16, v195
	v_and_b32_e32 v225, 0xffff0000, v195
	v_pk_add_f32 v[30:31], v[30:31], v[222:223]
	v_pk_add_f32 v[32:33], v[32:33], v[224:225]
	v_pk_fma_f32 v[250:251], v[30:31], v[30:31], v[250:251]
	v_pk_fma_f32 v[250:251], v[32:33], v[32:33], v[250:251]
	v_cvt_pk_bf16_f32 v218, v30, v31
	v_cvt_pk_bf16_f32 v219, v32, v33
	v_permlane16_swap_b32_e32 v208, v210
	v_permlane16_swap_b32_e32 v209, v211
	global_store_dwordx4 v[202:203], v[208:211], off
	v_permlane16_swap_b32_e32 v216, v218
	v_permlane16_swap_b32_e32 v217, v219
	global_store_dwordx4 v[202:203], v[216:219], off offset:256
	s_branch .Lres_red
.Lres_f32:
	s_mov_b64 s[2:3], 0x10000
	v_mov_b64_e32 v[222:223], v[204:205]
	global_load_dwordx4 v[132:135], v[222:223], off offset:0
	global_load_dwordx4 v[136:139], v[222:223], off offset:64
	global_load_dwordx4 v[140:143], v[222:223], off offset:512
	global_load_dwordx4 v[144:147], v[222:223], off offset:576
	v_lshl_add_u64 v[222:223], v[222:223], 0, s[2:3]
	global_load_dwordx4 v[148:151], v[222:223], off offset:0
	global_load_dwordx4 v[152:155], v[222:223], off offset:64
	global_load_dwordx4 v[156:159], v[222:223], off offset:512
	global_load_dwordx4 v[160:163], v[222:223], off offset:576
	v_lshl_add_u64 v[222:223], v[222:223], 0, s[2:3]
	global_load_dwordx4 v[164:167], v[222:223], off offset:0
	global_load_dwordx4 v[168:171], v[222:223], off offset:64
	global_load_dwordx4 v[172:175], v[222:223], off offset:512
	global_load_dwordx4 v[176:179], v[222:223], off offset:576
	v_lshl_add_u64 v[222:223], v[222:223], 0, s[2:3]
	global_load_dwordx4 v[180:183], v[222:223], off offset:0
	global_load_dwordx4 v[184:187], v[222:223], off offset:64
	global_load_dwordx4 v[188:191], v[222:223], off offset:512
	global_load_dwordx4 v[192:195], v[222:223], off offset:576
	s_waitcnt vmcnt(12)
	v_pk_add_f32 v[114:115], v[114:115], v[132:133]
	v_pk_add_f32 v[116:117], v[116:117], v[134:135]
	v_pk_mul_f32 v[236:237], v[114:115], v[114:115]
	v_pk_fma_f32 v[236:237], v[116:117], v[116:117], v[236:237]
	v_cvt_pk_bf16_f32 v208, v114, v115
	v_cvt_pk_bf16_f32 v209, v116, v117
	v_pk_add_f32 v[126:127], v[126:127], v[136:137]
	v_pk_add_f32 v[128:129], v[128:129], v[138:139]
	v_pk_fma_f32 v[236:237], v[126:127], v[126:127], v[236:237]
	v_pk_fma_f32 v[236:237], v[128:129], v[128:129], v[236:237]
	v_cvt_pk_bf16_f32 v210, v126, v127
	v_cvt_pk_bf16_f32 v211, v128, v129
	v_pk_add_f32 v[66:67], v[66:67], v[140:141]
	v_pk_add_f32 v[68:69], v[68:69], v[142:143]
	v_pk_fma_f32 v[236:237], v[66:67], v[66:67], v[236:237]
	v_pk_fma_f32 v[236:237], v[68:69], v[68:69], v[236:237]
	v_cvt_pk_bf16_f32 v216, v66, v67
	v_cvt_pk_bf16_f32 v217, v68, v69
	v_pk_add_f32 v[82:83], v[82:83], v[144:145]
	v_pk_add_f32 v[84:85], v[84:85], v[146:147]
	v_pk_fma_f32 v[236:237], v[82:83], v[82:83], v[236:237]
	v_pk_fma_f32 v[236:237], v[84:85], v[84:85], v[236:237]
	v_cvt_pk_bf16_f32 v218, v82, v83
	v_cvt_pk_bf16_f32 v219, v84, v85
	v_permlane16_swap_b32_e32 v208, v210
	v_permlane16_swap_b32_e32 v209, v211
	global_store_dwordx4 v[202:203], v[208:211], off
	v_permlane16_swap_b32_e32 v216, v218
	v_permlane16_swap_b32_e32 v217, v219
	global_store_dwordx4 v[202:203], v[216:219], off offset:256
	v_lshl_add_u64 v[202:203], v[202:203], 0, s[12:13]
	s_waitcnt vmcnt(10)
	v_pk_add_f32 v[110:111], v[110:111], v[148:149]
	v_pk_add_f32 v[112:113], v[112:113], v[150:151]
	v_pk_mul_f32 v[238:239], v[110:111], v[110:111]
	v_pk_fma_f32 v[238:239], v[112:113], v[112:113], v[238:239]
	v_cvt_pk_bf16_f32 v208, v110, v111
	v_cvt_pk_bf16_f32 v209, v112, v113
	v_pk_add_f32 v[122:123], v[122:123], v[152:153]
	v_pk_add_f32 v[124:125], v[124:125], v[154:155]
	v_pk_fma_f32 v[238:239], v[122:123], v[122:123], v[238:239]
	v_pk_fma_f32 v[238:239], v[124:125], v[124:125], v[238:239]
	v_cvt_pk_bf16_f32 v210, v122, v123
	v_cvt_pk_bf16_f32 v211, v124, v125
	v_pk_add_f32 v[70:71], v[70:71], v[156:157]
	v_pk_add_f32 v[72:73], v[72:73], v[158:159]
	v_pk_fma_f32 v[238:239], v[70:71], v[70:71], v[238:239]
	v_pk_fma_f32 v[238:239], v[72:73], v[72:73], v[238:239]
	v_cvt_pk_bf16_f32 v216, v70, v71
	v_cvt_pk_bf16_f32 v217, v72, v73
	v_pk_add_f32 v[86:87], v[86:87], v[160:161]
	v_pk_add_f32 v[88:89], v[88:89], v[162:163]
	v_pk_fma_f32 v[238:239], v[86:87], v[86:87], v[238:239]
	v_pk_fma_f32 v[238:239], v[88:89], v[88:89], v[238:239]
	v_cvt_pk_bf16_f32 v218, v86, v87
	v_cvt_pk_bf16_f32 v219, v88, v89
	v_permlane16_swap_b32_e32 v208, v210
	v_permlane16_swap_b32_e32 v209, v211
	global_store_dwordx4 v[202:203], v[208:211], off
	v_permlane16_swap_b32_e32 v216, v218
	v_permlane16_swap_b32_e32 v217, v219
	global_store_dwordx4 v[202:203], v[216:219], off offset:256
	v_lshl_add_u64 v[202:203], v[202:203], 0, s[12:13]
	s_waitcnt vmcnt(8)
; #define GPTR(T, ptr) ((__attribute__((address_space(1))) T*)(ptr))
; __device__ __forceinline__ unsigned pack2(float a, float b) { return (unsigned)f2bf(a) | ((unsigned)f2bf(b) << 16); }
; template <int EPI>
; __device__ __forceinline__ void gemm_tile(const GemmArgs& g, int brow, int bcol, int parity, bool first, bool nvalid, int nbrow, int nbcol) {
;     ...
;           _Pragma("unroll") for (int ps = 0; ps < 8; ++ps) {
;             const int r_ = ps * 8 + (lane >> 3), c_ = (lane & 7) * 4;
;             const long o = obase + (long)ps * 8 * 1024;
;             float4 v = *(const float4*)(W + r_ * 36 + c_);
;             const f32x4 hr = *GPTR(const f32x4, g.hres + o);
;             v.x += hr[0]; v.y += hr[1]; v.z += hr[2]; v.w += hr[3];
;             u32x2 hb2; hb2[0] = pack2(v.x, v.y); hb2[1] = pack2(v.z, v.w);
;             *GPTR(u32x2, g.hb + o) = hb2;
;             ssp[ps] += v.x * v.x + v.y * v.y + v.z * v.z + v.w * v.w;
;           }
	v_pk_add_f32 v[102:103], v[102:103], v[164:165]
	v_pk_add_f32 v[104:105], v[104:105], v[166:167]
	v_pk_mul_f32 v[240:241], v[102:103], v[102:103]
	v_pk_fma_f32 v[240:241], v[104:105], v[104:105], v[240:241]
	v_cvt_pk_bf16_f32 v208, v102, v103
	v_cvt_pk_bf16_f32 v209, v104, v105
	v_pk_add_f32 v[118:119], v[118:119], v[168:169]
	v_pk_add_f32 v[120:121], v[120:121], v[170:171]
	v_pk_fma_f32 v[240:241], v[118:119], v[118:119], v[240:241]
	v_pk_fma_f32 v[240:241], v[120:121], v[120:121], v[240:241]
	v_cvt_pk_bf16_f32 v210, v118, v119
	v_cvt_pk_bf16_f32 v211, v120, v121
	v_pk_add_f32 v[74:75], v[74:75], v[172:173]
	v_pk_add_f32 v[76:77], v[76:77], v[174:175]
	v_pk_fma_f32 v[240:241], v[74:75], v[74:75], v[240:241]
	v_pk_fma_f32 v[240:241], v[76:77], v[76:77], v[240:241]
	v_cvt_pk_bf16_f32 v216, v74, v75
	v_cvt_pk_bf16_f32 v217, v76, v77
	v_pk_add_f32 v[90:91], v[90:91], v[176:177]
	v_pk_add_f32 v[92:93], v[92:93], v[178:179]
	v_pk_fma_f32 v[240:241], v[90:91], v[90:91], v[240:241]
	v_pk_fma_f32 v[240:241], v[92:93], v[92:93], v[240:241]
	v_cvt_pk_bf16_f32 v218, v90, v91
	v_cvt_pk_bf16_f32 v219, v92, v93
	v_permlane16_swap_b32_e32 v208, v210
	v_permlane16_swap_b32_e32 v209, v211
	global_store_dwordx4 v[202:203], v[208:211], off
	v_permlane16_swap_b32_e32 v216, v218
	v_permlane16_swap_b32_e32 v217, v219
	global_store_dwordx4 v[202:203], v[216:219], off offset:256
	v_lshl_add_u64 v[202:203], v[202:203], 0, s[12:13]
	s_waitcnt vmcnt(6)
	v_pk_add_f32 v[98:99], v[98:99], v[180:181]
	v_pk_add_f32 v[100:101], v[100:101], v[182:183]
	v_pk_mul_f32 v[242:243], v[98:99], v[98:99]
	v_pk_fma_f32 v[242:243], v[100:101], v[100:101], v[242:243]
	v_cvt_pk_bf16_f32 v208, v98, v99
	v_cvt_pk_bf16_f32 v209, v100, v101
	v_pk_add_f32 v[106:107], v[106:107], v[184:185]
	v_pk_add_f32 v[108:109], v[108:109], v[186:187]
	v_pk_fma_f32 v[242:243], v[106:107], v[106:107], v[242:243]
	v_pk_fma_f32 v[242:243], v[108:109], v[108:109], v[242:243]
	v_cvt_pk_bf16_f32 v210, v106, v107
	v_cvt_pk_bf16_f32 v211, v108, v109
	v_pk_add_f32 v[78:79], v[78:79], v[188:189]
	v_pk_add_f32 v[80:81], v[80:81], v[190:191]
	v_pk_fma_f32 v[242:243], v[78:79], v[78:79], v[242:243]
	v_pk_fma_f32 v[242:243], v[80:81], v[80:81], v[242:243]
	v_cvt_pk_bf16_f32 v216, v78, v79
	v_cvt_pk_bf16_f32 v217, v80, v81
	v_pk_add_f32 v[94:95], v[94:95], v[192:193]
	v_pk_add_f32 v[96:97], v[96:97], v[194:195]
	v_pk_fma_f32 v[242:243], v[94:95], v[94:95], v[242:243]
	v_pk_fma_f32 v[242:243], v[96:97], v[96:97], v[242:243]
	v_cvt_pk_bf16_f32 v218, v94, v95
	v_cvt_pk_bf16_f32 v219, v96, v97
	v_permlane16_swap_b32_e32 v208, v210
	v_permlane16_swap_b32_e32 v209, v211
	global_store_dwordx4 v[202:203], v[208:211], off
	v_permlane16_swap_b32_e32 v216, v218
	v_permlane16_swap_b32_e32 v217, v219
	global_store_dwordx4 v[202:203], v[216:219], off offset:256
	v_lshl_add_u64 v[202:203], v[202:203], 0, s[14:15]
	s_mov_b64 s[14:15], 0x80000
	v_lshl_add_u64 v[204:205], v[204:205], 0, s[14:15]
	v_mov_b64_e32 v[222:223], v[204:205]
	global_load_dwordx4 v[132:135], v[222:223], off offset:0
	global_load_dwordx4 v[136:139], v[222:223], off offset:64
	global_load_dwordx4 v[140:143], v[222:223], off offset:512
	global_load_dwordx4 v[144:147], v[222:223], off offset:576
	v_lshl_add_u64 v[222:223], v[222:223], 0, s[2:3]
	global_load_dwordx4 v[148:151], v[222:223], off offset:0
	global_load_dwordx4 v[152:155], v[222:223], off offset:64
	global_load_dwordx4 v[156:159], v[222:223], off offset:512
	global_load_dwordx4 v[160:163], v[222:223], off offset:576
	v_lshl_add_u64 v[222:223], v[222:223], 0, s[2:3]
	global_load_dwordx4 v[164:167], v[222:223], off offset:0
	global_load_dwordx4 v[168:171], v[222:223], off offset:64
	global_load_dwordx4 v[172:175], v[222:223], off offset:512
	global_load_dwordx4 v[176:179], v[222:223], off offset:576
	v_lshl_add_u64 v[222:223], v[222:223], 0, s[2:3]
	global_load_dwordx4 v[180:183], v[222:223], off offset:0
	global_load_dwordx4 v[184:187], v[222:223], off offset:64
	global_load_dwordx4 v[188:191], v[222:223], off offset:512
	global_load_dwordx4 v[192:195], v[222:223], off offset:576
	s_waitcnt vmcnt(12)
	v_pk_add_f32 v[34:35], v[34:35], v[132:133]
	v_pk_add_f32 v[36:37], v[36:37], v[134:135]
	v_pk_mul_f32 v[244:245], v[34:35], v[34:35]
	v_pk_fma_f32 v[244:245], v[36:37], v[36:37], v[244:245]
	v_cvt_pk_bf16_f32 v208, v34, v35
	v_cvt_pk_bf16_f32 v209, v36, v37
	v_pk_add_f32 v[50:51], v[50:51], v[136:137]
	v_pk_add_f32 v[52:53], v[52:53], v[138:139]
	v_pk_fma_f32 v[244:245], v[50:51], v[50:51], v[244:245]
	v_pk_fma_f32 v[244:245], v[52:53], v[52:53], v[244:245]
	v_cvt_pk_bf16_f32 v210, v50, v51
	v_cvt_pk_bf16_f32 v211, v52, v53
	v_pk_add_f32 v[2:3], v[2:3], v[140:141]
	v_pk_add_f32 v[4:5], v[4:5], v[142:143]
	v_pk_fma_f32 v[244:245], v[2:3], v[2:3], v[244:245]
	v_pk_fma_f32 v[244:245], v[4:5], v[4:5], v[244:245]
	v_cvt_pk_bf16_f32 v216, v2, v3
	v_cvt_pk_bf16_f32 v217, v4, v5
	v_pk_add_f32 v[18:19], v[18:19], v[144:145]
	v_pk_add_f32 v[20:21], v[20:21], v[146:147]
	v_pk_fma_f32 v[244:245], v[18:19], v[18:19], v[244:245]
	v_pk_fma_f32 v[244:245], v[20:21], v[20:21], v[244:245]
	v_cvt_pk_bf16_f32 v218, v18, v19
	v_cvt_pk_bf16_f32 v219, v20, v21
	v_permlane16_swap_b32_e32 v208, v210
	v_permlane16_swap_b32_e32 v209, v211
	global_store_dwordx4 v[202:203], v[208:211], off
	v_permlane16_swap_b32_e32 v216, v218
	v_permlane16_swap_b32_e32 v217, v219
	global_store_dwordx4 v[202:203], v[216:219], off offset:256
	v_lshl_add_u64 v[202:203], v[202:203], 0, s[12:13]
	s_waitcnt vmcnt(10)
; #define GPTR(T, ptr) ((__attribute__((address_space(1))) T*)(ptr))
; template <int EPI>
; __device__ __forceinline__ void gemm_tile(const GemmArgs& g, int brow, int bcol, int parity, bool first, bool nvalid, int nbrow, int nbcol) {
;     ...
;   } else {
;     _Pragma("unroll") for (int ai = 0; ai < 2; ++ai) {
;       float ssp[8];
;       _Pragma("unroll") for (int ps = 0; ps < 8; ++ps) ssp[ps] = 0.f;
;       _Pragma("unroll") for (int bj = 0; bj < 2; ++bj) {
;         SCHED;
;         _Pragma("unroll") for (int m = 0; m < 4; ++m) _Pragma("unroll") for (int j = 0; j < 4; ++j)
;           _Pragma("unroll") for (int n = 0; n < 2; ++n) W_WRITE(m, n, j, acc[ai][bj][m][n][j]);
;         const long obase = (long)(wrow0 + ai * HALF + (lane >> 3)) * 1024 + wcol0 + bj * HALF + (lane & 7) * 4;
;         if (g.res_bf16) {
;           u32x2 hrv[8];
;           _Pragma("unroll") for (int ps = 0; ps < 8; ++ps) hrv[ps] = *GPTR(const u32x2, g.hb + obase + (long)ps * 8 * 1024);
;           _Pragma("unroll") for (int ps = 0; ps < 8; ++ps) {
;             const int r_ = ps * 8 + (lane >> 3), c_ = (lane & 7) * 4;
;             float4 v = *(const float4*)(W + r_ * 36 + c_);
;             v.x += __uint_as_float(hrv[ps][0] << 16); v.y += __uint_as_float(hrv[ps][0] & 0xffff0000u);
;             v.z += __uint_as_float(hrv[ps][1] << 16); v.w += __uint_as_float(hrv[ps][1] & 0xffff0000u);
;             u32x2 hb2; hb2[0] = pack2(v.x, v.y); hb2[1] = pack2(v.z, v.w);
;             *GPTR(u32x2, g.hb + obase + (long)ps * 8 * 1024) = hb2;
;             ssp[ps] += v.x * v.x + v.y * v.y + v.z * v.z + v.w * v.w;
;           }
;         } else {
;           _Pragma("unroll") for (int ps = 0; ps < 8; ++ps) {
;             const int r_ = ps * 8 + (lane >> 3), c_ = (lane & 7) * 4;
;             const long o = obase + (long)ps * 8 * 1024;
;             float4 v = *(const float4*)(W + r_ * 36 + c_);
;             const f32x4 hr = *GPTR(const f32x4, g.hres + o);
;             v.x += hr[0]; v.y += hr[1]; v.z += hr[2]; v.w += hr[3];
;             u32x2 hb2; hb2[0] = pack2(v.x, v.y); hb2[1] = pack2(v.z, v.w);
;             *GPTR(u32x2, g.hb + o) = hb2;
;             ssp[ps] += v.x * v.x + v.y * v.y + v.z * v.z + v.w * v.w;
;           }
;         }
;       }
;       _Pragma("unroll") for (int ps = 0; ps < 8; ++ps) {
;         float ss = ssp[ps];
;         ss += SHX(ss, 1); ss += SHX(ss, 2); ss += SHX(ss, 4);
	v_pk_add_f32 v[38:39], v[38:39], v[148:149]
	v_pk_add_f32 v[40:41], v[40:41], v[150:151]
	v_pk_mul_f32 v[246:247], v[38:39], v[38:39]
	v_pk_fma_f32 v[246:247], v[40:41], v[40:41], v[246:247]
	v_cvt_pk_bf16_f32 v208, v38, v39
	v_cvt_pk_bf16_f32 v209, v40, v41
	v_pk_add_f32 v[54:55], v[54:55], v[152:153]
	v_pk_add_f32 v[56:57], v[56:57], v[154:155]
	v_pk_fma_f32 v[246:247], v[54:55], v[54:55], v[246:247]
	v_pk_fma_f32 v[246:247], v[56:57], v[56:57], v[246:247]
	v_cvt_pk_bf16_f32 v210, v54, v55
	v_cvt_pk_bf16_f32 v211, v56, v57
	v_pk_add_f32 v[6:7], v[6:7], v[156:157]
	v_pk_add_f32 v[8:9], v[8:9], v[158:159]
	v_pk_fma_f32 v[246:247], v[6:7], v[6:7], v[246:247]
	v_pk_fma_f32 v[246:247], v[8:9], v[8:9], v[246:247]
	v_cvt_pk_bf16_f32 v216, v6, v7
	v_cvt_pk_bf16_f32 v217, v8, v9
	v_pk_add_f32 v[22:23], v[22:23], v[160:161]
	v_pk_add_f32 v[24:25], v[24:25], v[162:163]
	v_pk_fma_f32 v[246:247], v[22:23], v[22:23], v[246:247]
	v_pk_fma_f32 v[246:247], v[24:25], v[24:25], v[246:247]
	v_cvt_pk_bf16_f32 v218, v22, v23
	v_cvt_pk_bf16_f32 v219, v24, v25
	v_permlane16_swap_b32_e32 v208, v210
	v_permlane16_swap_b32_e32 v209, v211
	global_store_dwordx4 v[202:203], v[208:211], off
	v_permlane16_swap_b32_e32 v216, v218
	v_permlane16_swap_b32_e32 v217, v219
	global_store_dwordx4 v[202:203], v[216:219], off offset:256
	v_lshl_add_u64 v[202:203], v[202:203], 0, s[12:13]
	s_waitcnt vmcnt(8)
	v_pk_add_f32 v[42:43], v[42:43], v[164:165]
	v_pk_add_f32 v[44:45], v[44:45], v[166:167]
	v_pk_mul_f32 v[248:249], v[42:43], v[42:43]
	v_pk_fma_f32 v[248:249], v[44:45], v[44:45], v[248:249]
	v_cvt_pk_bf16_f32 v208, v42, v43
	v_cvt_pk_bf16_f32 v209, v44, v45
	v_pk_add_f32 v[58:59], v[58:59], v[168:169]
	v_pk_add_f32 v[60:61], v[60:61], v[170:171]
	v_pk_fma_f32 v[248:249], v[58:59], v[58:59], v[248:249]
	v_pk_fma_f32 v[248:249], v[60:61], v[60:61], v[248:249]
	v_cvt_pk_bf16_f32 v210, v58, v59
	v_cvt_pk_bf16_f32 v211, v60, v61
	v_pk_add_f32 v[10:11], v[10:11], v[172:173]
	v_pk_add_f32 v[12:13], v[12:13], v[174:175]
	v_pk_fma_f32 v[248:249], v[10:11], v[10:11], v[248:249]
	v_pk_fma_f32 v[248:249], v[12:13], v[12:13], v[248:249]
	v_cvt_pk_bf16_f32 v216, v10, v11
	v_cvt_pk_bf16_f32 v217, v12, v13
	v_pk_add_f32 v[26:27], v[26:27], v[176:177]
	v_pk_add_f32 v[28:29], v[28:29], v[178:179]
	v_pk_fma_f32 v[248:249], v[26:27], v[26:27], v[248:249]
	v_pk_fma_f32 v[248:249], v[28:29], v[28:29], v[248:249]
	v_cvt_pk_bf16_f32 v218, v26, v27
	v_cvt_pk_bf16_f32 v219, v28, v29
	v_permlane16_swap_b32_e32 v208, v210
	v_permlane16_swap_b32_e32 v209, v211
	global_store_dwordx4 v[202:203], v[208:211], off
	v_permlane16_swap_b32_e32 v216, v218
	v_permlane16_swap_b32_e32 v217, v219
	global_store_dwordx4 v[202:203], v[216:219], off offset:256
	v_lshl_add_u64 v[202:203], v[202:203], 0, s[12:13]
	s_waitcnt vmcnt(6)
	v_pk_add_f32 v[46:47], v[46:47], v[180:181]
	v_pk_add_f32 v[48:49], v[48:49], v[182:183]
	v_pk_mul_f32 v[250:251], v[46:47], v[46:47]
	v_pk_fma_f32 v[250:251], v[48:49], v[48:49], v[250:251]
	v_cvt_pk_bf16_f32 v208, v46, v47
	v_cvt_pk_bf16_f32 v209, v48, v49
	v_pk_add_f32 v[62:63], v[62:63], v[184:185]
	v_pk_add_f32 v[64:65], v[64:65], v[186:187]
	v_pk_fma_f32 v[250:251], v[62:63], v[62:63], v[250:251]
	v_pk_fma_f32 v[250:251], v[64:65], v[64:65], v[250:251]
	v_cvt_pk_bf16_f32 v210, v62, v63
	v_cvt_pk_bf16_f32 v211, v64, v65
	v_pk_add_f32 v[14:15], v[14:15], v[188:189]
	v_pk_add_f32 v[16:17], v[16:17], v[190:191]
	v_pk_fma_f32 v[250:251], v[14:15], v[14:15], v[250:251]
	v_pk_fma_f32 v[250:251], v[16:17], v[16:17], v[250:251]
	v_cvt_pk_bf16_f32 v216, v14, v15
	v_cvt_pk_bf16_f32 v217, v16, v17
	v_pk_add_f32 v[30:31], v[30:31], v[192:193]
	v_pk_add_f32 v[32:33], v[32:33], v[194:195]
	v_pk_fma_f32 v[250:251], v[30:31], v[30:31], v[250:251]
	v_pk_fma_f32 v[250:251], v[32:33], v[32:33], v[250:251]
	v_cvt_pk_bf16_f32 v218, v30, v31
	v_cvt_pk_bf16_f32 v219, v32, v33
	v_permlane16_swap_b32_e32 v208, v210
	v_permlane16_swap_b32_e32 v209, v211
	global_store_dwordx4 v[202:203], v[208:211], off
	v_permlane16_swap_b32_e32 v216, v218
	v_permlane16_swap_b32_e32 v217, v219
	global_store_dwordx4 v[202:203], v[216:219], off offset:256
.Lres_red:
	v_add_f32_e32 v236, v236, v237
	v_add_f32_e32 v238, v238, v239
	v_add_f32_e32 v240, v240, v241
	v_add_f32_e32 v242, v242, v243
	v_add_f32_e32 v244, v244, v245
	v_add_f32_e32 v246, v246, v247
	v_add_f32_e32 v248, v248, v249
	v_add_f32_e32 v250, v250, v251
	v_mov_b32_e32 v132, v236
	v_mov_b32_e32 v133, v238
	v_mov_b32_e32 v134, v240
	v_mov_b32_e32 v135, v242
	v_mov_b32_e32 v136, v244
	v_mov_b32_e32 v137, v246
	v_mov_b32_e32 v138, v248
	v_mov_b32_e32 v139, v250
	v_permlane32_swap_b32_e32 v236, v132
	v_permlane32_swap_b32_e32 v238, v133
	v_permlane32_swap_b32_e32 v240, v134
	v_permlane32_swap_b32_e32 v242, v135
	v_permlane32_swap_b32_e32 v244, v136
	v_permlane32_swap_b32_e32 v246, v137
	v_permlane32_swap_b32_e32 v248, v138
	v_permlane32_swap_b32_e32 v250, v139
	v_add_f32_e32 v236, v236, v132
	v_add_f32_e32 v238, v238, v133
	v_add_f32_e32 v240, v240, v134
	v_add_f32_e32 v242, v242, v135
	v_add_f32_e32 v244, v244, v136
	v_add_f32_e32 v246, v246, v137
	v_add_f32_e32 v248, v248, v138
	v_add_f32_e32 v250, v250, v139
	v_mov_b32_e32 v132, v236
	v_mov_b32_e32 v133, v238
	v_mov_b32_e32 v134, v240
	v_mov_b32_e32 v135, v242
	v_mov_b32_e32 v136, v244
	v_mov_b32_e32 v137, v246
	v_mov_b32_e32 v138, v248
	v_mov_b32_e32 v139, v250
	v_permlane16_swap_b32_e32 v236, v132
	v_permlane16_swap_b32_e32 v238, v133
	v_permlane16_swap_b32_e32 v240, v134
	v_permlane16_swap_b32_e32 v242, v135
	v_permlane16_swap_b32_e32 v244, v136
	v_permlane16_swap_b32_e32 v246, v137
	v_permlane16_swap_b32_e32 v248, v138
	v_permlane16_swap_b32_e32 v250, v139
	v_add_f32_e32 v236, v236, v132
	v_add_f32_e32 v238, v238, v133
	v_add_f32_e32 v240, v240, v134
	v_add_f32_e32 v242, v242, v135
	v_add_f32_e32 v244, v244, v136
	v_add_f32_e32 v246, v246, v137
	v_add_f32_e32 v248, v248, v138
	v_add_f32_e32 v250, v250, v139
	v_cmp_gt_u32_e32 vcc, 16, v196
	s_and_saveexec_b64 s[2:3], vcc
	s_mov_b64 s[12:13], 0x400
	s_mov_b64 s[14:15], 0x1400
	global_store_dword v[206:207], v236, off
	v_lshl_add_u64 v[206:207], v[206:207], 0, s[12:13]
	global_store_dword v[206:207], v238, off
	v_lshl_add_u64 v[206:207], v[206:207], 0, s[12:13]
	global_store_dword v[206:207], v240, off
	v_lshl_add_u64 v[206:207], v[206:207], 0, s[12:13]
	global_store_dword v[206:207], v242, off
	v_lshl_add_u64 v[206:207], v[206:207], 0, s[14:15]
	global_store_dword v[206:207], v244, off
	v_lshl_add_u64 v[206:207], v[206:207], 0, s[12:13]
	global_store_dword v[206:207], v246, off
	v_lshl_add_u64 v[206:207], v[206:207], 0, s[12:13]
	global_store_dword v[206:207], v248, off
	v_lshl_add_u64 v[206:207], v[206:207], 0, s[12:13]
	global_store_dword v[206:207], v250, off
	s_or_b64 exec, exec, s[2:3]
	s_mov_b64 s[12:13], -1
	s_branch .LBB0_181

; #define STAGE_B(P, br, kt) do { const char* _gb = (const char*)(Bt + ((long)(br) * K + (long)(kt) * BK)); \
;     __builtin_amdgcn_global_load_lds((const unsigned*)(_gb + bofl0), (unsigned*)((char*)(P) + gtid_ * 16), 16, 0, 0); \
;     __builtin_amdgcn_global_load_lds((const unsigned*)(_gb + (long)K * 128 + bofl0), (unsigned*)((char*)(P) + gtid_ * 16 + 8192), 16, 0, 0); } while (0)
; #define LDA(dst, b, h) for (int m = 0; m < 4; ++m) for (int k = 0; k < 2; ++k) \
;     dst[m][k] = *reinterpret_cast<const bf16x8*>((char*)SA(b, h) + lds_byte(wr * 64 + m * 16 + fr, k * 32 + fq * 8))
; #define LDB(dst, b, h) for (int n = 0; n < 2; ++n) for (int k = 0; k < 2; ++k) \
;     dst[n][k] = *reinterpret_cast<const bf16x8*>((char*)SB(b, h) + lds_byte(wc * 32 + n * 16 + fr, k * 32 + fq * 8))
; #define MMA(ai, bj, At_, Bt_) do { __builtin_amdgcn_s_setprio(1); \
;     for (int m = 0; m < 4; ++m) for (int n = 0; n < 2; ++n) for (int k = 0; k < 2; ++k) \
;       acc[ai][bj][m][n] = __builtin_amdgcn_mfma_f32_16x16x32_bf16(At_[m][k], Bt_[n][k], acc[ai][bj][m][n], 0, 0, 0); \
;     __builtin_amdgcn_s_setprio(0); } while (0)
; #define WAIT_V(n) asm volatile("s_waitcnt vmcnt(" #n ")" ::: "memory")
; #define WAIT_L(n) asm volatile("s_waitcnt lgkmcnt(" #n ")" ::: "memory")
; #define BAR __builtin_amdgcn_s_barrier()
; #define SCHED __builtin_amdgcn_sched_barrier(0)
; template <int EPI>
; __device__ __forceinline__ void gemm_tile(const GemmArgs& g, int brow, int bcol, int parity, bool first, bool nvalid, int nbrow, int nbcol) {
;     ...
;   for (int t = 0; t < nt - 2; t += 2) {
;     LDB(B0, 0, 0); SCHED; LDA(At, 0, 0); STAGE_A(SA(1, 1), brow + HALF, t + 1);
;     WAIT_L(8); BAR; WAIT_L(0); MMA(0, 0, At, B0); BAR; SCHED;
;     LDB(B1, 0, 1); STAGE_B(SB(0, 0), bcol, t + 2);
;     BAR; WAIT_L(0); MMA(0, 1, At, B1); BAR; SCHED;
;     LDA(At, 0, 1); STAGE_A(SA(0, 0), brow, t + 2);
;     BAR; WAIT_L(0); MMA(1, 0, At, B0); BAR; SCHED;
;     STAGE_B(SB(0, 1), bcol + HALF, t + 2);
;     WAIT_V(6); BAR; MMA(1, 1, At, B1); BAR; SCHED;
;     LDB(B0, 1, 0); SCHED; LDA(At, 1, 0); STAGE_A(SA(0, 1), brow + HALF, t + 2);
.LBB0_640:
	ds_read_b128 v[164:167], v157
	ds_read_b128 v[168:171], v157 offset:1024
	ds_read_b128 v[172:175], v157 offset:2048
	ds_read_b128 v[176:179], v157 offset:3072
	ds_read_b128 v[180:183], v147
	ds_read_b128 v[184:187], v147 offset:1024
	ds_read_b128 v[188:191], v146
	ds_read_b128 v[192:195], v146 offset:1024
	ds_read_b128 v[196:199], v145
	ds_read_b128 v[202:205], v145 offset:1024
	ds_read_b128 v[206:209], v144
	ds_read_b128 v[216:219], v144 offset:1024
	s_waitcnt lgkmcnt(6)
	ds_read_b128 v[228:231], v154
	ds_read_b128 v[232:235], v154 offset:1024
	ds_read_b128 v[236:239], v154 offset:2048
	ds_read_b128 v[240:243], v154 offset:3072
	v_add_u32_e32 v161, 0xc000, v137
	v_lshl_add_u64 v[210:211], s[12:13], 0, v[130:131]
	v_readfirstlane_b32 s2, v161
	v_add_u32_e32 v162, 0xe000, v137
	v_lshl_add_u64 v[158:159], v[210:211], 0, s[24:25]
	s_mov_b32 m0, s2
	v_readfirstlane_b32 s2, v162
	global_load_lds_dwordx4 v[158:159], off
	v_lshl_add_u64 v[158:159], v[210:211], 0, s[36:37]
	s_mov_b32 m0, s2
	s_nop 0
	global_load_lds_dwordx4 v[158:159], off
	s_waitcnt vmcnt(8)
	s_barrier
	s_waitcnt lgkmcnt(0)
	v_mfma_f32_16x16x32_bf16 v[126:129], v[164:167], v[180:183], v[126:129]
	v_mfma_f32_16x16x32_bf16 v[122:125], v[172:175], v[180:183], v[122:125]
	v_mfma_f32_16x16x32_bf16 v[118:121], v[164:167], v[188:191], v[118:121]
	v_mfma_f32_16x16x32_bf16 v[114:117], v[172:175], v[188:191], v[114:117]
	v_mfma_f32_16x16x32_bf16 v[110:113], v[164:167], v[196:199], v[110:113]
	v_mfma_f32_16x16x32_bf16 v[106:109], v[172:175], v[196:199], v[106:109]
	v_mfma_f32_16x16x32_bf16 v[102:105], v[164:167], v[206:209], v[102:105]
	v_mfma_f32_16x16x32_bf16 v[98:101], v[172:175], v[206:209], v[98:101]
	v_mfma_f32_16x16x32_bf16 v[126:129], v[168:171], v[184:187], v[126:129]
	v_mfma_f32_16x16x32_bf16 v[122:125], v[176:179], v[184:187], v[122:125]
	v_mfma_f32_16x16x32_bf16 v[118:121], v[168:171], v[192:195], v[118:121]
	v_mfma_f32_16x16x32_bf16 v[114:117], v[176:179], v[192:195], v[114:117]
	v_mfma_f32_16x16x32_bf16 v[110:113], v[168:171], v[202:205], v[110:113]
	v_mfma_f32_16x16x32_bf16 v[106:109], v[176:179], v[202:205], v[106:109]
	v_mfma_f32_16x16x32_bf16 v[102:105], v[168:171], v[216:219], v[102:105]
	v_mfma_f32_16x16x32_bf16 v[98:101], v[176:179], v[216:219], v[98:101]
	v_mfma_f32_16x16x32_bf16 v[94:97], v[228:231], v[180:183], v[94:97]
	v_mfma_f32_16x16x32_bf16 v[90:93], v[236:239], v[180:183], v[90:93]
	v_mfma_f32_16x16x32_bf16 v[86:89], v[228:231], v[188:191], v[86:89]
	v_mfma_f32_16x16x32_bf16 v[82:85], v[236:239], v[188:191], v[82:85]
	v_mfma_f32_16x16x32_bf16 v[78:81], v[228:231], v[196:199], v[78:81]
	v_mfma_f32_16x16x32_bf16 v[74:77], v[236:239], v[196:199], v[74:77]
	v_mfma_f32_16x16x32_bf16 v[70:73], v[228:231], v[206:209], v[70:73]
	v_mfma_f32_16x16x32_bf16 v[66:69], v[236:239], v[206:209], v[66:69]
	v_mfma_f32_16x16x32_bf16 v[94:97], v[232:235], v[184:187], v[94:97]
	v_mfma_f32_16x16x32_bf16 v[90:93], v[240:243], v[184:187], v[90:93]
	v_mfma_f32_16x16x32_bf16 v[86:89], v[232:235], v[192:195], v[86:89]
	v_mfma_f32_16x16x32_bf16 v[82:85], v[240:243], v[192:195], v[82:85]
	v_mfma_f32_16x16x32_bf16 v[78:81], v[232:235], v[202:205], v[78:81]
	v_mfma_f32_16x16x32_bf16 v[74:77], v[240:243], v[202:205], v[74:77]
	v_mfma_f32_16x16x32_bf16 v[70:73], v[232:235], v[216:219], v[70:73]
	v_mfma_f32_16x16x32_bf16 v[66:69], v[240:243], v[216:219], v[66:69]
	s_barrier
	ds_read_b128 v[180:183], v147 offset:16384
	ds_read_b128 v[184:187], v147 offset:17408
	ds_read_b128 v[188:191], v146 offset:16384
	ds_read_b128 v[192:195], v146 offset:17408
	ds_read_b128 v[196:199], v145 offset:16384
	ds_read_b128 v[202:205], v145 offset:17408
	ds_read_b128 v[206:209], v144 offset:16384
	ds_read_b128 v[216:219], v144 offset:17408
	v_add_u32_e32 v158, s15, v142
	v_lshl_add_u64 v[212:213], s[0:1], 0, v[130:131]
	v_readfirstlane_b32 s2, v158
	v_add_u32_e32 v159, 0x2000, v158
	v_lshl_add_u64 v[222:223], v[212:213], 0, s[78:79]
	s_mov_b32 m0, s2
	v_readfirstlane_b32 s2, v159
	global_load_lds_dwordx4 v[222:223], off
	v_lshl_add_u64 v[222:223], v[212:213], 0, s[66:67]
	s_mov_b32 m0, s2
	s_nop 0
	global_load_lds_dwordx4 v[222:223], off
	v_readfirstlane_b32 s2, v137
	v_lshl_add_u64 v[222:223], v[210:211], 0, s[38:39]
	s_mov_b32 m0, s2
	v_readfirstlane_b32 s2, v136
	global_load_lds_dwordx4 v[222:223], off
	v_lshl_add_u64 v[222:223], v[210:211], 0, s[42:43]
	s_mov_b32 m0, s2
	s_nop 0
	global_load_lds_dwordx4 v[222:223], off
	v_readfirstlane_b32 s2, v135
	v_add_u32_e32 v160, 0x2000, v135
	v_lshl_add_u64 v[244:245], v[212:213], 0, s[76:77]
	s_mov_b32 m0, s2
	v_readfirstlane_b32 s2, v160
	global_load_lds_dwordx4 v[244:245], off
	v_lshl_add_u64 v[244:245], v[212:213], 0, s[96:97]
	s_mov_b32 m0, s2
	s_nop 0
	global_load_lds_dwordx4 v[244:245], off
	s_waitcnt vmcnt(8)
	s_barrier
; #define STAGE_B(P, br, kt) do { const char* _gb = (const char*)(Bt + ((long)(br) * K + (long)(kt) * BK)); \
;     __builtin_amdgcn_global_load_lds((const unsigned*)(_gb + bofl0), (unsigned*)((char*)(P) + gtid_ * 16), 16, 0, 0); \
;     __builtin_amdgcn_global_load_lds((const unsigned*)(_gb + (long)K * 128 + bofl0), (unsigned*)((char*)(P) + gtid_ * 16 + 8192), 16, 0, 0); } while (0)
; #define LDA(dst, b, h) for (int m = 0; m < 4; ++m) for (int k = 0; k < 2; ++k) \
;     dst[m][k] = *reinterpret_cast<const bf16x8*>((char*)SA(b, h) + lds_byte(wr * 64 + m * 16 + fr, k * 32 + fq * 8))
; #define LDB(dst, b, h) for (int n = 0; n < 2; ++n) for (int k = 0; k < 2; ++k) \
;     dst[n][k] = *reinterpret_cast<const bf16x8*>((char*)SB(b, h) + lds_byte(wc * 32 + n * 16 + fr, k * 32 + fq * 8))
; #define MMA(ai, bj, At_, Bt_) do { __builtin_amdgcn_s_setprio(1); \
;     for (int m = 0; m < 4; ++m) for (int n = 0; n < 2; ++n) for (int k = 0; k < 2; ++k) \
;       acc[ai][bj][m][n] = __builtin_amdgcn_mfma_f32_16x16x32_bf16(At_[m][k], Bt_[n][k], acc[ai][bj][m][n], 0, 0, 0); \
;     __builtin_amdgcn_s_setprio(0); } while (0)
; #define WAIT_V(n) asm volatile("s_waitcnt vmcnt(" #n ")" ::: "memory")
; #define WAIT_L(n) asm volatile("s_waitcnt lgkmcnt(" #n ")" ::: "memory")
; #define BAR __builtin_amdgcn_s_barrier()
; #define SCHED __builtin_amdgcn_sched_barrier(0)
; template <int EPI>
; __device__ __forceinline__ void gemm_tile(const GemmArgs& g, int brow, int bcol, int parity, bool first, bool nvalid, int nbrow, int nbcol) {
;     ...
;     BAR; WAIT_L(0); MMA(0, 1, At, B1); BAR; SCHED;
;     LDA(At, 0, 1); STAGE_A(SA(0, 0), brow, t + 2);
;     BAR; WAIT_L(0); MMA(1, 0, At, B0); BAR; SCHED;
;     STAGE_B(SB(0, 1), bcol + HALF, t + 2);
;     WAIT_V(6); BAR; MMA(1, 1, At, B1); BAR; SCHED;
;     LDB(B0, 1, 0); SCHED; LDA(At, 1, 0); STAGE_A(SA(0, 1), brow + HALF, t + 2);
;     WAIT_L(8); BAR; WAIT_L(0); MMA(0, 0, At, B0); BAR; SCHED;
	s_waitcnt lgkmcnt(0)
	v_mfma_f32_16x16x32_bf16 v[62:65], v[164:167], v[180:183], v[62:65]
	v_mfma_f32_16x16x32_bf16 v[58:61], v[172:175], v[180:183], v[58:61]
	v_mfma_f32_16x16x32_bf16 v[54:57], v[164:167], v[188:191], v[54:57]
	v_mfma_f32_16x16x32_bf16 v[50:53], v[172:175], v[188:191], v[50:53]
	v_mfma_f32_16x16x32_bf16 v[46:49], v[164:167], v[196:199], v[46:49]
	v_mfma_f32_16x16x32_bf16 v[42:45], v[172:175], v[196:199], v[42:45]
	v_mfma_f32_16x16x32_bf16 v[38:41], v[164:167], v[206:209], v[38:41]
	v_mfma_f32_16x16x32_bf16 v[34:37], v[172:175], v[206:209], v[34:37]
	v_mfma_f32_16x16x32_bf16 v[62:65], v[168:171], v[184:187], v[62:65]
	v_mfma_f32_16x16x32_bf16 v[58:61], v[176:179], v[184:187], v[58:61]
	v_mfma_f32_16x16x32_bf16 v[54:57], v[168:171], v[192:195], v[54:57]
	v_mfma_f32_16x16x32_bf16 v[50:53], v[176:179], v[192:195], v[50:53]
	v_mfma_f32_16x16x32_bf16 v[46:49], v[168:171], v[202:205], v[46:49]
	v_mfma_f32_16x16x32_bf16 v[42:45], v[176:179], v[202:205], v[42:45]
	v_mfma_f32_16x16x32_bf16 v[38:41], v[168:171], v[216:219], v[38:41]
	v_mfma_f32_16x16x32_bf16 v[34:37], v[176:179], v[216:219], v[34:37]
	v_mfma_f32_16x16x32_bf16 v[30:33], v[228:231], v[180:183], v[30:33]
	v_mfma_f32_16x16x32_bf16 v[26:29], v[236:239], v[180:183], v[26:29]
	v_mfma_f32_16x16x32_bf16 v[22:25], v[228:231], v[188:191], v[22:25]
	v_mfma_f32_16x16x32_bf16 v[18:21], v[236:239], v[188:191], v[18:21]
	v_mfma_f32_16x16x32_bf16 v[14:17], v[228:231], v[196:199], v[14:17]
	v_mfma_f32_16x16x32_bf16 v[10:13], v[236:239], v[196:199], v[10:13]
	v_mfma_f32_16x16x32_bf16 v[6:9], v[228:231], v[206:209], v[6:9]
	v_mfma_f32_16x16x32_bf16 v[2:5], v[236:239], v[206:209], v[2:5]
	v_mfma_f32_16x16x32_bf16 v[30:33], v[232:235], v[184:187], v[30:33]
	v_mfma_f32_16x16x32_bf16 v[26:29], v[240:243], v[184:187], v[26:29]
	v_mfma_f32_16x16x32_bf16 v[22:25], v[232:235], v[192:195], v[22:25]
	v_mfma_f32_16x16x32_bf16 v[18:21], v[240:243], v[192:195], v[18:21]
	v_mfma_f32_16x16x32_bf16 v[14:17], v[232:235], v[202:205], v[14:17]
	v_mfma_f32_16x16x32_bf16 v[10:13], v[240:243], v[202:205], v[10:13]
	v_mfma_f32_16x16x32_bf16 v[6:9], v[232:235], v[216:219], v[6:9]
	v_mfma_f32_16x16x32_bf16 v[2:5], v[240:243], v[216:219], v[2:5]
	s_barrier
	ds_read_b128 v[164:167], v149
	ds_read_b128 v[168:171], v149 offset:1024
	ds_read_b128 v[172:175], v149 offset:2048
	ds_read_b128 v[176:179], v149 offset:3072
	ds_read_b128 v[180:183], v147 offset:32768
	ds_read_b128 v[184:187], v147 offset:33792
	ds_read_b128 v[188:191], v146 offset:32768
	ds_read_b128 v[192:195], v146 offset:33792
	ds_read_b128 v[196:199], v145 offset:32768
	ds_read_b128 v[202:205], v145 offset:33792
	ds_read_b128 v[206:209], v144 offset:32768
	ds_read_b128 v[216:219], v144 offset:33792
	s_waitcnt lgkmcnt(6)
	ds_read_b128 v[228:231], v148
	ds_read_b128 v[232:235], v148 offset:1024
	ds_read_b128 v[236:239], v148 offset:2048
	ds_read_b128 v[240:243], v148 offset:3072
	v_readfirstlane_b32 s2, v134
	v_lshl_add_u64 v[222:223], v[210:211], 0, s[44:45]
	s_mov_b32 m0, s2
	v_readfirstlane_b32 s2, v133
	global_load_lds_dwordx4 v[222:223], off
	v_lshl_add_u64 v[222:223], v[210:211], 0, s[46:47]
	s_mov_b32 m0, s2
	s_nop 0
	global_load_lds_dwordx4 v[222:223], off
	s_waitcnt vmcnt(8)
	s_barrier
	s_waitcnt lgkmcnt(0)
	v_mfma_f32_16x16x32_bf16 v[126:129], v[164:167], v[180:183], v[126:129]
	v_mfma_f32_16x16x32_bf16 v[122:125], v[172:175], v[180:183], v[122:125]
	v_mfma_f32_16x16x32_bf16 v[118:121], v[164:167], v[188:191], v[118:121]
	v_mfma_f32_16x16x32_bf16 v[114:117], v[172:175], v[188:191], v[114:117]
	v_mfma_f32_16x16x32_bf16 v[110:113], v[164:167], v[196:199], v[110:113]
	v_mfma_f32_16x16x32_bf16 v[106:109], v[172:175], v[196:199], v[106:109]
	v_mfma_f32_16x16x32_bf16 v[102:105], v[164:167], v[206:209], v[102:105]
	v_mfma_f32_16x16x32_bf16 v[98:101], v[172:175], v[206:209], v[98:101]
	v_mfma_f32_16x16x32_bf16 v[126:129], v[168:171], v[184:187], v[126:129]
	v_mfma_f32_16x16x32_bf16 v[122:125], v[176:179], v[184:187], v[122:125]
	v_mfma_f32_16x16x32_bf16 v[118:121], v[168:171], v[192:195], v[118:121]
	v_mfma_f32_16x16x32_bf16 v[114:117], v[176:179], v[192:195], v[114:117]
	v_mfma_f32_16x16x32_bf16 v[110:113], v[168:171], v[202:205], v[110:113]
	v_mfma_f32_16x16x32_bf16 v[106:109], v[176:179], v[202:205], v[106:109]
	v_mfma_f32_16x16x32_bf16 v[102:105], v[168:171], v[216:219], v[102:105]
	v_mfma_f32_16x16x32_bf16 v[98:101], v[176:179], v[216:219], v[98:101]
	v_mfma_f32_16x16x32_bf16 v[94:97], v[228:231], v[180:183], v[94:97]
	v_mfma_f32_16x16x32_bf16 v[90:93], v[236:239], v[180:183], v[90:93]
	v_mfma_f32_16x16x32_bf16 v[86:89], v[228:231], v[188:191], v[86:89]
	v_mfma_f32_16x16x32_bf16 v[82:85], v[236:239], v[188:191], v[82:85]
	v_mfma_f32_16x16x32_bf16 v[78:81], v[228:231], v[196:199], v[78:81]
	v_mfma_f32_16x16x32_bf16 v[74:77], v[236:239], v[196:199], v[74:77]
	v_mfma_f32_16x16x32_bf16 v[70:73], v[228:231], v[206:209], v[70:73]
	v_mfma_f32_16x16x32_bf16 v[66:69], v[236:239], v[206:209], v[66:69]
	v_mfma_f32_16x16x32_bf16 v[94:97], v[232:235], v[184:187], v[94:97]
	v_mfma_f32_16x16x32_bf16 v[90:93], v[240:243], v[184:187], v[90:93]
	v_mfma_f32_16x16x32_bf16 v[86:89], v[232:235], v[192:195], v[86:89]
	v_mfma_f32_16x16x32_bf16 v[82:85], v[240:243], v[192:195], v[82:85]
	v_mfma_f32_16x16x32_bf16 v[78:81], v[232:235], v[202:205], v[78:81]
	v_mfma_f32_16x16x32_bf16 v[74:77], v[240:243], v[202:205], v[74:77]
	v_mfma_f32_16x16x32_bf16 v[70:73], v[232:235], v[216:219], v[70:73]
	v_mfma_f32_16x16x32_bf16 v[66:69], v[240:243], v[216:219], v[66:69]
	s_barrier
; #define STAGE_B(P, br, kt) do { const char* _gb = (const char*)(Bt + ((long)(br) * K + (long)(kt) * BK)); \
;     __builtin_amdgcn_global_load_lds((const unsigned*)(_gb + bofl0), (unsigned*)((char*)(P) + gtid_ * 16), 16, 0, 0); \
;     __builtin_amdgcn_global_load_lds((const unsigned*)(_gb + (long)K * 128 + bofl0), (unsigned*)((char*)(P) + gtid_ * 16 + 8192), 16, 0, 0); } while (0)
; #define LDA(dst, b, h) for (int m = 0; m < 4; ++m) for (int k = 0; k < 2; ++k) \
;     dst[m][k] = *reinterpret_cast<const bf16x8*>((char*)SA(b, h) + lds_byte(wr * 64 + m * 16 + fr, k * 32 + fq * 8))
; #define LDB(dst, b, h) for (int n = 0; n < 2; ++n) for (int k = 0; k < 2; ++k) \
;     dst[n][k] = *reinterpret_cast<const bf16x8*>((char*)SB(b, h) + lds_byte(wc * 32 + n * 16 + fr, k * 32 + fq * 8))
; #define MMA(ai, bj, At_, Bt_) do { __builtin_amdgcn_s_setprio(1); \
;     for (int m = 0; m < 4; ++m) for (int n = 0; n < 2; ++n) for (int k = 0; k < 2; ++k) \
;       acc[ai][bj][m][n] = __builtin_amdgcn_mfma_f32_16x16x32_bf16(At_[m][k], Bt_[n][k], acc[ai][bj][m][n], 0, 0, 0); \
;     __builtin_amdgcn_s_setprio(0); } while (0)
; #define WAIT_V(n) asm volatile("s_waitcnt vmcnt(" #n ")" ::: "memory")
; #define WAIT_L(n) asm volatile("s_waitcnt lgkmcnt(" #n ")" ::: "memory")
; #define BAR __builtin_amdgcn_s_barrier()
; #define SCHED __builtin_amdgcn_sched_barrier(0)
; template <int EPI>
; __device__ __forceinline__ void gemm_tile(const GemmArgs& g, int brow, int bcol, int parity, bool first, bool nvalid, int nbrow, int nbcol) {
;     ...
;     WAIT_L(8); BAR; WAIT_L(0); MMA(0, 0, At, B0); BAR; SCHED;
;     LDB(B1, 1, 1); STAGE_B(SB(1, 0), bcol, t + 3);
;     BAR; WAIT_L(0); MMA(0, 1, At, B1); BAR; SCHED;
;     LDA(At, 1, 1); STAGE_A(SA(1, 0), brow, t + 3);
;     BAR; WAIT_L(0); MMA(1, 0, At, B0); BAR; SCHED;
;     STAGE_B(SB(1, 1), bcol + HALF, t + 3);
;     WAIT_V(6); BAR; MMA(1, 1, At, B1); BAR; SCHED;
;   }
;   { LDB(B0, 0, 0); LDA(At, 0, 0); STAGE_A(SA(1, 1), brow + HALF, nt - 1);
;     BAR; WAIT_L(0); MMA(0, 0, At, B0); BAR;
;     LDB(B1, 0, 1); BAR; WAIT_L(0); MMA(0, 1, At, B1); BAR; SCHED;
	ds_read_b128 v[180:183], v147 offset:49152
	ds_read_b128 v[184:187], v147 offset:50176
	ds_read_b128 v[188:191], v146 offset:49152
	ds_read_b128 v[192:195], v146 offset:50176
	ds_read_b128 v[196:199], v145 offset:49152
	ds_read_b128 v[202:205], v145 offset:50176
	ds_read_b128 v[206:209], v144 offset:49152
	ds_read_b128 v[216:219], v144 offset:50176
	v_readfirstlane_b32 s2, v150
	v_lshl_add_u64 v[222:223], v[212:213], 0, s[58:59]
	s_mov_b32 m0, s2
	v_readfirstlane_b32 s2, v151
	global_load_lds_dwordx4 v[222:223], off
	v_lshl_add_u64 v[222:223], v[212:213], 0, vcc
	s_mov_b32 m0, s2
	s_nop 0
	global_load_lds_dwordx4 v[222:223], off
	v_readfirstlane_b32 s2, v152
	v_lshl_add_u64 v[222:223], v[210:211], 0, s[48:49]
	s_mov_b32 m0, s2
	v_readfirstlane_b32 s2, v153
	global_load_lds_dwordx4 v[222:223], off
	v_lshl_add_u64 v[210:211], v[210:211], 0, s[50:51]
	s_mov_b32 m0, s2
	s_nop 0
	global_load_lds_dwordx4 v[210:211], off
	v_readfirstlane_b32 s2, v155
	v_lshl_add_u64 v[244:245], v[212:213], 0, s[60:61]
	s_mov_b32 m0, s2
	v_readfirstlane_b32 s2, v156
	global_load_lds_dwordx4 v[244:245], off
	v_lshl_add_u64 v[244:245], v[212:213], 0, s[94:95]
	s_mov_b32 m0, s2
	s_nop 0
	global_load_lds_dwordx4 v[244:245], off
	s_waitcnt vmcnt(8)
	s_barrier
	s_waitcnt lgkmcnt(0)
	v_mfma_f32_16x16x32_bf16 v[62:65], v[164:167], v[180:183], v[62:65]
	v_mfma_f32_16x16x32_bf16 v[58:61], v[172:175], v[180:183], v[58:61]
	v_mfma_f32_16x16x32_bf16 v[54:57], v[164:167], v[188:191], v[54:57]
	v_mfma_f32_16x16x32_bf16 v[50:53], v[172:175], v[188:191], v[50:53]
	v_mfma_f32_16x16x32_bf16 v[46:49], v[164:167], v[196:199], v[46:49]
	v_mfma_f32_16x16x32_bf16 v[42:45], v[172:175], v[196:199], v[42:45]
	v_mfma_f32_16x16x32_bf16 v[38:41], v[164:167], v[206:209], v[38:41]
	v_mfma_f32_16x16x32_bf16 v[34:37], v[172:175], v[206:209], v[34:37]
	v_mfma_f32_16x16x32_bf16 v[62:65], v[168:171], v[184:187], v[62:65]
	v_mfma_f32_16x16x32_bf16 v[58:61], v[176:179], v[184:187], v[58:61]
	v_mfma_f32_16x16x32_bf16 v[54:57], v[168:171], v[192:195], v[54:57]
	v_mfma_f32_16x16x32_bf16 v[50:53], v[176:179], v[192:195], v[50:53]
	v_mfma_f32_16x16x32_bf16 v[46:49], v[168:171], v[202:205], v[46:49]
	v_mfma_f32_16x16x32_bf16 v[42:45], v[176:179], v[202:205], v[42:45]
	v_mfma_f32_16x16x32_bf16 v[38:41], v[168:171], v[216:219], v[38:41]
	v_mfma_f32_16x16x32_bf16 v[34:37], v[176:179], v[216:219], v[34:37]
	v_mfma_f32_16x16x32_bf16 v[30:33], v[228:231], v[180:183], v[30:33]
	v_mfma_f32_16x16x32_bf16 v[26:29], v[236:239], v[180:183], v[26:29]
	v_mfma_f32_16x16x32_bf16 v[22:25], v[228:231], v[188:191], v[22:25]
	v_mfma_f32_16x16x32_bf16 v[18:21], v[236:239], v[188:191], v[18:21]
	v_mfma_f32_16x16x32_bf16 v[14:17], v[228:231], v[196:199], v[14:17]
	v_mfma_f32_16x16x32_bf16 v[10:13], v[236:239], v[196:199], v[10:13]
	v_mfma_f32_16x16x32_bf16 v[6:9], v[228:231], v[206:209], v[6:9]
	v_mfma_f32_16x16x32_bf16 v[2:5], v[236:239], v[206:209], v[2:5]
	v_mfma_f32_16x16x32_bf16 v[30:33], v[232:235], v[184:187], v[30:33]
	v_mfma_f32_16x16x32_bf16 v[26:29], v[240:243], v[184:187], v[26:29]
	v_mfma_f32_16x16x32_bf16 v[22:25], v[232:235], v[192:195], v[22:25]
	v_mfma_f32_16x16x32_bf16 v[18:21], v[240:243], v[192:195], v[18:21]
	v_mfma_f32_16x16x32_bf16 v[14:17], v[232:235], v[202:205], v[14:17]
	v_mfma_f32_16x16x32_bf16 v[10:13], v[240:243], v[202:205], v[10:13]
	v_mfma_f32_16x16x32_bf16 v[6:9], v[232:235], v[216:219], v[6:9]
	v_mfma_f32_16x16x32_bf16 v[2:5], v[240:243], v[216:219], v[2:5]
	s_barrier
	s_add_i32 s23, s23, 2
	s_add_u32 s12, s12, 0x100
	s_addc_u32 s13, s13, 0
	s_add_u32 s0, s0, 0x100
	s_addc_u32 s1, s1, 0
	s_cmp_lt_u32 s23, 12
	s_cbranch_scc1 .LBB0_640
	s_or_b32 s0, s40, 0x80
	s_ashr_i32 s1, s0, 31
	s_lshl_b64 s[0:1], s[0:1], 11
	s_add_u32 s0, s80, s0
	s_addc_u32 s1, s81, s1
	v_lshl_add_u64 v[130:131], s[0:1], 0, v[0:1]
	s_mov_b64 s[0:1], 0x780
	ds_read_b128 v[150:153], v157
	ds_read_b128 v[164:167], v157 offset:1024
	ds_read_b128 v[168:171], v157 offset:2048
	ds_read_b128 v[172:175], v157 offset:3072
	ds_read_b128 v[176:179], v147
	ds_read_b128 v[180:183], v147 offset:1024
	ds_read_b128 v[184:187], v146
	ds_read_b128 v[188:191], v146 offset:1024
	ds_read_b128 v[192:195], v145
	ds_read_b128 v[196:199], v145 offset:1024
	ds_read_b128 v[202:205], v144
	ds_read_b128 v[206:209], v144 offset:1024
	v_lshl_add_u64 v[156:157], v[130:131], 0, s[0:1]
	v_readfirstlane_b32 s0, v161
	s_mov_b32 m0, s0
	s_mov_b64 s[0:1], 0x20780
	v_lshl_add_u64 v[130:131], v[130:131], 0, s[0:1]
	v_readfirstlane_b32 s0, v162
	global_load_lds_dwordx4 v[156:157], off
	s_mov_b32 m0, s0
	s_nop 0
	global_load_lds_dwordx4 v[130:131], off
	s_waitcnt vmcnt(8)
	s_barrier
	s_waitcnt lgkmcnt(0)
	s_setprio 1
	s_waitcnt lgkmcnt(0)
	v_mfma_f32_16x16x32_bf16 v[126:129], v[150:153], v[176:179], v[126:129]
	v_mfma_f32_16x16x32_bf16 v[118:121], v[150:153], v[184:187], v[118:121]
	v_mfma_f32_16x16x32_bf16 v[110:113], v[150:153], v[192:195], v[110:113]
	v_mfma_f32_16x16x32_bf16 v[102:105], v[150:153], v[202:205], v[102:105]
	v_mfma_f32_16x16x32_bf16 v[126:129], v[164:167], v[180:183], v[126:129]
	v_mfma_f32_16x16x32_bf16 v[122:125], v[168:171], v[176:179], v[122:125]
	v_mfma_f32_16x16x32_bf16 v[118:121], v[164:167], v[188:191], v[118:121]
	v_mfma_f32_16x16x32_bf16 v[114:117], v[168:171], v[184:187], v[114:117]
	v_mfma_f32_16x16x32_bf16 v[110:113], v[164:167], v[196:199], v[110:113]
	v_mfma_f32_16x16x32_bf16 v[106:109], v[168:171], v[192:195], v[106:109]
	v_mfma_f32_16x16x32_bf16 v[102:105], v[164:167], v[206:209], v[102:105]
	v_mfma_f32_16x16x32_bf16 v[98:101], v[168:171], v[202:205], v[98:101]
	v_mfma_f32_16x16x32_bf16 v[216:219], v[172:175], v[180:183], v[122:125]
	v_mfma_f32_16x16x32_bf16 v[228:231], v[172:175], v[188:191], v[114:117]
	v_mfma_f32_16x16x32_bf16 v[232:235], v[172:175], v[196:199], v[106:109]
	v_mfma_f32_16x16x32_bf16 v[236:239], v[172:175], v[206:209], v[98:101]
	s_setprio 0
	s_barrier
; #define LDA(dst, b, h) for (int m = 0; m < 4; ++m) for (int k = 0; k < 2; ++k) \
;     dst[m][k] = *reinterpret_cast<const bf16x8*>((char*)SA(b, h) + lds_byte(wr * 64 + m * 16 + fr, k * 32 + fq * 8))
; #define LDB(dst, b, h) for (int n = 0; n < 2; ++n) for (int k = 0; k < 2; ++k) \
;     dst[n][k] = *reinterpret_cast<const bf16x8*>((char*)SB(b, h) + lds_byte(wc * 32 + n * 16 + fr, k * 32 + fq * 8))
; #define MMA(ai, bj, At_, Bt_) do { __builtin_amdgcn_s_setprio(1); \
;     for (int m = 0; m < 4; ++m) for (int n = 0; n < 2; ++n) for (int k = 0; k < 2; ++k) \
;       acc[ai][bj][m][n] = __builtin_amdgcn_mfma_f32_16x16x32_bf16(At_[m][k], Bt_[n][k], acc[ai][bj][m][n], 0, 0, 0); \
;     __builtin_amdgcn_s_setprio(0); } while (0)
; #define WAIT_V(n) asm volatile("s_waitcnt vmcnt(" #n ")" ::: "memory")
; #define WAIT_L(n) asm volatile("s_waitcnt lgkmcnt(" #n ")" ::: "memory")
; #define BAR __builtin_amdgcn_s_barrier()
; #define SCHED __builtin_amdgcn_sched_barrier(0)
; template <int EPI>
; __device__ __forceinline__ void gemm_tile(const GemmArgs& g, int brow, int bcol, int parity, bool first, bool nvalid, int nbrow, int nbcol) {
;     ...
;   { LDB(B0, 0, 0); LDA(At, 0, 0); STAGE_A(SA(1, 1), brow + HALF, nt - 1);
;     BAR; WAIT_L(0); MMA(0, 0, At, B0); BAR;
;     LDB(B1, 0, 1); BAR; WAIT_L(0); MMA(0, 1, At, B1); BAR; SCHED;
;     LDA(At, 0, 1); WAIT_V(4); BAR; WAIT_L(0); MMA(1, 0, At, B0); MMA(1, 1, At, B1); BAR; }
;   { LDB(B0, 1, 0); LDA(At, 1, 0); WAIT_V(2); BAR; WAIT_L(0); MMA(0, 0, At, B0); BAR;
	s_nop 1
	ds_read_b128 v[98:101], v154
	ds_read_b128 v[106:109], v154 offset:1024
	ds_read_b128 v[114:117], v154 offset:2048
	ds_read_b128 v[122:125], v154 offset:3072
	s_barrier
	s_waitcnt lgkmcnt(0)
	s_setprio 1
	s_waitcnt lgkmcnt(0)
	v_mfma_f32_16x16x32_bf16 v[94:97], v[98:101], v[176:179], v[94:97]
	v_mfma_f32_16x16x32_bf16 v[86:89], v[98:101], v[184:187], v[86:89]
	v_mfma_f32_16x16x32_bf16 v[78:81], v[98:101], v[192:195], v[78:81]
	v_mfma_f32_16x16x32_bf16 v[70:73], v[98:101], v[202:205], v[70:73]
	v_mfma_f32_16x16x32_bf16 v[94:97], v[106:109], v[180:183], v[94:97]
	v_mfma_f32_16x16x32_bf16 v[90:93], v[114:117], v[176:179], v[90:93]
	v_mfma_f32_16x16x32_bf16 v[86:89], v[106:109], v[188:191], v[86:89]
	v_mfma_f32_16x16x32_bf16 v[82:85], v[114:117], v[184:187], v[82:85]
	v_mfma_f32_16x16x32_bf16 v[78:81], v[106:109], v[196:199], v[78:81]
	v_mfma_f32_16x16x32_bf16 v[74:77], v[114:117], v[192:195], v[74:77]
	v_mfma_f32_16x16x32_bf16 v[70:73], v[106:109], v[206:209], v[70:73]
	v_mfma_f32_16x16x32_bf16 v[66:69], v[114:117], v[202:205], v[66:69]
	v_mfma_f32_16x16x32_bf16 v[154:157], v[122:125], v[180:183], v[90:93]
	v_mfma_f32_16x16x32_bf16 v[176:179], v[122:125], v[188:191], v[82:85]
	v_mfma_f32_16x16x32_bf16 v[180:183], v[122:125], v[196:199], v[74:77]
	v_mfma_f32_16x16x32_bf16 v[184:187], v[122:125], v[206:209], v[66:69]
	s_setprio 0
	s_barrier
	s_nop 1
	ds_read_b128 v[66:69], v147 offset:16384
	ds_read_b128 v[74:77], v147 offset:17408
	ds_read_b128 v[82:85], v146 offset:16384
	ds_read_b128 v[90:93], v146 offset:17408
	ds_read_b128 v[188:191], v145 offset:16384
	ds_read_b128 v[192:195], v145 offset:17408
	ds_read_b128 v[196:199], v144 offset:16384
	ds_read_b128 v[202:205], v144 offset:17408
	s_waitcnt vmcnt(4)
	s_barrier
	s_waitcnt lgkmcnt(0)
	s_setprio 1
	s_waitcnt lgkmcnt(0)
	v_mfma_f32_16x16x32_bf16 v[62:65], v[150:153], v[66:69], v[62:65]
	v_mfma_f32_16x16x32_bf16 v[54:57], v[150:153], v[82:85], v[54:57]
	v_mfma_f32_16x16x32_bf16 v[46:49], v[150:153], v[188:191], v[46:49]
	v_mfma_f32_16x16x32_bf16 v[38:41], v[150:153], v[196:199], v[38:41]
	v_mfma_f32_16x16x32_bf16 v[62:65], v[164:167], v[74:77], v[62:65]
	v_mfma_f32_16x16x32_bf16 v[58:61], v[168:171], v[66:69], v[58:61]
	v_mfma_f32_16x16x32_bf16 v[54:57], v[164:167], v[90:93], v[54:57]
	v_mfma_f32_16x16x32_bf16 v[50:53], v[168:171], v[82:85], v[50:53]
	v_mfma_f32_16x16x32_bf16 v[46:49], v[164:167], v[192:195], v[46:49]
	v_mfma_f32_16x16x32_bf16 v[42:45], v[168:171], v[188:191], v[42:45]
	v_mfma_f32_16x16x32_bf16 v[38:41], v[164:167], v[202:205], v[38:41]
	v_mfma_f32_16x16x32_bf16 v[34:37], v[168:171], v[196:199], v[34:37]
	v_mfma_f32_16x16x32_bf16 v[206:209], v[172:175], v[74:77], v[58:61]
	v_mfma_f32_16x16x32_bf16 v[240:243], v[172:175], v[90:93], v[50:53]
	v_mfma_f32_16x16x32_bf16 v[244:247], v[172:175], v[192:195], v[42:45]
	v_mfma_f32_16x16x32_bf16 v[150:153], v[172:175], v[202:205], v[34:37]
	s_setprio 0
	s_setprio 1
	v_mfma_f32_16x16x32_bf16 v[30:33], v[98:101], v[66:69], v[30:33]
	v_mfma_f32_16x16x32_bf16 v[22:25], v[98:101], v[82:85], v[22:25]
	v_mfma_f32_16x16x32_bf16 v[14:17], v[98:101], v[188:191], v[14:17]
	v_mfma_f32_16x16x32_bf16 v[6:9], v[98:101], v[196:199], v[6:9]
	v_mfma_f32_16x16x32_bf16 v[30:33], v[106:109], v[74:77], v[30:33]
	v_mfma_f32_16x16x32_bf16 v[26:29], v[114:117], v[66:69], v[26:29]
	v_mfma_f32_16x16x32_bf16 v[22:25], v[106:109], v[90:93], v[22:25]
	v_mfma_f32_16x16x32_bf16 v[18:21], v[114:117], v[82:85], v[18:21]
	v_mfma_f32_16x16x32_bf16 v[14:17], v[106:109], v[192:195], v[14:17]
	v_mfma_f32_16x16x32_bf16 v[10:13], v[114:117], v[188:191], v[10:13]
	v_mfma_f32_16x16x32_bf16 v[6:9], v[106:109], v[202:205], v[6:9]
	v_mfma_f32_16x16x32_bf16 v[2:5], v[114:117], v[196:199], v[2:5]
	v_mfma_f32_16x16x32_bf16 v[162:165], v[122:125], v[74:77], v[26:29]
	v_mfma_f32_16x16x32_bf16 v[166:169], v[122:125], v[90:93], v[18:21]
	v_mfma_f32_16x16x32_bf16 v[170:173], v[122:125], v[192:195], v[10:13]
	v_mfma_f32_16x16x32_bf16 v[188:191], v[122:125], v[202:205], v[2:5]
	s_setprio 0
	s_barrier
	s_nop 1
	ds_read_b128 v[2:5], v149
	ds_read_b128 v[10:13], v149 offset:1024
	ds_read_b128 v[18:21], v149 offset:2048
	ds_read_b128 v[26:29], v149 offset:3072
	ds_read_b128 v[34:37], v147 offset:32768
	ds_read_b128 v[42:45], v147 offset:33792
	ds_read_b128 v[50:53], v146 offset:32768
	ds_read_b128 v[58:61], v146 offset:33792
	ds_read_b128 v[66:69], v145 offset:32768
	ds_read_b128 v[192:195], v145 offset:33792
	ds_read_b128 v[196:199], v144 offset:32768
	ds_read_b128 v[202:205], v144 offset:33792
	s_waitcnt vmcnt(2)
	s_barrier
; #define LDA(dst, b, h) for (int m = 0; m < 4; ++m) for (int k = 0; k < 2; ++k) \
;     dst[m][k] = *reinterpret_cast<const bf16x8*>((char*)SA(b, h) + lds_byte(wr * 64 + m * 16 + fr, k * 32 + fq * 8))
; #define LDB(dst, b, h) for (int n = 0; n < 2; ++n) for (int k = 0; k < 2; ++k) \
;     dst[n][k] = *reinterpret_cast<const bf16x8*>((char*)SB(b, h) + lds_byte(wc * 32 + n * 16 + fr, k * 32 + fq * 8))
; #define MMA(ai, bj, At_, Bt_) do { __builtin_amdgcn_s_setprio(1); \
;     for (int m = 0; m < 4; ++m) for (int n = 0; n < 2; ++n) for (int k = 0; k < 2; ++k) \
;       acc[ai][bj][m][n] = __builtin_amdgcn_mfma_f32_16x16x32_bf16(At_[m][k], Bt_[n][k], acc[ai][bj][m][n], 0, 0, 0); \
;     __builtin_amdgcn_s_setprio(0); } while (0)
; #define WAIT_V(n) asm volatile("s_waitcnt vmcnt(" #n ")" ::: "memory")
; #define WAIT_L(n) asm volatile("s_waitcnt lgkmcnt(" #n ")" ::: "memory")
; #define BAR __builtin_amdgcn_s_barrier()
; #define SCHED __builtin_amdgcn_sched_barrier(0)
; template <int EPI>
; __device__ __forceinline__ void gemm_tile(const GemmArgs& g, int brow, int bcol, int parity, bool first, bool nvalid, int nbrow, int nbcol) {
;     ...
;     LDA(At, 0, 1); WAIT_V(4); BAR; WAIT_L(0); MMA(1, 0, At, B0); MMA(1, 1, At, B1); BAR; }
;   { LDB(B0, 1, 0); LDA(At, 1, 0); WAIT_V(2); BAR; WAIT_L(0); MMA(0, 0, At, B0); BAR;
;     LDB(B1, 1, 1); WAIT_V(0); BAR; WAIT_L(0); MMA(0, 1, At, B1); BAR; SCHED;
;     LDA(At, 1, 1); BAR; WAIT_L(0); MMA(1, 0, At, B0); MMA(1, 1, At, B1); BAR; }
;   if (wr == 0) BAR;
	s_waitcnt lgkmcnt(0)
	s_setprio 1
	s_waitcnt lgkmcnt(0)
	v_mfma_f32_16x16x32_bf16 v[74:77], v[2:5], v[34:37], v[126:129]
	v_mfma_f32_16x16x32_bf16 v[122:125], v[10:13], v[42:45], v[74:77]
	v_mfma_f32_16x16x32_bf16 v[74:77], v[18:21], v[34:37], v[216:219]
	v_mfma_f32_16x16x32_bf16 v[126:129], v[26:29], v[42:45], v[74:77]
	v_mfma_f32_16x16x32_bf16 v[74:77], v[2:5], v[50:53], v[118:121]
	v_mfma_f32_16x16x32_bf16 v[114:117], v[10:13], v[58:61], v[74:77]
	v_mfma_f32_16x16x32_bf16 v[74:77], v[18:21], v[50:53], v[228:231]
	v_mfma_f32_16x16x32_bf16 v[118:121], v[26:29], v[58:61], v[74:77]
	v_mfma_f32_16x16x32_bf16 v[74:77], v[2:5], v[66:69], v[110:113]
	v_mfma_f32_16x16x32_bf16 v[106:109], v[10:13], v[192:195], v[74:77]
	v_mfma_f32_16x16x32_bf16 v[74:77], v[18:21], v[66:69], v[232:235]
	v_mfma_f32_16x16x32_bf16 v[110:113], v[26:29], v[192:195], v[74:77]
	v_mfma_f32_16x16x32_bf16 v[74:77], v[2:5], v[196:199], v[102:105]
	v_mfma_f32_16x16x32_bf16 v[98:101], v[10:13], v[202:205], v[74:77]
	v_mfma_f32_16x16x32_bf16 v[74:77], v[18:21], v[196:199], v[236:239]
	v_mfma_f32_16x16x32_bf16 v[102:105], v[26:29], v[202:205], v[74:77]
	s_setprio 0
	s_barrier
	ds_read_b128 v[216:219], v148
	ds_read_b128 v[228:231], v148 offset:1024
	ds_read_b128 v[232:235], v148 offset:2048
	ds_read_b128 v[236:239], v148 offset:3072
	s_waitcnt vmcnt(0)
	s_barrier
	s_waitcnt lgkmcnt(0)
	s_setprio 1
	s_waitcnt lgkmcnt(0)
	v_mfma_f32_16x16x32_bf16 v[74:77], v[216:219], v[34:37], v[94:97]
	v_mfma_f32_16x16x32_bf16 v[34:37], v[232:235], v[34:37], v[154:157]
	v_mfma_f32_16x16x32_bf16 v[94:97], v[236:239], v[42:45], v[34:37]
	v_mfma_f32_16x16x32_bf16 v[34:37], v[216:219], v[50:53], v[86:89]
	v_mfma_f32_16x16x32_bf16 v[82:85], v[228:231], v[58:61], v[34:37]
	v_mfma_f32_16x16x32_bf16 v[34:37], v[232:235], v[50:53], v[176:179]
	v_mfma_f32_16x16x32_bf16 v[86:89], v[236:239], v[58:61], v[34:37]
	v_mfma_f32_16x16x32_bf16 v[34:37], v[216:219], v[66:69], v[78:81]
	v_mfma_f32_16x16x32_bf16 v[90:93], v[228:231], v[42:45], v[74:77]
	v_mfma_f32_16x16x32_bf16 v[74:77], v[228:231], v[192:195], v[34:37]
	v_mfma_f32_16x16x32_bf16 v[34:37], v[232:235], v[66:69], v[180:183]
	v_mfma_f32_16x16x32_bf16 v[78:81], v[236:239], v[192:195], v[34:37]
	v_mfma_f32_16x16x32_bf16 v[34:37], v[216:219], v[196:199], v[70:73]
	v_mfma_f32_16x16x32_bf16 v[66:69], v[228:231], v[202:205], v[34:37]
	v_mfma_f32_16x16x32_bf16 v[34:37], v[232:235], v[196:199], v[184:187]
	v_mfma_f32_16x16x32_bf16 v[70:73], v[236:239], v[202:205], v[34:37]
	s_setprio 0
	s_barrier
	ds_read_b128 v[154:157], v147 offset:49152
	ds_read_b128 v[174:177], v147 offset:50176
	ds_read_b128 v[178:181], v146 offset:49152
	ds_read_b128 v[146:149], v146 offset:50176
	ds_read_b128 v[182:185], v145 offset:49152
	ds_read_b128 v[192:195], v145 offset:50176
	ds_read_b128 v[196:199], v144 offset:49152
	ds_read_b128 v[202:205], v144 offset:50176
	s_barrier
	s_waitcnt lgkmcnt(0)
	s_setprio 1
	s_waitcnt lgkmcnt(0)
	v_mfma_f32_16x16x32_bf16 v[34:37], v[2:5], v[154:157], v[62:65]
	v_mfma_f32_16x16x32_bf16 v[58:61], v[10:13], v[174:177], v[34:37]
	v_mfma_f32_16x16x32_bf16 v[34:37], v[18:21], v[154:157], v[206:209]
	v_mfma_f32_16x16x32_bf16 v[62:65], v[26:29], v[174:177], v[34:37]
	v_mfma_f32_16x16x32_bf16 v[34:37], v[2:5], v[178:181], v[54:57]
	v_mfma_f32_16x16x32_bf16 v[50:53], v[10:13], v[146:149], v[34:37]
	v_mfma_f32_16x16x32_bf16 v[34:37], v[18:21], v[178:181], v[240:243]
	v_mfma_f32_16x16x32_bf16 v[54:57], v[26:29], v[146:149], v[34:37]
	v_mfma_f32_16x16x32_bf16 v[34:37], v[2:5], v[182:185], v[46:49]
	v_mfma_f32_16x16x32_bf16 v[42:45], v[10:13], v[192:195], v[34:37]
	v_mfma_f32_16x16x32_bf16 v[34:37], v[18:21], v[182:185], v[244:247]
	v_mfma_f32_16x16x32_bf16 v[2:5], v[2:5], v[196:199], v[38:41]
	v_mfma_f32_16x16x32_bf16 v[46:49], v[26:29], v[192:195], v[34:37]
	v_mfma_f32_16x16x32_bf16 v[34:37], v[10:13], v[202:205], v[2:5]
	v_mfma_f32_16x16x32_bf16 v[2:5], v[18:21], v[196:199], v[150:153]
	v_mfma_f32_16x16x32_bf16 v[38:41], v[26:29], v[202:205], v[2:5]
	s_setprio 0
	s_setprio 1
	v_mfma_f32_16x16x32_bf16 v[2:5], v[216:219], v[154:157], v[30:33]
	v_mfma_f32_16x16x32_bf16 v[26:29], v[228:231], v[174:177], v[2:5]
	v_mfma_f32_16x16x32_bf16 v[2:5], v[232:235], v[154:157], v[162:165]
	v_mfma_f32_16x16x32_bf16 v[30:33], v[236:239], v[174:177], v[2:5]
	v_mfma_f32_16x16x32_bf16 v[2:5], v[216:219], v[178:181], v[22:25]
	v_mfma_f32_16x16x32_bf16 v[18:21], v[228:231], v[146:149], v[2:5]
	v_mfma_f32_16x16x32_bf16 v[2:5], v[232:235], v[178:181], v[166:169]
	v_mfma_f32_16x16x32_bf16 v[22:25], v[236:239], v[146:149], v[2:5]
	v_mfma_f32_16x16x32_bf16 v[2:5], v[216:219], v[182:185], v[14:17]
	v_mfma_f32_16x16x32_bf16 v[10:13], v[228:231], v[192:195], v[2:5]
	v_mfma_f32_16x16x32_bf16 v[2:5], v[232:235], v[182:185], v[170:173]
	v_mfma_f32_16x16x32_bf16 v[14:17], v[236:239], v[192:195], v[2:5]
	v_mfma_f32_16x16x32_bf16 v[2:5], v[216:219], v[196:199], v[6:9]
	v_mfma_f32_16x16x32_bf16 v[6:9], v[232:235], v[196:199], v[188:191]
	v_mfma_f32_16x16x32_bf16 v[2:5], v[228:231], v[202:205], v[2:5]
	v_mfma_f32_16x16x32_bf16 v[6:9], v[236:239], v[202:205], v[6:9]
	s_setprio 0
	s_movk_i32 s0, 0x100
	v_cmp_gt_u32_e32 vcc, s0, v138
	s_barrier
	s_and_saveexec_b64 s[0:1], vcc
	s_cbranch_execz .LBB0_643
	s_barrier
